# flat->global everywhere; counted lgkmcnt in attention QK; pipelined EpiResid epilogues (6 groups in flight); Ph5 mla pre/post-step weight loads hoisted/prefetched; grid barrier leaders poll top genera
# speedup vs baseline: 1.0140x; 1.0082x over previous
; __device__ __forceinline__ unsigned xb_ld(unsigned* p)              { return __hip_atomic_load(p, __ATOMIC_RELAXED, __HIP_MEMORY_SCOPE_AGENT); }
; __device__ __forceinline__ unsigned xb_add(unsigned* p, unsigned v) { return __hip_atomic_fetch_add(p, v, __ATOMIC_RELAXED, __HIP_MEMORY_SCOPE_AGENT); }
; #define XB_SPIN(cond, bar) do { unsigned _sp = 0; while (cond) { __builtin_amdgcn_s_sleep(1); \
;     if ((++_sp & 255u) == 0u) { if (xb_ld(&(bar)[XB_TMO])) break; if (_sp > XB_SPIN_CAP) { atomicAdd(&(bar)[XB_TMO], 1u); break; } } } } while (0)
; __device__ __forceinline__ void xcd_barrier(const XcdBarrier& b, bool leader) {
;     ...
;     if (leader) {
;         unsigned* bar = b.bar;
;         __builtin_amdgcn_s_waitcnt(0);
;         unsigned nloc = b.st[0], nx = b.st[1];
;         if (nloc == 0u) { xcd_barrier_complete(bar, b.x, nloc, nx); b.st[0] = nloc; b.st[1] = nx; }
;         const unsigned old = xb_add(&bar[XB_XSUB(b.x)], 1u);
;         const unsigned gen = old / nloc;
;         if (old + 1u == (gen + 1u) * nloc) {
;             __builtin_amdgcn_fence(__ATOMIC_RELEASE, "agent");
;             asm volatile("s_waitcnt vmcnt(0)" ::: "memory");
;             const unsigned og = xb_add(&bar[XB_TOP], 1u);
;             const unsigned tg = og / nx;
;             if (og + 1u == (tg + 1u) * nx) xb_add(&bar[XB_TOPGEN], 1u);
;             else XB_SPIN(xb_ld(&bar[XB_TOPGEN]) == tg, bar);
;             __builtin_amdgcn_fence(__ATOMIC_ACQUIRE, "agent");
;             xb_add(&bar[XB_XGEN(b.x)], 1u);
;             asm volatile("s_waitcnt vmcnt(0)" ::: "memory");
;         } else {
;             XB_SPIN(xb_ld(&bar[XB_XGEN(b.x)]) == gen, bar);
;             __builtin_amdgcn_fence(__ATOMIC_ACQUIRE, "agent");
;             asm volatile("s_waitcnt vmcnt(0)" ::: "memory");
;         }
.LBB0_94:
	s_lshl_b32 s2, s36, 8
	s_add_u32 s2, s1, s2
	s_addc_u32 s3, s0, 0
	v_mov_b32_e32 v1, s2
	v_add_co_u32_e32 v4, vcc, 0x2000, v1
	v_mov_b32_e32 v1, s3
	s_nop 0
	v_addc_co_u32_e32 v5, vcc, 0, v1, vcc
	v_mov_b32_e32 v1, 1
	global_atomic_add v1, v[4:5], v1, off offset:1024 sc0
	v_cvt_f32_u32_e32 v3, v2
	v_sub_u32_e32 v4, 0, v2
	s_add_u32 s25, s2, 0x1000
	s_addc_u32 s24, s3, 0
	v_rcp_iflag_f32_e32 v3, v3
	s_nop 0
	v_mul_f32_e32 v3, 0x4f7ffffe, v3
	v_cvt_u32_f32_e32 v3, v3
	v_mul_lo_u32 v4, v4, v3
	v_mul_hi_u32 v4, v3, v4
	v_add_u32_e32 v3, v3, v4
	s_waitcnt vmcnt(0) lgkmcnt(0)
	v_mul_hi_u32 v3, v1, v3
	v_mul_lo_u32 v5, v3, v2
	v_add_u32_e32 v4, 1, v1
	v_sub_u32_e32 v1, v1, v5
	v_add_u32_e32 v6, 1, v3
	v_cmp_ge_u32_e32 vcc, v1, v2
	v_sub_u32_e32 v5, v1, v2
	s_nop 0
	v_cndmask_b32_e32 v3, v3, v6, vcc
	v_cndmask_b32_e32 v1, v1, v5, vcc
	v_add_u32_e32 v5, 1, v3
	v_cmp_ge_u32_e32 vcc, v1, v2
	s_nop 1
	v_cndmask_b32_e32 v1, v3, v5, vcc
	v_mad_u64_u32 v[2:3], s[2:3], v2, v1, v[2:3]
	v_cmp_ne_u32_e32 vcc, v4, v2
	s_and_saveexec_b64 s[2:3], vcc
	s_xor_b64 s[2:3], exec, s[2:3]
	s_cbranch_execz .LBB0_107
	v_mov_b32_e32 v0, s1
	v_add_co_u32_e32 v2, vcc, 0x4100, v0
	v_mov_b32_e32 v0, s0
	s_nop 0
	v_addc_co_u32_e32 v3, vcc, 0, v0, vcc
	global_load_dword v0, v[2:3], off offset:1024 sc1
	s_add_u32 s8, s1, 0x4500
	s_addc_u32 s9, s0, 0
	s_waitcnt vmcnt(0) lgkmcnt(0)
	v_cmp_eq_u32_e32 vcc, v0, v1
	s_and_saveexec_b64 s[4:5], vcc
	s_cbranch_execz .LBB0_106
	s_add_u32 s6, s1, 0x1200
	s_addc_u32 s7, s0, 0
	s_mov_b32 s26, 1
	s_mov_b64 s[10:11], 0
	s_branch .LBB0_98

; __device__ __forceinline__ float bflo(unsigned w) { return __uint_as_float(w << 16); }
; __device__ __forceinline__ float bfhi(unsigned w) { return __uint_as_float(w & 0xffff0000u); }
; __device__ __forceinline__ unsigned pk2(float lo, float hi) { const f32x2 v = {lo, hi}; return __builtin_bit_cast(unsigned, __builtin_convertvector(v, bf16x2_t)); }
; __device__ __forceinline__ float ex2f(float x) { return __builtin_amdgcn_exp2f(x); }
; template <int DQK, int DV, int MODE>
; __device__ __forceinline__ void flash_unit(LAS unsigned char* lds, const bf16* Qp, int qpitch, const bf16* K0, int kpitch, const bf16* K1, const bf16* VT, int vpitch,
;                                            bf16* Op, int opitch, int NT, int jbase, int qpos0) {
;     ...
;         const float pos = (float)(qpos0 + wid * 32 + r32);
;         const u32x4 xa = __builtin_bit_cast(u32x4, qf[ND0 - 2]), xb = __builtin_bit_cast(u32x4, qf[ND0 - 1]); u32x4 ra, rb;
; #pragma unroll
;         for (int e = 0; e < 4; ++e) { const float a0 = bflo(xa[e]), a1 = bfhi(xa[e]), b0 = bflo(xb[e]), b1 = bfhi(xb[e]);
;             float s0_, c0_, s1_, c1_; sincos_rev(pos * ex2f(-(float)(8 * hi + 2 * e) * (2.0f / 32.0f) * LG2_10000), s0_, c0_); sincos_rev(pos * ex2f(-(float)(8 * hi + 2 * e + 1) * (2.0f / 32.0f) * LG2_10000), s1_, c1_);
;             ra[e] = pk2(a0 * c0_ - b0 * s0_, a1 * c1_ - b1 * s1_); rb[e] = pk2(b0 * c0_ + a0 * s0_, b1 * c1_ + a1 * s1_); }
;         qf[ND0 - 2] = __builtin_bit_cast(bf16x8, ra); qf[ND0 - 1] = __builtin_bit_cast(bf16x8, rb);
.LBB0_540:
	s_or_b64 exec, exec, s[26:27]
	global_load_dwordx4 v[64:67], v[156:157], off offset:128
	v_or_b32_e32 v10, s8, v17
	v_add_u32_e32 v10, s66, v10
	v_cvt_f32_i32_e32 v20, v10
	v_cvt_f32_ubyte0_e32 v10, v154
	v_mul_f32_e32 v10, 0xbd800000, v10
	v_mul_f32_e32 v10, 0x41549a78, v10
	v_exp_f32_e32 v10, v10
	v_or_b32_e32 v11, 1, v154
	v_cvt_f32_ubyte0_e32 v11, v11
	v_mad_u32_u24 v0, v17, s51, v154
	v_mul_f32_e32 v11, 0xbd800000, v11
	v_lshl_add_u32 v169, v0, 1, 0
	v_mul_u32_u24_e32 v0, 0x88, v17
	v_mul_f32_e32 v11, 0x41549a78, v11
	v_add3_u32 v165, 0, v154, v0
	v_mul_f32_e32 v0, v10, v20
	v_exp_f32_e32 v11, v11
	v_mul_f32_e32 v10, 0.15915494, v0
	v_floor_f32_e32 v10, v10
	v_fma_f32 v0, v0, 0.15915494, -v10
	v_sin_f32_e32 v10, v0
	v_cos_f32_e32 v12, v0
	v_mul_f32_e32 v0, v11, v20
	v_mul_f32_e32 v11, 0.15915494, v0
	v_floor_f32_e32 v11, v11
	v_fma_f32 v0, v0, 0.15915494, -v11
	v_sin_f32_e32 v11, v0
	v_cos_f32_e32 v13, v0
	v_or_b32_e32 v0, 2, v154
	v_cvt_f32_ubyte0_e32 v0, v0
	v_mul_f32_e32 v0, 0xbd800000, v0
	v_mul_f32_e32 v0, 0x41549a78, v0
	v_lshlrev_b32_e32 v14, 16, v6
	v_and_b32_e32 v15, 0xffff0000, v6
	v_exp_f32_e32 v0, v0
	v_or_b32_e32 v6, 3, v154
	v_cvt_f32_ubyte0_e32 v6, v6
	v_mul_f32_e32 v6, 0xbd800000, v6
	v_mul_f32_e32 v6, 0x41549a78, v6
	v_mul_f32_e32 v0, v0, v20
	v_exp_f32_e32 v6, v6
	v_lshlrev_b32_e32 v16, 16, v2
	v_and_b32_e32 v17, 0xffff0000, v2
	v_mul_f32_e32 v2, 0.15915494, v0
	v_pk_mul_f32 v[18:19], v[10:11], v[16:17]
	v_pk_mul_f32 v[10:11], v[10:11], v[14:15]
	v_floor_f32_e32 v2, v2
	v_pk_fma_f32 v[10:11], v[12:13], v[16:17], v[10:11]
	v_fma_f32 v0, v0, 0.15915494, -v2
	v_pk_fma_f32 v[18:19], v[12:13], v[14:15], v[18:19] neg_lo:[0,0,1] neg_hi:[0,0,1]
	v_cvt_pk_bf16_f32 v124, v10, v11
	v_sin_f32_e32 v10, v0
	v_cos_f32_e32 v12, v0
	v_mul_f32_e32 v0, v6, v20
	v_mul_f32_e32 v2, 0.15915494, v0
	v_floor_f32_e32 v2, v2
	v_fma_f32 v0, v0, 0.15915494, -v2
	v_sin_f32_e32 v11, v0
	v_cos_f32_e32 v13, v0
	v_lshlrev_b32_e32 v2, 16, v3
	v_and_b32_e32 v3, 0xffff0000, v3
	v_or_b32_e32 v0, 4, v154
	v_lshlrev_b32_e32 v6, 16, v7
	v_and_b32_e32 v7, 0xffff0000, v7
	v_pk_mul_f32 v[14:15], v[10:11], v[2:3]
	v_cvt_f32_ubyte0_e32 v0, v0
	v_pk_fma_f32 v[14:15], v[12:13], v[6:7], v[14:15] neg_lo:[0,0,1] neg_hi:[0,0,1]
	v_mul_f32_e32 v0, 0xbd800000, v0
	v_pk_mul_f32 v[6:7], v[10:11], v[6:7]
	v_mul_f32_e32 v0, 0x41549a78, v0
	v_pk_fma_f32 v[2:3], v[12:13], v[2:3], v[6:7]
	v_exp_f32_e32 v0, v0
	v_cvt_pk_bf16_f32 v125, v2, v3
	v_or_b32_e32 v3, 5, v154
	v_cvt_f32_ubyte0_e32 v3, v3
	v_mul_f32_e32 v3, 0xbd800000, v3
	v_mul_f32_e32 v3, 0x41549a78, v3
	v_mul_f32_e32 v0, v0, v20
	v_exp_f32_e32 v3, v3
	v_mul_f32_e32 v2, 0.15915494, v0
	v_floor_f32_e32 v2, v2
	v_fma_f32 v0, v0, 0.15915494, -v2
	v_sin_f32_e32 v2, v0
	v_cos_f32_e32 v6, v0
	v_mul_f32_e32 v0, v3, v20
	v_mul_f32_e32 v3, 0.15915494, v0
	v_floor_f32_e32 v3, v3
	v_fma_f32 v0, v0, 0.15915494, -v3
	v_sin_f32_e32 v3, v0
	v_cos_f32_e32 v7, v0
	v_or_b32_e32 v0, 6, v154
	v_lshlrev_b32_e32 v10, 16, v8
	v_and_b32_e32 v11, 0xffff0000, v8
	v_lshlrev_b32_e32 v12, 16, v4
	v_and_b32_e32 v13, 0xffff0000, v4
	v_cvt_f32_ubyte0_e32 v0, v0
	v_cvt_pk_bf16_f32 v121, v14, v15
	v_pk_mul_f32 v[14:15], v[2:3], v[12:13]
	v_mul_f32_e32 v0, 0xbd800000, v0
	v_pk_mul_f32 v[2:3], v[2:3], v[10:11]
	v_mul_f32_e32 v0, 0x41549a78, v0
	v_pk_fma_f32 v[2:3], v[6:7], v[12:13], v[2:3]
	v_exp_f32_e32 v0, v0
	v_cvt_pk_bf16_f32 v126, v2, v3
	v_or_b32_e32 v3, 7, v154
	v_cvt_f32_ubyte0_e32 v3, v3
	v_mul_f32_e32 v3, 0xbd800000, v3
	v_mul_f32_e32 v3, 0x41549a78, v3
	v_mul_f32_e32 v0, v0, v20
	v_exp_f32_e32 v3, v3
	v_mul_f32_e32 v2, 0.15915494, v0
	v_floor_f32_e32 v2, v2
	v_fma_f32 v0, v0, 0.15915494, -v2
	v_pk_fma_f32 v[14:15], v[6:7], v[10:11], v[14:15] neg_lo:[0,0,1] neg_hi:[0,0,1]
	v_sin_f32_e32 v2, v0
	v_cos_f32_e32 v6, v0
	v_mul_f32_e32 v0, v3, v20
	v_mul_f32_e32 v3, 0.15915494, v0
	v_floor_f32_e32 v3, v3
	v_fma_f32 v0, v0, 0.15915494, -v3
	v_sin_f32_e32 v3, v0
	v_cos_f32_e32 v7, v0
	v_lshlrev_b32_e32 v8, 16, v9
	v_and_b32_e32 v9, 0xffff0000, v9
	v_lshlrev_b32_e32 v4, 16, v5
	v_and_b32_e32 v5, 0xffff0000, v5
	s_lshl_b32 s27, s64, 2
	s_ashr_i32 s26, s65, 7
	v_pk_mul_f32 v[10:11], v[2:3], v[4:5]
	v_pk_mul_f32 v[2:3], v[2:3], v[8:9]
	s_add_i32 s26, s26, s27
	v_pk_fma_f32 v[10:11], v[6:7], v[8:9], v[10:11] neg_lo:[0,0,1] neg_hi:[0,0,1]
	v_pk_fma_f32 v[2:3], v[6:7], v[4:5], v[2:3]
	v_cvt_pk_bf16_f32 v120, v18, v19
	v_cvt_pk_bf16_f32 v122, v14, v15
	v_cvt_pk_bf16_f32 v123, v10, v11
	s_cmp_lt_i32 s26, 0
	v_cvt_pk_bf16_f32 v127, v2, v3
	s_cbranch_scc1 .LBB0_542
	ds_read_b128 v[2:5], v169
	ds_read_b128 v[6:9], v169 offset:32
	ds_read_b128 v[10:13], v169 offset:6656
	ds_read_b128 v[48:51], v169 offset:6688
	ds_read_b128 v[52:55], v169 offset:64
	ds_read_b128 v[56:59], v169 offset:96
	ds_read_b128 v[60:63], v169 offset:6720
	ds_read_b128 v[68:71], v169 offset:6752
	ds_read_b128 v[72:75], v169 offset:128
	ds_read_b128 v[76:79], v169 offset:160
	ds_read_b128 v[80:83], v169 offset:6784
	ds_read_b128 v[128:131], v169 offset:6816
	s_waitcnt lgkmcnt(11)
	v_mfma_f32_32x32x16_bf16 v[32:47], v[2:5], v[116:119], 0
	s_waitcnt lgkmcnt(9)
	v_mfma_f32_32x32x16_bf16 v[16:31], v[10:13], v[116:119], 0
	v_mfma_f32_32x32x16_bf16 v[32:47], v[6:9], v[112:115], v[32:47]
	s_waitcnt lgkmcnt(8)
	v_mfma_f32_32x32x16_bf16 v[16:31], v[48:51], v[112:115], v[16:31]
	s_waitcnt lgkmcnt(7)
	v_mfma_f32_32x32x16_bf16 v[32:47], v[52:55], v[108:111], v[32:47]
	s_waitcnt lgkmcnt(5)
	v_mfma_f32_32x32x16_bf16 v[16:31], v[60:63], v[108:111], v[16:31]
	v_mfma_f32_32x32x16_bf16 v[32:47], v[56:59], v[104:107], v[32:47]
	s_waitcnt lgkmcnt(4)
	v_mfma_f32_32x32x16_bf16 v[16:31], v[68:71], v[104:107], v[16:31]
	s_waitcnt lgkmcnt(3)
	v_mfma_f32_32x32x16_bf16 v[32:47], v[72:75], v[120:123], v[32:47]
	s_waitcnt lgkmcnt(1)
	v_mfma_f32_32x32x16_bf16 v[16:31], v[80:83], v[120:123], v[16:31]
	v_mfma_f32_32x32x16_bf16 v[32:47], v[76:79], v[124:127], v[32:47]
	s_waitcnt lgkmcnt(0)
	v_mfma_f32_32x32x16_bf16 v[16:31], v[128:131], v[124:127], v[16:31]
	v_add_u32_e32 v0, 0x6800, v165
	ds_read2_b64 v[128:131], v0 offset1:2
	ds_read2_b64 v[80:83], v0 offset0:4 offset1:6
	ds_read2_b64 v[76:79], v0 offset0:8 offset1:10
	ds_read2_b64 v[72:75], v0 offset0:12 offset1:14
	v_add_u32_e32 v0, 0x7800, v165
	ds_read2_b64 v[60:63], v0 offset0:32 offset1:34
	ds_read2_b64 v[50:53], v0 offset0:36 offset1:38
	ds_read2_b64 v[56:59], v0 offset0:40 offset1:42
	ds_read2_b64 v[68:71], v0 offset0:44 offset1:46
	s_nop 1
	v_max_f32_e32 v2, v17, v17
	v_max_f32_e32 v3, v16, v16
	v_max_f32_e32 v2, v3, v2
	v_max3_f32 v0, v32, v33, v34
	v_max3_f32 v2, v2, v18, v19
	v_max3_f32 v0, v0, v35, v36
	v_max3_f32 v2, v2, v20, v21
	v_max3_f32 v0, v0, v37, v38
	v_max3_f32 v2, v2, v22, v23
	v_max3_f32 v0, v0, v39, v40
	v_max3_f32 v2, v2, v24, v25
	v_max3_f32 v0, v0, v41, v42
	v_max3_f32 v2, v2, v26, v27
	v_max3_f32 v0, v0, v43, v44
	v_max3_f32 v2, v2, v28, v29
	v_max3_f32 v0, v0, v45, v46
	v_max3_f32 v2, v2, v30, v31
	v_max3_f32 v0, v0, v47, v2
	v_mov_b32_e32 v2, v0
	s_nop 1
	v_permlane32_swap_b32_e32 v0, v2
	v_max_f32_e32 v2, v2, v2
	v_max_f32_e32 v0, v0, v0
	v_max_f32_e32 v48, v0, v2
	v_sub_f32_e32 v0, v32, v48
	v_sub_f32_e32 v16, v16, v48
	v_sub_f32_e32 v32, v33, v48
	v_sub_f32_e32 v17, v17, v48
	v_exp_f32_e32 v49, v0
	v_exp_f32_e32 v93, v16
	v_exp_f32_e32 v32, v32
	v_exp_f32_e32 v0, v17
	v_sub_f32_e32 v34, v34, v48
	v_add_f32_e32 v33, v49, v93
	v_sub_f32_e32 v54, v18, v48
	v_pk_add_f32 v[16:17], v[32:33], v[0:1]
	v_sub_f32_e32 v35, v35, v48
	v_sub_f32_e32 v55, v19, v48
	v_pk_add_f32 v[18:19], v[16:17], v[16:17] op_sel_hi:[0,1]
	v_exp_f32_e32 v33, v34
	v_exp_f32_e32 v94, v54
	v_exp_f32_e32 v34, v35
	v_exp_f32_e32 v18, v55
	v_sub_f32_e32 v36, v36, v48
	v_add_f32_e32 v35, v33, v94
	v_sub_f32_e32 v54, v20, v48
	v_pk_add_f32 v[16:17], v[34:35], v[18:19]
	v_sub_f32_e32 v37, v37, v48
	v_sub_f32_e32 v55, v21, v48
	v_pk_add_f32 v[20:21], v[16:17], v[16:17] op_sel_hi:[0,1]
	v_exp_f32_e32 v19, v36
	v_exp_f32_e32 v35, v54
	v_exp_f32_e32 v36, v37
	v_exp_f32_e32 v20, v55
	v_sub_f32_e32 v38, v38, v48
	v_add_f32_e32 v37, v19, v35
	v_sub_f32_e32 v54, v22, v48
	v_pk_add_f32 v[16:17], v[36:37], v[20:21]
	v_sub_f32_e32 v39, v39, v48
	v_sub_f32_e32 v55, v23, v48
	v_pk_add_f32 v[22:23], v[16:17], v[16:17] op_sel_hi:[0,1]
	v_exp_f32_e32 v21, v38
	v_exp_f32_e32 v37, v54
	v_exp_f32_e32 v38, v39
	v_exp_f32_e32 v22, v55
	v_sub_f32_e32 v40, v40, v48
	v_add_f32_e32 v39, v21, v37
	v_sub_f32_e32 v54, v24, v48
	v_pk_add_f32 v[16:17], v[38:39], v[22:23]
	v_sub_f32_e32 v41, v41, v48
	v_sub_f32_e32 v55, v25, v48
	v_pk_add_f32 v[24:25], v[16:17], v[16:17] op_sel_hi:[0,1]
	v_exp_f32_e32 v23, v40
	v_exp_f32_e32 v39, v54
	v_exp_f32_e32 v40, v41
	v_exp_f32_e32 v24, v55
	v_sub_f32_e32 v42, v42, v48
	v_add_f32_e32 v41, v23, v39
	v_sub_f32_e32 v54, v26, v48
	v_pk_add_f32 v[16:17], v[40:41], v[24:25]
	v_sub_f32_e32 v43, v43, v48
	v_sub_f32_e32 v55, v27, v48
	v_pk_add_f32 v[26:27], v[16:17], v[16:17] op_sel_hi:[0,1]
	v_exp_f32_e32 v25, v42
	v_exp_f32_e32 v41, v54
	v_exp_f32_e32 v42, v43
	v_exp_f32_e32 v26, v55
	v_sub_f32_e32 v44, v44, v48
	v_add_f32_e32 v43, v25, v41
	v_sub_f32_e32 v54, v28, v48
	v_pk_add_f32 v[16:17], v[42:43], v[26:27]
	v_sub_f32_e32 v45, v45, v48
	v_sub_f32_e32 v55, v29, v48
	v_pk_add_f32 v[28:29], v[16:17], v[16:17] op_sel_hi:[0,1]
	v_exp_f32_e32 v27, v44
	v_exp_f32_e32 v43, v54
	v_exp_f32_e32 v44, v45
	v_exp_f32_e32 v28, v55
	v_sub_f32_e32 v46, v46, v48
	v_add_f32_e32 v45, v27, v43
	v_sub_f32_e32 v54, v30, v48
	v_pk_add_f32 v[16:17], v[44:45], v[28:29]
	v_sub_f32_e32 v47, v47, v48
	v_sub_f32_e32 v55, v31, v48
	v_pk_add_f32 v[30:31], v[16:17], v[16:17] op_sel_hi:[0,1]
	v_exp_f32_e32 v29, v46
	v_exp_f32_e32 v45, v54
	v_exp_f32_e64 v2, -v48
	v_exp_f32_e32 v46, v47
	v_exp_f32_e32 v30, v55
	v_add_f32_e32 v47, v29, v45
	v_mul_f32_e32 v2, 0, v2
	v_mov_b32_e32 v16, v2
	v_pk_add_f32 v[54:55], v[46:47], v[30:31]
	v_mov_b32_e32 v17, v2
	v_pk_add_f32 v[54:55], v[54:55], v[54:55] op_sel_hi:[0,1]
	v_mov_b32_e32 v3, v2
	v_mov_b32_e32 v4, v2
	v_mov_b32_e32 v5, v2
	v_mov_b32_e32 v6, v2
	v_mov_b32_e32 v7, v2
	v_mov_b32_e32 v8, v2
	v_mov_b32_e32 v9, v2
	v_mov_b32_e32 v10, v2
	v_mov_b32_e32 v11, v2
	v_mov_b32_e32 v12, v2
	v_mov_b32_e32 v13, v2
	v_mov_b32_e32 v14, v2
	v_mov_b32_e32 v15, v2
	v_cvt_pk_bf16_f32 v132, v49, v32
	v_cvt_pk_bf16_f32 v133, v33, v34
	v_cvt_pk_bf16_f32 v134, v19, v36
	v_cvt_pk_bf16_f32 v135, v21, v38
	v_cvt_pk_bf16_f32 v136, v23, v40
	v_cvt_pk_bf16_f32 v137, v25, v42
	v_cvt_pk_bf16_f32 v138, v27, v44
	v_cvt_pk_bf16_f32 v139, v29, v46
	v_cvt_pk_bf16_f32 v140, v93, v0
	v_cvt_pk_bf16_f32 v141, v94, v18
	v_cvt_pk_bf16_f32 v142, v35, v20
	v_cvt_pk_bf16_f32 v143, v37, v22
	v_cvt_pk_bf16_f32 v144, v39, v24
	v_cvt_pk_bf16_f32 v145, v41, v26
	v_cvt_pk_bf16_f32 v146, v43, v28
	v_cvt_pk_bf16_f32 v147, v45, v30
	s_waitcnt lgkmcnt(0)
	v_mfma_f32_32x32x16_bf16 v[32:47], v[128:131], v[132:135], v[2:17]
	v_mov_b64_e32 v[30:31], v[16:17]
	v_mov_b64_e32 v[28:29], v[14:15]
	v_mov_b64_e32 v[26:27], v[12:13]
	v_mov_b64_e32 v[24:25], v[10:11]
	v_mov_b64_e32 v[22:23], v[8:9]
	v_mov_b64_e32 v[20:21], v[6:7]
	v_mov_b64_e32 v[18:19], v[4:5]
	v_mov_b64_e32 v[16:17], v[2:3]
	v_mfma_f32_32x32x16_bf16 v[32:47], v[80:83], v[136:139], v[32:47]
	v_mov_b32_e32 v49, v2
	v_mov_b32_e32 v54, v1
	v_add_f32_e64 v158, v48, v54
	v_add_f32_e64 v159, v49, v55
	v_xor_b32_e32 v48, 0x80000000, v158
	v_mov_b32_e32 v49, v48
	v_mov_b32_e32 v54, v48
	v_mfma_f32_32x32x16_bf16 v[16:31], v[60:63], v[132:135], v[16:31]
	v_mov_b32_e32 v55, v48
	v_mov_b32_e32 v60, v48
	v_mov_b32_e32 v61, v48
	v_mov_b32_e32 v62, v48
	v_mov_b32_e32 v63, v48
	v_mfma_f32_32x32x16_bf16 v[16:31], v[50:53], v[136:139], v[16:31]
	v_mov_b32_e32 v50, v48
	v_mov_b32_e32 v51, v48
	v_mov_b32_e32 v52, v48
	v_mov_b32_e32 v53, v48
	v_mfma_f32_32x32x16_bf16 v[32:47], v[76:79], v[140:143], v[32:47]
	v_mfma_f32_32x32x16_bf16 v[16:31], v[56:59], v[140:143], v[16:31]
	v_mov_b32_e32 v56, v48
	v_mov_b32_e32 v57, v48
	v_mov_b32_e32 v58, v48
	v_mov_b32_e32 v59, v48
	v_mfma_f32_32x32x16_bf16 v[32:47], v[72:75], v[144:147], v[32:47]
	v_mfma_f32_32x32x16_bf16 v[16:31], v[68:71], v[144:147], v[16:31]
	s_and_saveexec_b64 s[6:7], s[2:3]
	s_cbranch_execnz .LBB0_543
	s_branch .LBB0_544

.LBB0_554:
	s_or_b64 exec, exec, s[6:7]
	global_load_dwordx4 v[2:5], v[174:175], off
	s_add_i32 s7, s64, 3
	s_and_b32 s6, s7, 1
	s_cmp_gt_i32 s7, s26
	s_cbranch_scc1 .LBB0_558
	s_mul_i32 s7, s6, 0x3400
	v_add_u32_e32 v0, s7, v169
	ds_read_b128 v[6:9], v0
	ds_read_b128 v[10:13], v0 offset:32
	ds_read_b128 v[128:131], v0 offset:6656
	ds_read_b128 v[132:135], v0 offset:6688
	ds_read_b128 v[136:139], v0 offset:64
	ds_read_b128 v[140:143], v0 offset:96
	ds_read_b128 v[144:147], v0 offset:6720
	ds_read_b128 v[148:151], v0 offset:6752
	ds_read_b128 v[180:183], v0 offset:128
	ds_read_b128 v[184:187], v0 offset:160
	ds_read_b128 v[188:191], v0 offset:6784
	ds_read_b128 v[192:195], v0 offset:6816
	s_waitcnt lgkmcnt(11)
	v_mfma_f32_32x32x16_bf16 v[80:95], v[6:9], v[116:119], v[48:63]
	s_waitcnt lgkmcnt(9)
	v_mfma_f32_32x32x16_bf16 v[64:79], v[128:131], v[116:119], v[48:63]
	v_mfma_f32_32x32x16_bf16 v[80:95], v[10:13], v[112:115], v[80:95]
	s_waitcnt lgkmcnt(8)
	v_mfma_f32_32x32x16_bf16 v[64:79], v[132:135], v[112:115], v[64:79]
	s_waitcnt lgkmcnt(7)
	v_mfma_f32_32x32x16_bf16 v[80:95], v[136:139], v[108:111], v[80:95]
	s_waitcnt lgkmcnt(5)
	v_mfma_f32_32x32x16_bf16 v[64:79], v[144:147], v[108:111], v[64:79]
	v_mfma_f32_32x32x16_bf16 v[80:95], v[140:143], v[104:107], v[80:95]
	s_waitcnt lgkmcnt(4)
	v_mfma_f32_32x32x16_bf16 v[64:79], v[148:151], v[104:107], v[64:79]
	s_waitcnt lgkmcnt(3)
	v_mfma_f32_32x32x16_bf16 v[80:95], v[180:183], v[120:123], v[80:95]
	s_waitcnt lgkmcnt(1)
	v_mfma_f32_32x32x16_bf16 v[64:79], v[188:191], v[120:123], v[64:79]
	v_mfma_f32_32x32x16_bf16 v[80:95], v[184:187], v[124:127], v[80:95]
	s_waitcnt lgkmcnt(0)
	v_mfma_f32_32x32x16_bf16 v[64:79], v[192:195], v[124:127], v[64:79]
	s_mul_i32 s7, s6, 0x2200
	v_add_u32_e32 v0, s7, v165
	v_add_u32_e32 v6, 0x6800, v0
	v_add_u32_e32 v0, 0x7800, v0
	ds_read2_b64 v[148:151], v6 offset1:2
	ds_read2_b64 v[144:147], v6 offset0:4 offset1:6
	ds_read2_b64 v[140:143], v6 offset0:8 offset1:10
	ds_read2_b64 v[136:139], v6 offset0:12 offset1:14
	ds_read2_b64 v[132:135], v0 offset0:32 offset1:34
	ds_read2_b64 v[128:131], v0 offset0:36 offset1:38
	ds_read2_b64 v[10:13], v0 offset0:40 offset1:42
	ds_read2_b64 v[6:9], v0 offset0:44 offset1:46
	v_max_f32_e32 v15, v65, v65
	v_max_f32_e32 v161, v64, v64
	v_max_f32_e32 v15, v161, v15
	v_max3_f32 v0, v80, v81, v82
	v_max3_f32 v15, v15, v66, v67
	v_max3_f32 v0, v0, v83, v84
	v_max3_f32 v15, v15, v68, v69
	v_max3_f32 v0, v0, v85, v86
	v_max3_f32 v15, v15, v70, v71
	v_max3_f32 v0, v0, v87, v88
	v_max3_f32 v15, v15, v72, v73
	v_max3_f32 v0, v0, v89, v90
	v_max3_f32 v15, v15, v74, v75
	v_max3_f32 v0, v0, v91, v92
	v_max3_f32 v15, v15, v76, v77
	v_max3_f32 v0, v0, v93, v94
	v_max3_f32 v15, v15, v78, v79
	v_max3_f32 v0, v0, v95, v15
	v_mov_b32_e32 v15, v0
	s_nop 1
	v_permlane32_swap_b32_e32 v0, v15
	v_max_f32_e32 v15, v15, v15
	v_max_f32_e32 v0, v0, v0
	v_max_f32_e32 v0, v0, v15
	v_cmp_lt_f32_e32 vcc, s56, v0
	s_cbranch_vccz .LBB0_557
	s_nop 0
	v_cndmask_b32_e32 v0, 0, v0, vcc
	v_exp_f32_e64 v180, -v0
	v_add_f32_e32 v158, v158, v0
	v_xor_b32_e32 v48, 0x80000000, v158
	v_mov_b32_e32 v49, v48
	v_mov_b32_e32 v50, v48
	v_mov_b32_e32 v51, v48
	v_mov_b32_e32 v52, v48
	v_mov_b32_e32 v53, v48
	v_mov_b32_e32 v54, v48
	v_mov_b32_e32 v55, v48
	v_mov_b32_e32 v56, v48
	v_mov_b32_e32 v57, v48
	v_mov_b32_e32 v58, v48
	v_mov_b32_e32 v59, v48
	v_mov_b32_e32 v60, v48
	v_mov_b32_e32 v61, v48
	v_mov_b32_e32 v62, v48
	v_mov_b32_e32 v63, v48
	v_pk_add_f32 v[80:81], v[80:81], v[0:1] op_sel_hi:[1,0] neg_lo:[0,1] neg_hi:[0,1]
	v_pk_add_f32 v[64:65], v[64:65], v[0:1] op_sel_hi:[1,0] neg_lo:[0,1] neg_hi:[0,1]
	v_pk_add_f32 v[82:83], v[82:83], v[0:1] op_sel_hi:[1,0] neg_lo:[0,1] neg_hi:[0,1]
	v_pk_add_f32 v[66:67], v[66:67], v[0:1] op_sel_hi:[1,0] neg_lo:[0,1] neg_hi:[0,1]
	v_pk_add_f32 v[84:85], v[84:85], v[0:1] op_sel_hi:[1,0] neg_lo:[0,1] neg_hi:[0,1]
	v_pk_add_f32 v[68:69], v[68:69], v[0:1] op_sel_hi:[1,0] neg_lo:[0,1] neg_hi:[0,1]
	v_pk_add_f32 v[86:87], v[86:87], v[0:1] op_sel_hi:[1,0] neg_lo:[0,1] neg_hi:[0,1]
	v_pk_add_f32 v[70:71], v[70:71], v[0:1] op_sel_hi:[1,0] neg_lo:[0,1] neg_hi:[0,1]
	v_pk_add_f32 v[88:89], v[88:89], v[0:1] op_sel_hi:[1,0] neg_lo:[0,1] neg_hi:[0,1]
	v_pk_add_f32 v[72:73], v[72:73], v[0:1] op_sel_hi:[1,0] neg_lo:[0,1] neg_hi:[0,1]
	v_pk_add_f32 v[90:91], v[90:91], v[0:1] op_sel_hi:[1,0] neg_lo:[0,1] neg_hi:[0,1]
	v_pk_add_f32 v[74:75], v[74:75], v[0:1] op_sel_hi:[1,0] neg_lo:[0,1] neg_hi:[0,1]
	v_pk_add_f32 v[92:93], v[92:93], v[0:1] op_sel_hi:[1,0] neg_lo:[0,1] neg_hi:[0,1]
	v_pk_add_f32 v[76:77], v[76:77], v[0:1] op_sel_hi:[1,0] neg_lo:[0,1] neg_hi:[0,1]
	v_pk_add_f32 v[94:95], v[94:95], v[0:1] op_sel_hi:[1,0] neg_lo:[0,1] neg_hi:[0,1]
	v_pk_add_f32 v[78:79], v[78:79], v[0:1] op_sel_hi:[1,0] neg_lo:[0,1] neg_hi:[0,1]
	v_pk_mul_f32 v[46:47], v[46:47], v[180:181] op_sel_hi:[1,0]
	v_pk_mul_f32 v[44:45], v[44:45], v[180:181] op_sel_hi:[1,0]
	v_pk_mul_f32 v[42:43], v[42:43], v[180:181] op_sel_hi:[1,0]
	v_pk_mul_f32 v[40:41], v[40:41], v[180:181] op_sel_hi:[1,0]
	v_pk_mul_f32 v[38:39], v[38:39], v[180:181] op_sel_hi:[1,0]
	v_pk_mul_f32 v[36:37], v[36:37], v[180:181] op_sel_hi:[1,0]
	v_pk_mul_f32 v[34:35], v[34:35], v[180:181] op_sel_hi:[1,0]
	v_pk_mul_f32 v[32:33], v[32:33], v[180:181] op_sel_hi:[1,0]
	v_pk_mul_f32 v[30:31], v[30:31], v[180:181] op_sel_hi:[1,0]
	v_pk_mul_f32 v[28:29], v[28:29], v[180:181] op_sel_hi:[1,0]
	v_pk_mul_f32 v[26:27], v[26:27], v[180:181] op_sel_hi:[1,0]
	v_pk_mul_f32 v[24:25], v[24:25], v[180:181] op_sel_hi:[1,0]
	v_pk_mul_f32 v[22:23], v[22:23], v[180:181] op_sel_hi:[1,0]
	v_pk_mul_f32 v[20:21], v[20:21], v[180:181] op_sel_hi:[1,0]
	v_pk_mul_f32 v[18:19], v[18:19], v[180:181] op_sel_hi:[1,0]
	v_pk_mul_f32 v[16:17], v[16:17], v[180:181] op_sel_hi:[1,0]
	v_mul_f32_e32 v159, v159, v180

.LBB0_568:
	s_add_i32 s6, s64, -1
	s_or_b32 s7, s27, 2
	s_and_b32 s6, s6, 1
	s_cmp_ge_i32 s7, s26
	s_cbranch_scc1 .LBB0_572
	s_mul_i32 s7, s6, 0x3400
	v_add_u32_e32 v0, s7, v169
	ds_read_b128 v[6:9], v0
	ds_read_b128 v[10:13], v0 offset:32
	ds_read_b128 v[80:83], v0 offset:6656
	ds_read_b128 v[84:87], v0 offset:6688
	ds_read_b128 v[88:91], v0 offset:64
	ds_read_b128 v[92:95], v0 offset:96
	ds_read_b128 v[128:131], v0 offset:6720
	ds_read_b128 v[132:135], v0 offset:6752
	ds_read_b128 v[136:139], v0 offset:128
	ds_read_b128 v[140:143], v0 offset:160
	ds_read_b128 v[144:147], v0 offset:6784
	ds_read_b128 v[148:151], v0 offset:6816
	s_waitcnt lgkmcnt(11)
	v_mfma_f32_32x32x16_bf16 v[64:79], v[6:9], v[116:119], v[48:63]
	s_waitcnt lgkmcnt(9)
	v_mfma_f32_32x32x16_bf16 v[48:63], v[80:83], v[116:119], v[48:63]
	v_mfma_f32_32x32x16_bf16 v[64:79], v[10:13], v[112:115], v[64:79]
	s_waitcnt lgkmcnt(8)
	v_mfma_f32_32x32x16_bf16 v[48:63], v[84:87], v[112:115], v[48:63]
	s_waitcnt lgkmcnt(7)
	v_mfma_f32_32x32x16_bf16 v[64:79], v[88:91], v[108:111], v[64:79]
	s_waitcnt lgkmcnt(5)
	v_mfma_f32_32x32x16_bf16 v[48:63], v[128:131], v[108:111], v[48:63]
	v_mfma_f32_32x32x16_bf16 v[64:79], v[92:95], v[104:107], v[64:79]
	s_waitcnt lgkmcnt(4)
	v_mfma_f32_32x32x16_bf16 v[48:63], v[132:135], v[104:107], v[48:63]
	s_waitcnt lgkmcnt(3)
	v_mfma_f32_32x32x16_bf16 v[64:79], v[136:139], v[120:123], v[64:79]
	s_waitcnt lgkmcnt(1)
	v_mfma_f32_32x32x16_bf16 v[48:63], v[144:147], v[120:123], v[48:63]
	v_mfma_f32_32x32x16_bf16 v[64:79], v[140:143], v[124:127], v[64:79]
	s_waitcnt lgkmcnt(0)
	v_mfma_f32_32x32x16_bf16 v[48:63], v[148:151], v[124:127], v[48:63]
	s_mul_i32 s7, s6, 0x2200
	v_add_u32_e32 v0, s7, v165
	v_add_u32_e32 v6, 0x6800, v0
	v_add_u32_e32 v0, 0x7800, v0
	ds_read2_b64 v[108:111], v6 offset1:2
	ds_read2_b64 v[104:107], v6 offset0:4 offset1:6
	ds_read2_b64 v[92:95], v6 offset0:8 offset1:10
	ds_read2_b64 v[88:91], v6 offset0:12 offset1:14
	ds_read2_b64 v[84:87], v0 offset0:32 offset1:34
	ds_read2_b64 v[80:83], v0 offset0:36 offset1:38
	ds_read2_b64 v[10:13], v0 offset0:40 offset1:42
	ds_read2_b64 v[6:9], v0 offset0:44 offset1:46
	v_max_f32_e32 v14, v49, v49
	v_max_f32_e32 v15, v48, v48
	v_max_f32_e32 v14, v15, v14
	v_max3_f32 v0, v64, v65, v66
	v_max3_f32 v14, v14, v50, v51
	v_max3_f32 v0, v0, v67, v68
	v_max3_f32 v14, v14, v52, v53
	v_max3_f32 v0, v0, v69, v70
	v_max3_f32 v14, v14, v54, v55
	v_max3_f32 v0, v0, v71, v72
	v_max3_f32 v14, v14, v56, v57
	v_max3_f32 v0, v0, v73, v74
	v_max3_f32 v14, v14, v58, v59
	v_max3_f32 v0, v0, v75, v76
	v_max3_f32 v14, v14, v60, v61
	v_max3_f32 v0, v0, v77, v78
	v_max3_f32 v14, v14, v62, v63
	v_max3_f32 v0, v0, v79, v14
	v_mov_b32_e32 v14, v0
	s_nop 1
	v_permlane32_swap_b32_e32 v0, v14
	v_max_f32_e32 v14, v14, v14
	v_max_f32_e32 v0, v0, v0
	v_max_f32_e32 v0, v0, v14
	v_cmp_lt_f32_e32 vcc, s56, v0
	s_cbranch_vccz .LBB0_571
	s_nop 0
	v_cndmask_b32_e32 v0, 0, v0, vcc
	v_exp_f32_e64 v14, -v0
	v_pk_add_f32 v[64:65], v[64:65], v[0:1] op_sel_hi:[1,0] neg_lo:[0,1] neg_hi:[0,1]
	v_pk_add_f32 v[48:49], v[48:49], v[0:1] op_sel_hi:[1,0] neg_lo:[0,1] neg_hi:[0,1]
	v_pk_add_f32 v[66:67], v[66:67], v[0:1] op_sel_hi:[1,0] neg_lo:[0,1] neg_hi:[0,1]
	v_pk_add_f32 v[50:51], v[50:51], v[0:1] op_sel_hi:[1,0] neg_lo:[0,1] neg_hi:[0,1]
	v_pk_add_f32 v[68:69], v[68:69], v[0:1] op_sel_hi:[1,0] neg_lo:[0,1] neg_hi:[0,1]
	v_pk_add_f32 v[52:53], v[52:53], v[0:1] op_sel_hi:[1,0] neg_lo:[0,1] neg_hi:[0,1]
	v_pk_add_f32 v[70:71], v[70:71], v[0:1] op_sel_hi:[1,0] neg_lo:[0,1] neg_hi:[0,1]
	v_pk_add_f32 v[54:55], v[54:55], v[0:1] op_sel_hi:[1,0] neg_lo:[0,1] neg_hi:[0,1]
	v_pk_add_f32 v[72:73], v[72:73], v[0:1] op_sel_hi:[1,0] neg_lo:[0,1] neg_hi:[0,1]
	v_pk_add_f32 v[56:57], v[56:57], v[0:1] op_sel_hi:[1,0] neg_lo:[0,1] neg_hi:[0,1]
	v_pk_add_f32 v[74:75], v[74:75], v[0:1] op_sel_hi:[1,0] neg_lo:[0,1] neg_hi:[0,1]
	v_pk_add_f32 v[58:59], v[58:59], v[0:1] op_sel_hi:[1,0] neg_lo:[0,1] neg_hi:[0,1]
	v_pk_add_f32 v[76:77], v[76:77], v[0:1] op_sel_hi:[1,0] neg_lo:[0,1] neg_hi:[0,1]
	v_pk_add_f32 v[60:61], v[60:61], v[0:1] op_sel_hi:[1,0] neg_lo:[0,1] neg_hi:[0,1]
	v_pk_add_f32 v[78:79], v[78:79], v[0:1] op_sel_hi:[1,0] neg_lo:[0,1] neg_hi:[0,1]
	v_pk_add_f32 v[62:63], v[62:63], v[0:1] op_sel_hi:[1,0] neg_lo:[0,1] neg_hi:[0,1]
	v_pk_mul_f32 v[46:47], v[46:47], v[14:15] op_sel_hi:[1,0]
	v_pk_mul_f32 v[44:45], v[44:45], v[14:15] op_sel_hi:[1,0]
	v_pk_mul_f32 v[42:43], v[42:43], v[14:15] op_sel_hi:[1,0]
	v_pk_mul_f32 v[40:41], v[40:41], v[14:15] op_sel_hi:[1,0]
	v_pk_mul_f32 v[38:39], v[38:39], v[14:15] op_sel_hi:[1,0]
	v_pk_mul_f32 v[36:37], v[36:37], v[14:15] op_sel_hi:[1,0]
	v_pk_mul_f32 v[34:35], v[34:35], v[14:15] op_sel_hi:[1,0]
	v_pk_mul_f32 v[32:33], v[32:33], v[14:15] op_sel_hi:[1,0]
	v_pk_mul_f32 v[30:31], v[30:31], v[14:15] op_sel_hi:[1,0]
	v_pk_mul_f32 v[28:29], v[28:29], v[14:15] op_sel_hi:[1,0]
	v_pk_mul_f32 v[26:27], v[26:27], v[14:15] op_sel_hi:[1,0]
	v_pk_mul_f32 v[24:25], v[24:25], v[14:15] op_sel_hi:[1,0]
	v_pk_mul_f32 v[22:23], v[22:23], v[14:15] op_sel_hi:[1,0]
	v_pk_mul_f32 v[20:21], v[20:21], v[14:15] op_sel_hi:[1,0]
	v_pk_mul_f32 v[18:19], v[18:19], v[14:15] op_sel_hi:[1,0]
	v_pk_mul_f32 v[16:17], v[16:17], v[14:15] op_sel_hi:[1,0]
	v_mul_f32_e32 v159, v159, v14

; #define LAS __attribute__((address_space(3)))
; __device__ __forceinline__ bf16 f2bf(float f) { return (bf16)(pk2(f, 0.f) & 0xffffu); }
; __device__ __forceinline__ void mla_sample_unit(LAS unsigned char* lds, size_t ws_q, size_t ws_olat, size_t ws_mixed, int b) {
;     ...
;       for (int h2 = 0; h2 < 2; ++h2) { const int h = 2 * hg + h2; const float* wr = w_uk + (size_t)(r * 8 + h) * 64; float a[16];
; #pragma unroll
;           for (int t = 0; t < 16; ++t) a[t] = 0.f;
; #pragma unroll 4
;           for (int d4 = 0; d4 < 16; ++d4) { const f32x4 w = *(const f32x4*)(wr + 4 * d4);
; #pragma unroll
;               for (int t = 0; t < 16; ++t) { const f32x4 q = *(const LAS f32x4*)(QS + t * 768 + h * 96 + 4 * d4); a[t] += (w.x * q.x + w.y * q.y) + (w.z * q.z + w.w * q.w); } }
; #pragma unroll
;           for (int t = 0; t < 16; ++t) QA[(h * 16 + t) * KP + r] = f2bf(a[t]); }
.LBB0_686:
	global_load_dwordx4 v[60:63], v[20:21], off
	global_load_dwordx4 v[64:67], v[20:21], off offset:16
	global_load_dwordx4 v[68:71], v[20:21], off offset:32
	global_load_dwordx4 v[72:75], v[20:21], off offset:48
	v_add_u32_e32 v54, s6, v53
	ds_read_b128 v[38:41], v54 offset:43008
	ds_read_b128 v[10:13], v54 offset:43024
	ds_read_b128 v[6:9], v54 offset:43040
	ds_read_b128 v[2:5], v54 offset:43056
	ds_read_b128 v[42:45], v54 offset:46080
	s_waitcnt lgkmcnt(0)
	v_mov_b32_e32 v47, v39
	s_add_i32 s6, s6, 64
	s_cmpk_eq_i32 s6, 0x100
	v_mov_b32_e32 v46, v42
	v_pk_mov_b32 v[38:39], v[42:43], v[38:39] op_sel:[1,0]
	v_mov_b32_e32 v42, v44
	v_mov_b32_e32 v43, v41
	v_pk_mov_b32 v[40:41], v[44:45], v[40:41] op_sel:[1,0]
	s_waitcnt vmcnt(3)
	v_mov_b64_e32 v[14:15], v[60:61]
	v_mov_b64_e32 v[16:17], v[62:63]
	v_pk_mul_f32 v[42:43], v[16:17], v[42:43]
	s_nop 0
	v_pk_fma_f32 v[40:41], v[16:17], v[40:41], v[42:43] op_sel:[1,0,0] op_sel_hi:[0,1,1]
	ds_read_b128 v[42:45], v54 offset:49152
	ds_read_b128 v[56:59], v54 offset:52224
	v_pk_mul_f32 v[46:47], v[14:15], v[46:47]
	s_nop 0
	v_pk_fma_f32 v[38:39], v[14:15], v[38:39], v[46:47] op_sel:[1,0,0] op_sel_hi:[0,1,1]
	v_pk_add_f32 v[38:39], v[38:39], v[40:41]
	s_nop 0
	v_pk_add_f32 v[40:41], v[22:23], v[38:39]
	s_waitcnt lgkmcnt(0)
	v_mov_b32_e32 v22, v56
	v_mov_b32_e32 v23, v43
	v_pk_mul_f32 v[22:23], v[14:15], v[22:23]
	v_pk_mov_b32 v[38:39], v[56:57], v[42:43] op_sel:[1,0]
	v_pk_mov_b32 v[42:43], v[58:59], v[44:45] op_sel:[1,0]
	v_pk_fma_f32 v[22:23], v[14:15], v[38:39], v[22:23] op_sel:[1,0,0] op_sel_hi:[0,1,1]
	v_mov_b32_e32 v38, v58
	v_mov_b32_e32 v39, v45
	v_pk_mul_f32 v[38:39], v[16:17], v[38:39]
	s_nop 0
	v_pk_fma_f32 v[38:39], v[16:17], v[42:43], v[38:39] op_sel:[1,0,0] op_sel_hi:[0,1,1]
	v_pk_add_f32 v[22:23], v[22:23], v[38:39]
	s_nop 0
	v_pk_add_f32 v[38:39], v[24:25], v[22:23]
	ds_read_b128 v[22:25], v54 offset:55296
	ds_read_b128 v[42:45], v54 offset:58368
	s_waitcnt lgkmcnt(1)
	v_mov_b32_e32 v47, v23
	s_waitcnt lgkmcnt(0)
	v_mov_b32_e32 v46, v42
	v_pk_mov_b32 v[22:23], v[42:43], v[22:23] op_sel:[1,0]
	v_mov_b32_e32 v42, v44
	v_mov_b32_e32 v43, v25
	v_pk_mul_f32 v[42:43], v[16:17], v[42:43]
	v_pk_mov_b32 v[24:25], v[44:45], v[24:25] op_sel:[1,0]
	v_pk_mul_f32 v[46:47], v[14:15], v[46:47]
	v_pk_fma_f32 v[24:25], v[16:17], v[24:25], v[42:43] op_sel:[1,0,0] op_sel_hi:[0,1,1]
	ds_read_b128 v[42:45], v54 offset:61440
	ds_read_b128 v[56:59], v54 offset:64512
	v_pk_fma_f32 v[22:23], v[14:15], v[22:23], v[46:47] op_sel:[1,0,0] op_sel_hi:[0,1,1]
	v_pk_add_f32 v[22:23], v[22:23], v[24:25]
	s_nop 0
	v_pk_add_f32 v[24:25], v[26:27], v[22:23]
	s_waitcnt lgkmcnt(0)
	v_mov_b32_e32 v22, v56
	v_mov_b32_e32 v23, v43
	v_pk_mul_f32 v[22:23], v[14:15], v[22:23]
	v_pk_mov_b32 v[26:27], v[56:57], v[42:43] op_sel:[1,0]
	v_pk_mov_b32 v[42:43], v[58:59], v[44:45] op_sel:[1,0]
	v_pk_fma_f32 v[22:23], v[14:15], v[26:27], v[22:23] op_sel:[1,0,0] op_sel_hi:[0,1,1]
	v_mov_b32_e32 v26, v58
	v_mov_b32_e32 v27, v45
	v_pk_mul_f32 v[26:27], v[16:17], v[26:27]
	s_nop 0
	v_pk_fma_f32 v[26:27], v[16:17], v[42:43], v[26:27] op_sel:[1,0,0] op_sel_hi:[0,1,1]
	v_pk_add_f32 v[22:23], v[22:23], v[26:27]
	v_add_u32_e32 v26, 0x10800, v54
	v_add_u32_e32 v42, 0x11400, v54
	v_pk_add_f32 v[22:23], v[28:29], v[22:23]
	ds_read_b128 v[26:29], v26
	ds_read_b128 v[42:45], v42
	s_waitcnt lgkmcnt(1)
	v_mov_b32_e32 v47, v27
	s_waitcnt lgkmcnt(0)
	v_mov_b32_e32 v46, v42
	v_pk_mov_b32 v[26:27], v[42:43], v[26:27] op_sel:[1,0]
	v_mov_b32_e32 v42, v44
	v_mov_b32_e32 v43, v29
	v_pk_mul_f32 v[46:47], v[14:15], v[46:47]
	v_pk_mul_f32 v[42:43], v[16:17], v[42:43]
	v_pk_mov_b32 v[28:29], v[44:45], v[28:29] op_sel:[1,0]
	v_pk_fma_f32 v[26:27], v[14:15], v[26:27], v[46:47] op_sel:[1,0,0] op_sel_hi:[0,1,1]
	v_pk_fma_f32 v[28:29], v[16:17], v[28:29], v[42:43] op_sel:[1,0,0] op_sel_hi:[0,1,1]
	v_pk_add_f32 v[26:27], v[26:27], v[28:29]
	v_add_u32_e32 v28, 0x12000, v54
	v_add_u32_e32 v42, 0x12c00, v54
	v_pk_add_f32 v[26:27], v[30:31], v[26:27]
	ds_read_b128 v[28:31], v28
	ds_read_b128 v[42:45], v42
	s_waitcnt lgkmcnt(1)
	v_mov_b32_e32 v47, v29
	s_waitcnt lgkmcnt(0)
	v_mov_b32_e32 v46, v42
	v_pk_mov_b32 v[28:29], v[42:43], v[28:29] op_sel:[1,0]
	v_mov_b32_e32 v42, v44
	v_mov_b32_e32 v43, v31
	v_pk_mul_f32 v[46:47], v[14:15], v[46:47]
	v_pk_mul_f32 v[42:43], v[16:17], v[42:43]
	v_pk_mov_b32 v[30:31], v[44:45], v[30:31] op_sel:[1,0]
	v_pk_fma_f32 v[28:29], v[14:15], v[28:29], v[46:47] op_sel:[1,0,0] op_sel_hi:[0,1,1]
	v_pk_fma_f32 v[30:31], v[16:17], v[30:31], v[42:43] op_sel:[1,0,0] op_sel_hi:[0,1,1]
	v_pk_add_f32 v[28:29], v[28:29], v[30:31]
	v_add_u32_e32 v30, 0x13800, v54
	v_add_u32_e32 v42, 0x14400, v54
	v_pk_add_f32 v[28:29], v[32:33], v[28:29]
	ds_read_b128 v[30:33], v30
	ds_read_b128 v[42:45], v42
	s_waitcnt lgkmcnt(0)
	v_pk_mov_b32 v[46:47], v[30:31], v[42:43] op_sel:[1,0]
	v_mov_b32_e32 v31, v43
	v_pk_mov_b32 v[42:43], v[32:33], v[44:45] op_sel:[1,0]
	v_mov_b32_e32 v33, v45
	v_pk_mul_f32 v[30:31], v[14:15], v[30:31]
	v_pk_mul_f32 v[32:33], v[16:17], v[32:33]
	v_pk_fma_f32 v[30:31], v[14:15], v[46:47], v[30:31] op_sel:[1,0,0] op_sel_hi:[0,1,1]
	v_pk_fma_f32 v[32:33], v[16:17], v[42:43], v[32:33] op_sel:[1,0,0] op_sel_hi:[0,1,1]
	v_pk_add_f32 v[30:31], v[30:31], v[32:33]
	v_add_u32_e32 v32, 0x15000, v54
	v_add_u32_e32 v42, 0x15c00, v54
	v_pk_add_f32 v[30:31], v[34:35], v[30:31]
	ds_read_b128 v[32:35], v32
	ds_read_b128 v[42:45], v42
	s_waitcnt lgkmcnt(0)
; #define LAS __attribute__((address_space(3)))
; __device__ __forceinline__ bf16 f2bf(float f) { return (bf16)(pk2(f, 0.f) & 0xffffu); }
; __device__ __forceinline__ void mla_sample_unit(LAS unsigned char* lds, size_t ws_q, size_t ws_olat, size_t ws_mixed, int b) {
;     ...
;       for (int h2 = 0; h2 < 2; ++h2) { const int h = 2 * hg + h2; const float* wr = w_uk + (size_t)(r * 8 + h) * 64; float a[16];
; #pragma unroll
;           for (int t = 0; t < 16; ++t) a[t] = 0.f;
; #pragma unroll 4
;           for (int d4 = 0; d4 < 16; ++d4) { const f32x4 w = *(const f32x4*)(wr + 4 * d4);
; #pragma unroll
;               for (int t = 0; t < 16; ++t) { const f32x4 q = *(const LAS f32x4*)(QS + t * 768 + h * 96 + 4 * d4); a[t] += (w.x * q.x + w.y * q.y) + (w.z * q.z + w.w * q.w); } }
; #pragma unroll
;           for (int t = 0; t < 16; ++t) QA[(h * 16 + t) * KP + r] = f2bf(a[t]); }
	v_pk_mov_b32 v[46:47], v[32:33], v[42:43] op_sel:[1,0]
	v_mov_b32_e32 v33, v43
	v_pk_mul_f32 v[32:33], v[14:15], v[32:33]
	v_mov_b32_e32 v43, v11
	v_pk_fma_f32 v[14:15], v[14:15], v[46:47], v[32:33] op_sel:[1,0,0] op_sel_hi:[0,1,1]
	v_pk_mov_b32 v[32:33], v[34:35], v[44:45] op_sel:[1,0]
	v_mov_b32_e32 v35, v45
	v_pk_mul_f32 v[34:35], v[16:17], v[34:35]
	s_nop 0
	v_pk_fma_f32 v[16:17], v[16:17], v[32:33], v[34:35] op_sel:[1,0,0] op_sel_hi:[0,1,1]
	v_pk_add_f32 v[14:15], v[14:15], v[16:17]
	s_nop 0
	v_pk_add_f32 v[32:33], v[36:37], v[14:15]
	ds_read_b128 v[34:37], v54 offset:46096
	s_waitcnt lgkmcnt(0)
	v_mov_b32_e32 v42, v34
	v_pk_mov_b32 v[10:11], v[34:35], v[10:11] op_sel:[1,0]
	v_mov_b32_e32 v34, v36
	v_mov_b32_e32 v35, v13
	v_pk_mov_b32 v[12:13], v[36:37], v[12:13] op_sel:[1,0]
	s_waitcnt vmcnt(2)
	v_mov_b64_e32 v[14:15], v[64:65]
	v_mov_b64_e32 v[16:17], v[66:67]
	v_pk_mul_f32 v[42:43], v[14:15], v[42:43]
	v_pk_mul_f32 v[34:35], v[16:17], v[34:35]
	v_pk_fma_f32 v[10:11], v[14:15], v[10:11], v[42:43] op_sel:[1,0,0] op_sel_hi:[0,1,1]
	v_pk_fma_f32 v[12:13], v[16:17], v[12:13], v[34:35] op_sel:[1,0,0] op_sel_hi:[0,1,1]
	v_pk_add_f32 v[10:11], v[10:11], v[12:13]
	s_nop 0
	v_pk_add_f32 v[40:41], v[40:41], v[10:11]
	ds_read_b128 v[10:13], v54 offset:49168
	ds_read_b128 v[34:37], v54 offset:52240
	s_waitcnt lgkmcnt(1)
	v_mov_b32_e32 v43, v11
	s_waitcnt lgkmcnt(0)
	v_mov_b32_e32 v42, v34
	v_pk_mov_b32 v[10:11], v[34:35], v[10:11] op_sel:[1,0]
	v_mov_b32_e32 v34, v36
	v_mov_b32_e32 v35, v13
	v_pk_mul_f32 v[42:43], v[14:15], v[42:43]
	v_pk_mul_f32 v[34:35], v[16:17], v[34:35]
	v_pk_mov_b32 v[12:13], v[36:37], v[12:13] op_sel:[1,0]
	v_pk_fma_f32 v[10:11], v[14:15], v[10:11], v[42:43] op_sel:[1,0,0] op_sel_hi:[0,1,1]
	v_pk_fma_f32 v[12:13], v[16:17], v[12:13], v[34:35] op_sel:[1,0,0] op_sel_hi:[0,1,1]
	v_pk_add_f32 v[10:11], v[10:11], v[12:13]
	s_nop 0
	v_pk_add_f32 v[42:43], v[38:39], v[10:11]
	ds_read_b128 v[10:13], v54 offset:55312
	ds_read_b128 v[34:37], v54 offset:58384
	s_waitcnt lgkmcnt(1)
	v_mov_b32_e32 v39, v11
	s_waitcnt lgkmcnt(0)
	v_mov_b32_e32 v38, v34
	v_pk_mov_b32 v[10:11], v[34:35], v[10:11] op_sel:[1,0]
	v_mov_b32_e32 v34, v36
	v_mov_b32_e32 v35, v13
	v_pk_mul_f32 v[38:39], v[14:15], v[38:39]
	v_pk_mul_f32 v[34:35], v[16:17], v[34:35]
	v_pk_mov_b32 v[12:13], v[36:37], v[12:13] op_sel:[1,0]
	v_pk_fma_f32 v[10:11], v[14:15], v[10:11], v[38:39] op_sel:[1,0,0] op_sel_hi:[0,1,1]
	v_pk_fma_f32 v[12:13], v[16:17], v[12:13], v[34:35] op_sel:[1,0,0] op_sel_hi:[0,1,1]
	v_pk_add_f32 v[10:11], v[10:11], v[12:13]
	s_nop 0
	v_pk_add_f32 v[44:45], v[24:25], v[10:11]
	ds_read_b128 v[10:13], v54 offset:61456
	ds_read_b128 v[34:37], v54 offset:64528
	s_waitcnt lgkmcnt(1)
	v_mov_b32_e32 v25, v11
	s_waitcnt lgkmcnt(0)
	v_mov_b32_e32 v24, v34
	v_pk_mul_f32 v[24:25], v[14:15], v[24:25]
	v_pk_mov_b32 v[10:11], v[34:35], v[10:11] op_sel:[1,0]
	s_nop 0
	v_pk_fma_f32 v[10:11], v[14:15], v[10:11], v[24:25] op_sel:[1,0,0] op_sel_hi:[0,1,1]
	v_mov_b32_e32 v24, v36
	v_mov_b32_e32 v25, v13
	v_pk_mul_f32 v[24:25], v[16:17], v[24:25]
	v_pk_mov_b32 v[12:13], v[36:37], v[12:13] op_sel:[1,0]
	s_nop 0
	v_pk_fma_f32 v[12:13], v[16:17], v[12:13], v[24:25] op_sel:[1,0,0] op_sel_hi:[0,1,1]
	v_pk_add_f32 v[10:11], v[10:11], v[12:13]
	s_nop 0
	v_pk_add_f32 v[46:47], v[22:23], v[10:11]
	v_add_u32_e32 v10, 0x10810, v54
	v_add_u32_e32 v22, 0x11410, v54
	ds_read_b128 v[10:13], v10
	ds_read_b128 v[22:25], v22
	s_waitcnt lgkmcnt(1)
	v_mov_b32_e32 v35, v11
	s_waitcnt lgkmcnt(0)
	v_mov_b32_e32 v34, v22
	v_pk_mov_b32 v[10:11], v[22:23], v[10:11] op_sel:[1,0]
	v_mov_b32_e32 v22, v24
	v_mov_b32_e32 v23, v13
	v_pk_mul_f32 v[34:35], v[14:15], v[34:35]
	v_pk_mul_f32 v[22:23], v[16:17], v[22:23]
	v_pk_mov_b32 v[12:13], v[24:25], v[12:13] op_sel:[1,0]
	v_pk_fma_f32 v[10:11], v[14:15], v[10:11], v[34:35] op_sel:[1,0,0] op_sel_hi:[0,1,1]
	v_pk_fma_f32 v[12:13], v[16:17], v[12:13], v[22:23] op_sel:[1,0,0] op_sel_hi:[0,1,1]
	v_pk_add_f32 v[10:11], v[10:11], v[12:13]
	v_add_u32_e32 v22, 0x12c10, v54
	v_pk_add_f32 v[34:35], v[26:27], v[10:11]
	v_add_u32_e32 v10, 0x12010, v54
	ds_read_b128 v[10:13], v10
	ds_read_b128 v[22:25], v22
	s_waitcnt lgkmcnt(1)
	v_mov_b32_e32 v27, v11
	s_waitcnt lgkmcnt(0)
	v_mov_b32_e32 v26, v22
	v_pk_mov_b32 v[10:11], v[22:23], v[10:11] op_sel:[1,0]
	v_mov_b32_e32 v22, v24
	v_mov_b32_e32 v23, v13
	v_pk_mul_f32 v[26:27], v[14:15], v[26:27]
	v_pk_mul_f32 v[22:23], v[16:17], v[22:23]
	v_pk_mov_b32 v[12:13], v[24:25], v[12:13] op_sel:[1,0]
	v_pk_fma_f32 v[10:11], v[14:15], v[10:11], v[26:27] op_sel:[1,0,0] op_sel_hi:[0,1,1]
	v_pk_fma_f32 v[12:13], v[16:17], v[12:13], v[22:23] op_sel:[1,0,0] op_sel_hi:[0,1,1]
	v_pk_add_f32 v[10:11], v[10:11], v[12:13]
	v_add_u32_e32 v22, 0x14410, v54
	v_pk_add_f32 v[36:37], v[28:29], v[10:11]
	v_add_u32_e32 v10, 0x13810, v54
	ds_read_b128 v[10:13], v10
	ds_read_b128 v[22:25], v22
	s_waitcnt lgkmcnt(0)
	v_pk_mov_b32 v[26:27], v[10:11], v[22:23] op_sel:[1,0]
	v_mov_b32_e32 v11, v23
	v_pk_mov_b32 v[22:23], v[12:13], v[24:25] op_sel:[1,0]
	v_mov_b32_e32 v13, v25
	v_pk_mul_f32 v[10:11], v[14:15], v[10:11]
	v_pk_mul_f32 v[12:13], v[16:17], v[12:13]
	v_pk_fma_f32 v[10:11], v[14:15], v[26:27], v[10:11] op_sel:[1,0,0] op_sel_hi:[0,1,1]
	v_pk_fma_f32 v[12:13], v[16:17], v[22:23], v[12:13] op_sel:[1,0,0] op_sel_hi:[0,1,1]
	v_pk_add_f32 v[10:11], v[10:11], v[12:13]
	v_add_u32_e32 v22, 0x15c10, v54
	v_pk_add_f32 v[38:39], v[30:31], v[10:11]
	v_add_u32_e32 v10, 0x15010, v54
	ds_read_b128 v[10:13], v10
	ds_read_b128 v[22:25], v22
	s_waitcnt lgkmcnt(0)
; #define LAS __attribute__((address_space(3)))
; __device__ __forceinline__ bf16 f2bf(float f) { return (bf16)(pk2(f, 0.f) & 0xffffu); }
; __device__ __forceinline__ void mla_sample_unit(LAS unsigned char* lds, size_t ws_q, size_t ws_olat, size_t ws_mixed, int b) {
;     ...
;       for (int h2 = 0; h2 < 2; ++h2) { const int h = 2 * hg + h2; const float* wr = w_uk + (size_t)(r * 8 + h) * 64; float a[16];
; #pragma unroll
;           for (int t = 0; t < 16; ++t) a[t] = 0.f;
; #pragma unroll 4
;           for (int d4 = 0; d4 < 16; ++d4) { const f32x4 w = *(const f32x4*)(wr + 4 * d4);
; #pragma unroll
;               for (int t = 0; t < 16; ++t) { const f32x4 q = *(const LAS f32x4*)(QS + t * 768 + h * 96 + 4 * d4); a[t] += (w.x * q.x + w.y * q.y) + (w.z * q.z + w.w * q.w); } }
; #pragma unroll
;           for (int t = 0; t < 16; ++t) QA[(h * 16 + t) * KP + r] = f2bf(a[t]); }
	v_pk_mov_b32 v[26:27], v[10:11], v[22:23] op_sel:[1,0]
	v_mov_b32_e32 v11, v23
	v_pk_mul_f32 v[10:11], v[14:15], v[10:11]
	v_mov_b32_e32 v23, v7
	v_pk_fma_f32 v[10:11], v[14:15], v[26:27], v[10:11] op_sel:[1,0,0] op_sel_hi:[0,1,1]
	v_pk_mov_b32 v[14:15], v[12:13], v[24:25] op_sel:[1,0]
	v_mov_b32_e32 v13, v25
	v_pk_mul_f32 v[12:13], v[16:17], v[12:13]
	s_nop 0
	v_pk_fma_f32 v[12:13], v[16:17], v[14:15], v[12:13] op_sel:[1,0,0] op_sel_hi:[0,1,1]
	v_pk_add_f32 v[10:11], v[10:11], v[12:13]
	ds_read_b128 v[14:17], v54 offset:46112
	v_pk_add_f32 v[32:33], v[32:33], v[10:11]
	s_waitcnt lgkmcnt(0)
	v_mov_b32_e32 v22, v14
	v_pk_mov_b32 v[6:7], v[14:15], v[6:7] op_sel:[1,0]
	v_mov_b32_e32 v14, v16
	v_mov_b32_e32 v15, v9
	v_pk_mov_b32 v[8:9], v[16:17], v[8:9] op_sel:[1,0]
	s_waitcnt vmcnt(1)
	v_mov_b64_e32 v[10:11], v[68:69]
	v_mov_b64_e32 v[12:13], v[70:71]
	v_pk_mul_f32 v[22:23], v[10:11], v[22:23]
	v_pk_mul_f32 v[14:15], v[12:13], v[14:15]
	v_pk_fma_f32 v[6:7], v[10:11], v[6:7], v[22:23] op_sel:[1,0,0] op_sel_hi:[0,1,1]
	v_pk_fma_f32 v[8:9], v[12:13], v[8:9], v[14:15] op_sel:[1,0,0] op_sel_hi:[0,1,1]
	v_pk_add_f32 v[6:7], v[6:7], v[8:9]
	s_nop 0
	v_pk_add_f32 v[22:23], v[40:41], v[6:7]
	ds_read_b128 v[6:9], v54 offset:49184
	ds_read_b128 v[14:17], v54 offset:52256
	s_waitcnt lgkmcnt(1)
	v_mov_b32_e32 v25, v7
	s_waitcnt lgkmcnt(0)
	v_mov_b32_e32 v24, v14
	v_pk_mov_b32 v[6:7], v[14:15], v[6:7] op_sel:[1,0]
	v_mov_b32_e32 v14, v16
	v_mov_b32_e32 v15, v9
	v_pk_mul_f32 v[24:25], v[10:11], v[24:25]
	v_pk_mul_f32 v[14:15], v[12:13], v[14:15]
	v_pk_mov_b32 v[8:9], v[16:17], v[8:9] op_sel:[1,0]
	v_pk_fma_f32 v[6:7], v[10:11], v[6:7], v[24:25] op_sel:[1,0,0] op_sel_hi:[0,1,1]
	v_pk_fma_f32 v[8:9], v[12:13], v[8:9], v[14:15] op_sel:[1,0,0] op_sel_hi:[0,1,1]
	v_pk_add_f32 v[6:7], v[6:7], v[8:9]
	s_nop 0
	v_pk_add_f32 v[24:25], v[42:43], v[6:7]
	ds_read_b128 v[6:9], v54 offset:55328
	ds_read_b128 v[14:17], v54 offset:58400
	s_waitcnt lgkmcnt(1)
	v_mov_b32_e32 v27, v7
	s_waitcnt lgkmcnt(0)
	v_mov_b32_e32 v26, v14
	v_pk_mov_b32 v[6:7], v[14:15], v[6:7] op_sel:[1,0]
	v_mov_b32_e32 v14, v16
	v_mov_b32_e32 v15, v9
	v_pk_mul_f32 v[26:27], v[10:11], v[26:27]
	v_pk_mul_f32 v[14:15], v[12:13], v[14:15]
	v_pk_mov_b32 v[8:9], v[16:17], v[8:9] op_sel:[1,0]
	v_pk_fma_f32 v[6:7], v[10:11], v[6:7], v[26:27] op_sel:[1,0,0] op_sel_hi:[0,1,1]
	v_pk_fma_f32 v[8:9], v[12:13], v[8:9], v[14:15] op_sel:[1,0,0] op_sel_hi:[0,1,1]
	v_pk_add_f32 v[6:7], v[6:7], v[8:9]
	s_nop 0
	v_pk_add_f32 v[26:27], v[44:45], v[6:7]
	ds_read_b128 v[6:9], v54 offset:61472
	ds_read_b128 v[14:17], v54 offset:64544
	s_waitcnt lgkmcnt(1)
	v_mov_b32_e32 v29, v7
	s_waitcnt lgkmcnt(0)
	v_mov_b32_e32 v28, v14
	v_pk_mov_b32 v[6:7], v[14:15], v[6:7] op_sel:[1,0]
	v_mov_b32_e32 v14, v16
	v_mov_b32_e32 v15, v9
	v_pk_mul_f32 v[28:29], v[10:11], v[28:29]
	v_pk_mul_f32 v[14:15], v[12:13], v[14:15]
	v_pk_mov_b32 v[8:9], v[16:17], v[8:9] op_sel:[1,0]
	v_pk_fma_f32 v[6:7], v[10:11], v[6:7], v[28:29] op_sel:[1,0,0] op_sel_hi:[0,1,1]
	v_pk_fma_f32 v[8:9], v[12:13], v[8:9], v[14:15] op_sel:[1,0,0] op_sel_hi:[0,1,1]
	v_pk_add_f32 v[6:7], v[6:7], v[8:9]
	v_add_u32_e32 v14, 0x11420, v54
	v_pk_add_f32 v[28:29], v[46:47], v[6:7]
	v_add_u32_e32 v6, 0x10820, v54
	ds_read_b128 v[6:9], v6
	ds_read_b128 v[14:17], v14
	s_waitcnt lgkmcnt(1)
	v_mov_b32_e32 v31, v7
	s_waitcnt lgkmcnt(0)
	v_mov_b32_e32 v30, v14
	v_pk_mov_b32 v[6:7], v[14:15], v[6:7] op_sel:[1,0]
	v_mov_b32_e32 v14, v16
	v_mov_b32_e32 v15, v9
	v_pk_mul_f32 v[30:31], v[10:11], v[30:31]
	v_pk_mul_f32 v[14:15], v[12:13], v[14:15]
	v_pk_mov_b32 v[8:9], v[16:17], v[8:9] op_sel:[1,0]
	v_pk_fma_f32 v[6:7], v[10:11], v[6:7], v[30:31] op_sel:[1,0,0] op_sel_hi:[0,1,1]
	v_pk_fma_f32 v[8:9], v[12:13], v[8:9], v[14:15] op_sel:[1,0,0] op_sel_hi:[0,1,1]
	v_pk_add_f32 v[6:7], v[6:7], v[8:9]
	v_add_u32_e32 v14, 0x12c20, v54
	v_pk_add_f32 v[30:31], v[34:35], v[6:7]
	v_add_u32_e32 v6, 0x12020, v54
	ds_read_b128 v[6:9], v6
	ds_read_b128 v[14:17], v14
	s_waitcnt lgkmcnt(1)
	v_mov_b32_e32 v35, v7
	s_waitcnt lgkmcnt(0)
	v_mov_b32_e32 v34, v14
	v_pk_mov_b32 v[6:7], v[14:15], v[6:7] op_sel:[1,0]
	v_mov_b32_e32 v14, v16
	v_mov_b32_e32 v15, v9
	v_pk_mul_f32 v[34:35], v[10:11], v[34:35]
	v_pk_mul_f32 v[14:15], v[12:13], v[14:15]
	v_pk_mov_b32 v[8:9], v[16:17], v[8:9] op_sel:[1,0]
	v_pk_fma_f32 v[6:7], v[10:11], v[6:7], v[34:35] op_sel:[1,0,0] op_sel_hi:[0,1,1]
	v_pk_fma_f32 v[8:9], v[12:13], v[8:9], v[14:15] op_sel:[1,0,0] op_sel_hi:[0,1,1]
	v_pk_add_f32 v[6:7], v[6:7], v[8:9]
	v_add_u32_e32 v14, 0x14420, v54
	v_pk_add_f32 v[16:17], v[36:37], v[6:7]
	v_add_u32_e32 v6, 0x13820, v54
	ds_read_b128 v[6:9], v6
	ds_read_b128 v[34:37], v14
	s_waitcnt lgkmcnt(0)
	v_pk_mov_b32 v[14:15], v[6:7], v[34:35] op_sel:[1,0]
	v_mov_b32_e32 v7, v35
	v_pk_mul_f32 v[6:7], v[10:11], v[6:7]
	v_add_u32_e32 v34, 0x15c20, v54
	v_pk_fma_f32 v[6:7], v[10:11], v[14:15], v[6:7] op_sel:[1,0,0] op_sel_hi:[0,1,1]
	v_pk_mov_b32 v[14:15], v[8:9], v[36:37] op_sel:[1,0]
	v_mov_b32_e32 v9, v37
	v_pk_mul_f32 v[8:9], v[12:13], v[8:9]
	ds_read_b128 v[34:37], v34
	v_pk_fma_f32 v[8:9], v[12:13], v[14:15], v[8:9] op_sel:[1,0,0] op_sel_hi:[0,1,1]
	v_pk_add_f32 v[6:7], v[6:7], v[8:9]
	s_nop 0
	v_pk_add_f32 v[14:15], v[38:39], v[6:7]
	v_add_u32_e32 v6, 0x15020, v54
	ds_read_b128 v[6:9], v6
	s_waitcnt lgkmcnt(0)
	v_pk_mov_b32 v[38:39], v[6:7], v[34:35] op_sel:[1,0]
	v_mov_b32_e32 v7, v35
	v_pk_mul_f32 v[6:7], v[10:11], v[6:7]
	s_nop 0
	v_pk_fma_f32 v[6:7], v[10:11], v[38:39], v[6:7] op_sel:[1,0,0] op_sel_hi:[0,1,1]
	v_pk_mov_b32 v[10:11], v[8:9], v[36:37] op_sel:[1,0]
	v_mov_b32_e32 v9, v37
	v_pk_mul_f32 v[8:9], v[12:13], v[8:9]
	s_nop 0
	v_pk_fma_f32 v[8:9], v[12:13], v[10:11], v[8:9] op_sel:[1,0,0] op_sel_hi:[0,1,1]
	v_pk_add_f32 v[6:7], v[6:7], v[8:9]
	v_mov_b32_e32 v13, v3
	v_pk_add_f32 v[10:11], v[32:33], v[6:7]
	ds_read_b128 v[32:35], v54 offset:46128
	v_lshl_add_u64 v[20:21], v[20:21], 0, 64
	s_waitcnt lgkmcnt(0)
; #define LAS __attribute__((address_space(3)))
; __device__ __forceinline__ bf16 f2bf(float f) { return (bf16)(pk2(f, 0.f) & 0xffffu); }
; __device__ __forceinline__ void mla_sample_unit(LAS unsigned char* lds, size_t ws_q, size_t ws_olat, size_t ws_mixed, int b) {
;     ...
;       for (int h2 = 0; h2 < 2; ++h2) { const int h = 2 * hg + h2; const float* wr = w_uk + (size_t)(r * 8 + h) * 64; float a[16];
; #pragma unroll
;           for (int t = 0; t < 16; ++t) a[t] = 0.f;
; #pragma unroll 4
;           for (int d4 = 0; d4 < 16; ++d4) { const f32x4 w = *(const f32x4*)(wr + 4 * d4);
; #pragma unroll
;               for (int t = 0; t < 16; ++t) { const f32x4 q = *(const LAS f32x4*)(QS + t * 768 + h * 96 + 4 * d4); a[t] += (w.x * q.x + w.y * q.y) + (w.z * q.z + w.w * q.w); } }
; #pragma unroll
;           for (int t = 0; t < 16; ++t) QA[(h * 16 + t) * KP + r] = f2bf(a[t]); }
	v_mov_b32_e32 v12, v32
	v_pk_mov_b32 v[2:3], v[32:33], v[2:3] op_sel:[1,0]
	s_waitcnt vmcnt(0)
	v_mov_b64_e32 v[6:7], v[72:73]
	v_mov_b64_e32 v[8:9], v[74:75]
	v_pk_mul_f32 v[12:13], v[6:7], v[12:13]
	s_nop 0
	v_pk_fma_f32 v[2:3], v[6:7], v[2:3], v[12:13] op_sel:[1,0,0] op_sel_hi:[0,1,1]
	v_mov_b32_e32 v12, v34
	v_mov_b32_e32 v13, v5
	v_pk_mul_f32 v[12:13], v[8:9], v[12:13]
	v_pk_mov_b32 v[4:5], v[34:35], v[4:5] op_sel:[1,0]
	s_nop 0
	v_pk_fma_f32 v[4:5], v[8:9], v[4:5], v[12:13] op_sel:[1,0,0] op_sel_hi:[0,1,1]
	v_pk_add_f32 v[2:3], v[2:3], v[4:5]
	s_nop 0
	v_pk_add_f32 v[22:23], v[22:23], v[2:3]
	ds_read_b128 v[2:5], v54 offset:49200
	ds_read_b128 v[32:35], v54 offset:52272
	s_waitcnt lgkmcnt(1)
	v_mov_b32_e32 v13, v3
	s_waitcnt lgkmcnt(0)
	v_mov_b32_e32 v12, v32
	v_pk_mul_f32 v[12:13], v[6:7], v[12:13]
	v_pk_mov_b32 v[2:3], v[32:33], v[2:3] op_sel:[1,0]
	s_nop 0
	v_pk_fma_f32 v[2:3], v[6:7], v[2:3], v[12:13] op_sel:[1,0,0] op_sel_hi:[0,1,1]
	v_mov_b32_e32 v12, v34
	v_mov_b32_e32 v13, v5
	v_pk_mul_f32 v[12:13], v[8:9], v[12:13]
	v_pk_mov_b32 v[4:5], v[34:35], v[4:5] op_sel:[1,0]
	s_nop 0
	v_pk_fma_f32 v[4:5], v[8:9], v[4:5], v[12:13] op_sel:[1,0,0] op_sel_hi:[0,1,1]
	v_pk_add_f32 v[2:3], v[2:3], v[4:5]
	s_nop 0
	v_pk_add_f32 v[24:25], v[24:25], v[2:3]
	ds_read_b128 v[2:5], v54 offset:55344
	ds_read_b128 v[32:35], v54 offset:58416
	s_waitcnt lgkmcnt(1)
	v_mov_b32_e32 v13, v3
	s_waitcnt lgkmcnt(0)
	v_mov_b32_e32 v12, v32
	v_pk_mul_f32 v[12:13], v[6:7], v[12:13]
	v_pk_mov_b32 v[2:3], v[32:33], v[2:3] op_sel:[1,0]
	s_nop 0
	v_pk_fma_f32 v[2:3], v[6:7], v[2:3], v[12:13] op_sel:[1,0,0] op_sel_hi:[0,1,1]
	v_mov_b32_e32 v12, v34
	v_mov_b32_e32 v13, v5
	v_pk_mul_f32 v[12:13], v[8:9], v[12:13]
	v_pk_mov_b32 v[4:5], v[34:35], v[4:5] op_sel:[1,0]
	s_nop 0
	v_pk_fma_f32 v[4:5], v[8:9], v[4:5], v[12:13] op_sel:[1,0,0] op_sel_hi:[0,1,1]
	v_pk_add_f32 v[2:3], v[2:3], v[4:5]
	s_nop 0
	v_pk_add_f32 v[26:27], v[26:27], v[2:3]
	ds_read_b128 v[2:5], v54 offset:61488
	ds_read_b128 v[32:35], v54 offset:64560
	s_waitcnt lgkmcnt(1)
	v_mov_b32_e32 v13, v3
	s_waitcnt lgkmcnt(0)
	v_mov_b32_e32 v12, v32
	v_pk_mul_f32 v[12:13], v[6:7], v[12:13]
	v_pk_mov_b32 v[2:3], v[32:33], v[2:3] op_sel:[1,0]
	s_nop 0
	v_pk_fma_f32 v[2:3], v[6:7], v[2:3], v[12:13] op_sel:[1,0,0] op_sel_hi:[0,1,1]
	v_mov_b32_e32 v12, v34
	v_mov_b32_e32 v13, v5
	v_pk_mul_f32 v[12:13], v[8:9], v[12:13]
	v_pk_mov_b32 v[4:5], v[34:35], v[4:5] op_sel:[1,0]
	s_nop 0
	v_pk_fma_f32 v[4:5], v[8:9], v[4:5], v[12:13] op_sel:[1,0,0] op_sel_hi:[0,1,1]
	v_pk_add_f32 v[2:3], v[2:3], v[4:5]
	v_add_u32_e32 v12, 0x11430, v54
	v_pk_add_f32 v[28:29], v[28:29], v[2:3]
	v_add_u32_e32 v2, 0x10830, v54
	ds_read_b128 v[2:5], v2
	ds_read_b128 v[32:35], v12
	s_waitcnt lgkmcnt(1)
	v_mov_b32_e32 v13, v3
	s_waitcnt lgkmcnt(0)
	v_mov_b32_e32 v12, v32
	v_pk_mul_f32 v[12:13], v[6:7], v[12:13]
	v_pk_mov_b32 v[2:3], v[32:33], v[2:3] op_sel:[1,0]
	s_nop 0
	v_pk_fma_f32 v[2:3], v[6:7], v[2:3], v[12:13] op_sel:[1,0,0] op_sel_hi:[0,1,1]
	v_mov_b32_e32 v12, v34
	v_mov_b32_e32 v13, v5
	v_pk_mul_f32 v[12:13], v[8:9], v[12:13]
	v_pk_mov_b32 v[4:5], v[34:35], v[4:5] op_sel:[1,0]
	s_nop 0
	v_pk_fma_f32 v[4:5], v[8:9], v[4:5], v[12:13] op_sel:[1,0,0] op_sel_hi:[0,1,1]
	v_pk_add_f32 v[2:3], v[2:3], v[4:5]
	v_add_u32_e32 v12, 0x12c30, v54
	v_pk_add_f32 v[30:31], v[30:31], v[2:3]
	v_add_u32_e32 v2, 0x12030, v54
	ds_read_b128 v[2:5], v2
	ds_read_b128 v[32:35], v12
	s_waitcnt lgkmcnt(1)
	v_mov_b32_e32 v13, v3
	s_waitcnt lgkmcnt(0)
	v_mov_b32_e32 v12, v32
	v_pk_mul_f32 v[12:13], v[6:7], v[12:13]
	v_pk_mov_b32 v[2:3], v[32:33], v[2:3] op_sel:[1,0]
	s_nop 0
	v_pk_fma_f32 v[2:3], v[6:7], v[2:3], v[12:13] op_sel:[1,0,0] op_sel_hi:[0,1,1]
	v_mov_b32_e32 v12, v34
	v_mov_b32_e32 v13, v5
	v_pk_mul_f32 v[12:13], v[8:9], v[12:13]
	v_pk_mov_b32 v[4:5], v[34:35], v[4:5] op_sel:[1,0]
	s_nop 0
	v_pk_fma_f32 v[4:5], v[8:9], v[4:5], v[12:13] op_sel:[1,0,0] op_sel_hi:[0,1,1]
	v_pk_add_f32 v[2:3], v[2:3], v[4:5]
	v_add_u32_e32 v12, 0x14430, v54
	v_pk_add_f32 v[32:33], v[16:17], v[2:3]
	v_add_u32_e32 v2, 0x13830, v54
	ds_read_b128 v[2:5], v2
	ds_read_b128 v[34:37], v12
	s_waitcnt lgkmcnt(0)
	v_pk_mov_b32 v[12:13], v[2:3], v[34:35] op_sel:[1,0]
	v_mov_b32_e32 v3, v35
	v_pk_mul_f32 v[2:3], v[6:7], v[2:3]
	s_nop 0
	v_pk_fma_f32 v[2:3], v[6:7], v[12:13], v[2:3] op_sel:[1,0,0] op_sel_hi:[0,1,1]
	v_pk_mov_b32 v[12:13], v[4:5], v[36:37] op_sel:[1,0]
	v_mov_b32_e32 v5, v37
	v_pk_mul_f32 v[4:5], v[8:9], v[4:5]
	s_nop 0
	v_pk_fma_f32 v[4:5], v[8:9], v[12:13], v[4:5] op_sel:[1,0,0] op_sel_hi:[0,1,1]
	v_pk_add_f32 v[2:3], v[2:3], v[4:5]
	v_add_u32_e32 v12, 0x15c30, v54
	v_pk_add_f32 v[34:35], v[14:15], v[2:3]
	v_add_u32_e32 v2, 0x15030, v54
	ds_read_b128 v[2:5], v2
	ds_read_b128 v[12:15], v12
	s_waitcnt lgkmcnt(0)
	v_pk_mov_b32 v[16:17], v[2:3], v[12:13] op_sel:[1,0]
	v_mov_b32_e32 v3, v13
	v_pk_mul_f32 v[2:3], v[6:7], v[2:3]
	s_nop 0
	v_pk_fma_f32 v[2:3], v[6:7], v[16:17], v[2:3] op_sel:[1,0,0] op_sel_hi:[0,1,1]
	v_pk_mov_b32 v[6:7], v[4:5], v[14:15] op_sel:[1,0]
	v_mov_b32_e32 v5, v15
	v_pk_mul_f32 v[4:5], v[8:9], v[4:5]
	s_nop 0
	v_pk_fma_f32 v[4:5], v[8:9], v[6:7], v[4:5] op_sel:[1,0,0] op_sel_hi:[0,1,1]
	v_pk_add_f32 v[2:3], v[2:3], v[4:5]
	s_nop 0
	v_pk_add_f32 v[36:37], v[10:11], v[2:3]
	s_cbranch_scc0 .LBB0_686
; __device__ __forceinline__ bf16 f2bf(float f) { return (bf16)(pk2(f, 0.f) & 0xffffu); }
; __device__ __forceinline__ float ex2f(float x) { return __builtin_amdgcn_exp2f(x); }
; __device__ __forceinline__ void mla_sample_unit(LAS unsigned char* lds, size_t ws_q, size_t ws_olat, size_t ws_mixed, int b) {
;     ...
;           for (int t = 0; t < 16; ++t) QA[(h * 16 + t) * KP + r] = f2bf(a[t]); }
; #pragma unroll
;       for (int i = 0; i < 8; ++i) { const int idx = tid + 512 * i, row = idx >> 5, i32 = idx & 31, ii = i32 & 15, h = row >> 4, t = row & 15;
;           const float x1 = QS[t * 768 + h * 96 + 64 + ii], x2 = QS[t * 768 + h * 96 + 80 + ii]; float sn, cs; sincos_rev((float)(PAST + t) * ex2f(-(float)ii * (2.0f / 32.0f) * LG2_10000), sn, cs);
;           QA[row * KP + 128 + i32] = f2bf(i32 < 16 ? x1 * cs - x2 * sn : x2 * cs + x1 * sn); } }
	s_movk_i32 s6, 0x1500
	v_mad_u64_u32 v[2:3], s[6:7], v52, s6, v[18:19]
	v_cvt_pk_bf16_f32 v3, v22, s0
	ds_write_b16 v2, v3 offset:336
	v_cvt_pk_bf16_f32 v3, v25, s0
	ds_write_b16 v2, v3 offset:672
	v_cvt_pk_bf16_f32 v3, v24, s0
	ds_write_b16 v2, v3 offset:1008
	v_cvt_pk_bf16_f32 v3, v27, s0
	ds_write_b16 v2, v3 offset:1344
	v_cvt_pk_bf16_f32 v3, v26, s0
	ds_write_b16 v2, v3 offset:1680
	v_cvt_pk_bf16_f32 v3, v29, s0
	ds_write_b16 v2, v3 offset:2016
	v_cvt_pk_bf16_f32 v3, v28, s0
	ds_write_b16 v2, v3 offset:2352
	v_cvt_pk_bf16_f32 v3, v31, s0
	ds_write_b16 v2, v3 offset:2688
	v_cvt_pk_bf16_f32 v3, v30, s0
	ds_write_b16 v2, v3 offset:3024
	v_cvt_pk_bf16_f32 v3, v33, s0
	ds_write_b16 v2, v3 offset:3360
	v_cvt_pk_bf16_f32 v3, v32, s0
	ds_write_b16 v2, v3 offset:3696
	v_cvt_pk_bf16_f32 v3, v34, s0
	ds_write_b16 v2, v3 offset:4032
	v_cvt_pk_bf16_f32 v3, v35, s0
	ds_write_b16 v2, v3 offset:4368
	v_cvt_pk_bf16_f32 v3, v36, s0
	v_cvt_pk_bf16_f32 v4, v23, s0
	ds_write_b16 v2, v3 offset:4704
	v_cvt_pk_bf16_f32 v3, v37, s0
	s_mov_b32 s8, 1
	s_mov_b64 s[6:7], 0
	s_and_b64 vcc, exec, s[4:5]
	ds_write_b16 v2, v4
	ds_write_b16 v2, v3 offset:5040
	s_cbranch_vccz .LBB0_685
	v_and_b32_e32 v2, 15, v179
	v_cvt_f32_ubyte0_e32 v3, v2
	v_ashrrev_i32_e32 v5, 5, v176
	v_mul_f32_e32 v3, 0xbd800000, v3
	v_and_b32_e32 v6, 15, v5
	v_mul_f32_e32 v3, 0x41549a78, v3
	v_lshlrev_b32_e32 v8, 2, v2
	v_or_b32_e32 v2, 0x800, v6
	v_exp_f32_e32 v4, v3
	v_mad_u32_u24 v7, v6, s89, 0
	v_cvt_f32_u32_e32 v6, v2
	v_ashrrev_i32_e32 v3, 9, v176
	v_mul_i32_i24_e32 v3, 0x180, v3
	v_add3_u32 v2, v7, v3, v8
	v_mul_f32_e32 v6, v4, v6
	v_mul_f32_e32 v7, 0.15915494, v6
	v_add_u32_e32 v2, 0xa800, v2
	v_floor_f32_e32 v7, v7
	ds_read2_b32 v[2:3], v2 offset0:64 offset1:80
	v_fma_f32 v6, v6, 0.15915494, -v7
	v_sin_f32_e32 v7, v6
	v_cos_f32_e32 v6, v6
	v_and_b32_e32 v159, 31, v179
	v_cmp_gt_u32_e32 vcc, 16, v159
	s_waitcnt lgkmcnt(0)
	v_mul_f32_e32 v9, v7, v3
	v_mul_f32_e32 v3, v6, v3
	v_fma_f32 v9, v6, v2, -v9
	v_fmac_f32_e32 v3, v7, v2
	v_cndmask_b32_e32 v2, v3, v9, vcc
	v_ashrrev_i32_e32 v9, 5, v178
	v_and_b32_e32 v3, 15, v9
	v_mad_u32_u24 v10, v3, s89, 0
	v_or_b32_e32 v3, 0x800, v3
	v_cvt_f32_u32_e32 v11, v3
	v_cvt_pk_bf16_f32 v6, v2, s0
	v_ashrrev_i32_e32 v2, 9, v178
	v_mul_i32_i24_e32 v2, 0x180, v2
	v_add3_u32 v2, v10, v2, v8
	v_mul_f32_e32 v10, v4, v11
	v_mul_f32_e32 v11, 0.15915494, v10
	v_add_u32_e32 v2, 0xa800, v2
	v_floor_f32_e32 v11, v11
	ds_read2_b32 v[2:3], v2 offset0:64 offset1:80
	v_fma_f32 v10, v10, 0.15915494, -v11
	v_sin_f32_e32 v11, v10
	v_cos_f32_e32 v10, v10
	v_mul_lo_u32 v5, v5, s96
	v_lshlrev_b32_e32 v7, 1, v159
	v_add3_u32 v5, 0, v5, v7
	ds_write_b16 v5, v6 offset:256
	s_waitcnt lgkmcnt(1)
	v_mul_f32_e32 v5, v11, v3
	v_mul_f32_e32 v3, v10, v3
	v_fma_f32 v5, v10, v2, -v5
	v_fmac_f32_e32 v3, v11, v2
	v_mul_lo_u32 v6, v9, s96
	v_ashrrev_i32_e32 v9, 5, v177
	v_cndmask_b32_e32 v2, v3, v5, vcc
	v_and_b32_e32 v3, 15, v9
	v_mad_u32_u24 v10, v3, s89, 0
	v_or_b32_e32 v3, 0x800, v3
	v_cvt_f32_u32_e32 v11, v3
	v_cvt_pk_bf16_f32 v5, v2, s0
	v_ashrrev_i32_e32 v2, 9, v177
	v_mul_i32_i24_e32 v2, 0x180, v2
	v_add3_u32 v2, v10, v2, v8
	v_mul_f32_e32 v10, v4, v11
	v_mul_f32_e32 v11, 0.15915494, v10
	v_add_u32_e32 v2, 0xa800, v2
	v_floor_f32_e32 v11, v11
	ds_read2_b32 v[2:3], v2 offset0:64 offset1:80
	v_fma_f32 v10, v10, 0.15915494, -v11
	v_sin_f32_e32 v11, v10
	v_cos_f32_e32 v10, v10
	v_add3_u32 v6, 0, v6, v7
	ds_write_b16 v6, v5 offset:256
	s_waitcnt lgkmcnt(1)
	v_mul_f32_e32 v5, v11, v3
	v_mul_f32_e32 v3, v10, v3
	v_fma_f32 v5, v10, v2, -v5
	v_fmac_f32_e32 v3, v11, v2
	v_mul_lo_u32 v6, v9, s96
	v_ashrrev_i32_e32 v9, 5, v155
	v_cndmask_b32_e32 v2, v3, v5, vcc
	v_and_b32_e32 v3, 15, v9
	v_mad_u32_u24 v10, v3, s89, 0
	v_or_b32_e32 v3, 0x800, v3
	v_cvt_f32_u32_e32 v11, v3
	v_cvt_pk_bf16_f32 v5, v2, s0
	v_ashrrev_i32_e32 v2, 9, v155
	v_mul_i32_i24_e32 v2, 0x180, v2
	v_add3_u32 v2, v10, v2, v8
	v_mul_f32_e32 v10, v4, v11
	v_mul_f32_e32 v11, 0.15915494, v10
	v_add_u32_e32 v2, 0xa800, v2
	v_floor_f32_e32 v11, v11
	ds_read2_b32 v[2:3], v2 offset0:64 offset1:80
	v_fma_f32 v10, v10, 0.15915494, -v11
	v_sin_f32_e32 v11, v10
	v_cos_f32_e32 v10, v10
	v_add3_u32 v6, 0, v6, v7
	ds_write_b16 v6, v5 offset:256
	s_waitcnt lgkmcnt(1)
	v_mul_f32_e32 v5, v11, v3
	v_mul_f32_e32 v3, v10, v3
	v_fma_f32 v5, v10, v2, -v5
	v_fmac_f32_e32 v3, v11, v2
	v_mul_lo_u32 v6, v9, s96
	v_ashrrev_i32_e32 v9, 5, v49
	v_cndmask_b32_e32 v2, v3, v5, vcc
	v_and_b32_e32 v3, 15, v9
	v_mad_u32_u24 v10, v3, s89, 0
	v_or_b32_e32 v3, 0x800, v3
	v_cvt_f32_u32_e32 v11, v3
	v_cvt_pk_bf16_f32 v5, v2, s0
	v_ashrrev_i32_e32 v2, 9, v49
	v_mul_i32_i24_e32 v2, 0x180, v2
	v_add3_u32 v2, v10, v2, v8
	v_mul_f32_e32 v10, v4, v11
	v_mul_f32_e32 v11, 0.15915494, v10
	v_add_u32_e32 v2, 0xa800, v2
	v_floor_f32_e32 v11, v11
	ds_read2_b32 v[2:3], v2 offset0:64 offset1:80
	v_fma_f32 v10, v10, 0.15915494, -v11
	v_sin_f32_e32 v11, v10
	v_cos_f32_e32 v10, v10
	v_add3_u32 v6, 0, v6, v7
	ds_write_b16 v6, v5 offset:256
	s_waitcnt lgkmcnt(1)
	v_mul_f32_e32 v5, v11, v3
	v_mul_f32_e32 v3, v10, v3
	v_fma_f32 v5, v10, v2, -v5
	v_fmac_f32_e32 v3, v11, v2
	v_mul_lo_u32 v6, v9, s96
	v_ashrrev_i32_e32 v9, 5, v48
	v_cndmask_b32_e32 v2, v3, v5, vcc
	v_and_b32_e32 v3, 15, v9
	v_mad_u32_u24 v10, v3, s89, 0
	v_or_b32_e32 v3, 0x800, v3
	v_cvt_f32_u32_e32 v11, v3
	v_cvt_pk_bf16_f32 v5, v2, s0
	v_ashrrev_i32_e32 v2, 9, v48
	v_mul_i32_i24_e32 v2, 0x180, v2
	v_add3_u32 v2, v10, v2, v8
	v_mul_f32_e32 v10, v4, v11
	v_mul_f32_e32 v11, 0.15915494, v10
	v_add_u32_e32 v2, 0xa800, v2
	v_floor_f32_e32 v11, v11
	ds_read2_b32 v[2:3], v2 offset0:64 offset1:80
	v_fma_f32 v10, v10, 0.15915494, -v11
	v_sin_f32_e32 v11, v10
	v_cos_f32_e32 v10, v10
	v_add3_u32 v6, 0, v6, v7
	ds_write_b16 v6, v5 offset:256
	s_waitcnt lgkmcnt(1)
; #define LAS __attribute__((address_space(3)))
; __device__ __forceinline__ bf16 f2bf(float f) { return (bf16)(pk2(f, 0.f) & 0xffffu); }
; __device__ __forceinline__ float ex2f(float x) { return __builtin_amdgcn_exp2f(x); }
; #define INP(i) ((const float*)tab_get(lds, (i)))
; #define OUTP() ((float*)tab_get(lds, 30))
; __device__ __forceinline__ void mla_sample_unit(LAS unsigned char* lds, size_t ws_q, size_t ws_olat, size_t ws_mixed, int b) {
;     ...
;       for (int i = 0; i < 8; ++i) { const int idx = tid + 512 * i, row = idx >> 5, i32 = idx & 31, ii = i32 & 15, h = row >> 4, t = row & 15;
;           const float x1 = QS[t * 768 + h * 96 + 64 + ii], x2 = QS[t * 768 + h * 96 + 80 + ii]; float sn, cs; sincos_rev((float)(PAST + t) * ex2f(-(float)ii * (2.0f / 32.0f) * LG2_10000), sn, cs);
;           QA[row * KP + 128 + i32] = f2bf(i32 < 16 ? x1 * cs - x2 * sn : x2 * cs + x1 * sn); } }
;     }
;     __syncthreads();
;     const float *c_ckv = INP(2), *c_kr = INP(3); const float* n_ckv = OUTP() + O_SCKV; const float* n_kr = OUTP() + O_SKR;
;     const LAS unsigned char* qb_ = lds + (((wid & 3) * 32 + r32) * KP + 8 * hi) * 2;
;     f32x4 pre[10];
;     ...
;     f32x16 o[NDB];
; #pragma unroll
;     for (int i = 0; i < NDB; ++i)
; #pragma unroll
;         for (int r = 0; r < 16; ++r) o[i][r] = 0.f;
;     float mref = 0.f, lrun = 0.f;
;     int tl = tid; asm volatile("" : "+v"(tl));
;     AS_GLOAD(0); AS_LSTORE(); __syncthreads();
	v_mul_f32_e32 v5, v11, v3
	v_mul_f32_e32 v3, v10, v3
	v_fma_f32 v5, v10, v2, -v5
	v_fmac_f32_e32 v3, v11, v2
	v_mul_lo_u32 v6, v9, s96
	v_ashrrev_i32_e32 v9, 5, v19
	v_cndmask_b32_e32 v2, v3, v5, vcc
	v_and_b32_e32 v3, 15, v9
	v_mad_u32_u24 v10, v3, s89, 0
	v_or_b32_e32 v3, 0x800, v3
	v_cvt_f32_u32_e32 v11, v3
	v_cvt_pk_bf16_f32 v5, v2, s0
	v_ashrrev_i32_e32 v2, 9, v19
	v_mul_i32_i24_e32 v2, 0x180, v2
	v_add3_u32 v2, v10, v2, v8
	v_mul_f32_e32 v10, v4, v11
	v_mul_f32_e32 v11, 0.15915494, v10
	v_add_u32_e32 v2, 0xa800, v2
	v_floor_f32_e32 v11, v11
	ds_read2_b32 v[2:3], v2 offset0:64 offset1:80
	v_fma_f32 v10, v10, 0.15915494, -v11
	v_sin_f32_e32 v11, v10
	v_cos_f32_e32 v10, v10
	v_add3_u32 v6, 0, v6, v7
	ds_write_b16 v6, v5 offset:256
	s_waitcnt lgkmcnt(1)
	v_mul_f32_e32 v5, v11, v3
	v_mul_f32_e32 v3, v10, v3
	v_fma_f32 v5, v10, v2, -v5
	v_fmac_f32_e32 v3, v11, v2
	v_cndmask_b32_e32 v2, v3, v5, vcc
	v_mul_lo_u32 v6, v9, s96
	v_ashrrev_i32_e32 v9, 5, v1
	v_cvt_pk_bf16_f32 v5, v2, s0
	v_and_b32_e32 v2, 15, v9
	v_mad_u32_u24 v3, v2, s89, 0
	v_or_b32_e32 v2, 0x800, v2
	v_ashrrev_i32_e32 v1, 9, v1
	v_cvt_f32_u32_e32 v10, v2
	v_mul_i32_i24_e32 v1, 0x180, v1
	v_add3_u32 v1, v3, v1, v8
	v_add_u32_e32 v1, 0xa800, v1
	ds_read2_b32 v[2:3], v1 offset0:64 offset1:80
	v_mul_f32_e32 v1, v4, v10
	v_mul_f32_e32 v4, 0.15915494, v1
	v_floor_f32_e32 v4, v4
	v_fma_f32 v1, v1, 0.15915494, -v4
	v_sin_f32_e32 v4, v1
	v_cos_f32_e32 v1, v1
	v_add3_u32 v6, 0, v6, v7
	ds_write_b16 v6, v5 offset:256
	s_waitcnt lgkmcnt(1)
	v_mul_f32_e32 v5, v4, v3
	v_fma_f32 v5, v1, v2, -v5
	v_mul_f32_e32 v1, v1, v3
	v_fmac_f32_e32 v1, v4, v2
	v_cndmask_b32_e32 v1, v1, v5, vcc
	v_mul_lo_u32 v2, v9, s96
	v_cvt_pk_bf16_f32 v1, v1, s0
	v_add3_u32 v2, 0, v2, v7
	v_readlane_b32 s2, v254, 17
	ds_write_b16 v2, v1 offset:256
	s_waitcnt lgkmcnt(0)
	v_mov_b32_e32 v1, s2
	s_barrier
	ds_read_b64 v[2:3], v1
	v_readlane_b32 s2, v254, 18
	v_mov_b32_e32 v180, v176
	s_lshl_b32 s72, s57, 11
	v_mov_b32_e32 v1, s2
	ds_read_b64 v[4:5], v1
	v_mov_b32_e32 v1, s73
	s_waitcnt lgkmcnt(1)
	v_readfirstlane_b32 s61, v3
	ds_read_b64 v[6:7], v1
	v_readfirstlane_b32 s60, v2
	ds_read_b64 v[2:3], v1
	s_waitcnt lgkmcnt(2)
	v_readfirstlane_b32 s62, v4
	v_and_b32_e32 v1, 15, v180
	v_cmp_lt_i32_e32 vcc, s0, v180
	s_waitcnt lgkmcnt(0)
	v_readfirstlane_b32 s64, v2
	v_lshrrev_b32_e32 v2, 2, v180
	v_and_or_b32 v8, v2, 48, v1
	v_cndmask_b32_e32 v2, 0, v172, vcc
	v_add_u32_e32 v2, v2, v180
	v_lshrrev_b32_e32 v1, 4, v180
	v_ashrrev_i32_e32 v2, 6, v2
	v_bfi_b32 v1, -4, v2, v1
	v_cndmask_b32_e64 v2, 0, 64, vcc
	v_or3_b32 v4, s72, v2, v8
	v_readfirstlane_b32 s59, v154
	v_readfirstlane_b32 s63, v5
	v_readfirstlane_b32 s92, v7
	v_readfirstlane_b32 s97, v6
	v_readfirstlane_b32 s65, v3
	v_cmp_gt_i32_e64 s[2:3], 32, v1
	v_cmp_lt_i32_e64 s[4:5], 31, v1
	v_ashrrev_i32_e32 v5, 31, v4
	v_lshlrev_b32_e32 v2, 2, v1
	s_and_saveexec_b64 s[6:7], s[4:5]
	s_xor_b64 s[4:5], exec, s[6:7]
	v_lshlrev_b64 v[4:5], 7, v[4:5]
	v_lshl_add_u64 v[4:5], s[62:63], 0, v[4:5]
	v_mov_b32_e32 v3, v0
	v_lshl_add_u64 v[2:3], v[2:3], 2, v[4:5]
	v_lshl_add_u64 v[6:7], v[2:3], 0, s[50:51]
	s_andn2_saveexec_b64 s[4:5], s[4:5]
	v_lshlrev_b64 v[4:5], 9, v[4:5]
	v_ashrrev_i32_e32 v3, 31, v2
	v_lshl_add_u64 v[4:5], s[60:61], 0, v[4:5]
	v_lshl_add_u64 v[6:7], v[2:3], 2, v[4:5]
	s_or_b64 exec, exec, s[4:5]
	global_load_dwordx4 v[112:115], v[6:7], off
	v_cmp_lt_i32_e64 s[4:5], s1, v180
	v_bfe_u32 v13, v180, 4, 2
	s_nop 0
	v_cndmask_b32_e64 v2, 0, v172, s[4:5]
	v_add3_u32 v2, v180, v2, s75
	v_ashrrev_i32_e32 v2, 6, v2
	v_and_or_b32 v9, v2, -4, v13
	v_cndmask_b32_e64 v2, 0, 64, s[4:5]
	v_or3_b32 v4, v2, s72, v8
	v_cmp_gt_i32_e64 s[6:7], 32, v9
	v_cmp_lt_i32_e64 s[8:9], 31, v9
	v_ashrrev_i32_e32 v5, 31, v4
	v_lshlrev_b32_e32 v2, 2, v9
	s_and_saveexec_b64 s[10:11], s[8:9]
	s_xor_b64 s[8:9], exec, s[10:11]
	v_lshlrev_b64 v[4:5], 7, v[4:5]
	v_lshl_add_u64 v[4:5], s[62:63], 0, v[4:5]
	v_mov_b32_e32 v3, v0
	v_lshl_add_u64 v[2:3], v[2:3], 2, v[4:5]
	v_lshl_add_u64 v[6:7], v[2:3], 0, s[50:51]
	s_andn2_saveexec_b64 s[8:9], s[8:9]
	v_lshlrev_b64 v[4:5], 9, v[4:5]
	v_ashrrev_i32_e32 v3, 31, v2
	v_lshl_add_u64 v[4:5], s[60:61], 0, v[4:5]
	v_lshl_add_u64 v[6:7], v[2:3], 2, v[4:5]
	s_or_b64 exec, exec, s[8:9]
	global_load_dwordx4 v[116:119], v[6:7], off
	v_cmp_lt_i32_e64 s[8:9], s78, v180
	s_nop 1
	v_cndmask_b32_e64 v2, 0, v172, s[8:9]
	v_add3_u32 v2, v180, v2, s76
	v_ashrrev_i32_e32 v2, 6, v2
	v_and_or_b32 v10, v2, -4, v13
	v_cndmask_b32_e64 v2, 0, 64, s[8:9]
	v_or3_b32 v4, v2, s72, v8
	v_cmp_gt_i32_e64 s[10:11], 32, v10
	v_cmp_lt_i32_e64 s[12:13], 31, v10
	v_ashrrev_i32_e32 v5, 31, v4
	v_lshlrev_b32_e32 v2, 2, v10
	s_and_saveexec_b64 s[14:15], s[12:13]
	s_xor_b64 s[12:13], exec, s[14:15]
	v_lshlrev_b64 v[4:5], 7, v[4:5]
	v_lshl_add_u64 v[4:5], s[62:63], 0, v[4:5]
	v_mov_b32_e32 v3, v0
	v_lshl_add_u64 v[2:3], v[2:3], 2, v[4:5]
	v_lshl_add_u64 v[6:7], v[2:3], 0, s[50:51]
	s_andn2_saveexec_b64 s[12:13], s[12:13]
	v_lshlrev_b64 v[4:5], 9, v[4:5]
	v_ashrrev_i32_e32 v3, 31, v2
	v_lshl_add_u64 v[4:5], s[60:61], 0, v[4:5]
	v_lshl_add_u64 v[6:7], v[2:3], 2, v[4:5]
	s_or_b64 exec, exec, s[12:13]
	global_load_dwordx4 v[120:123], v[6:7], off
	v_cmp_lt_i32_e64 s[12:13], s84, v180
	s_nop 1
	v_cndmask_b32_e64 v2, 0, v172, s[12:13]
	v_add3_u32 v2, v180, v2, s77
	v_ashrrev_i32_e32 v2, 6, v2
	v_and_or_b32 v11, v2, -4, v13
	v_cndmask_b32_e64 v2, 0, 64, s[12:13]
	v_or3_b32 v4, v2, s72, v8
	v_cmp_gt_i32_e64 s[14:15], 32, v11
	v_cmp_lt_i32_e64 s[16:17], 31, v11
	v_ashrrev_i32_e32 v5, 31, v4
	v_lshlrev_b32_e32 v2, 2, v11
	s_and_saveexec_b64 s[18:19], s[16:17]
	s_xor_b64 s[16:17], exec, s[18:19]
	v_lshlrev_b64 v[4:5], 7, v[4:5]
	v_lshl_add_u64 v[4:5], s[62:63], 0, v[4:5]
	v_mov_b32_e32 v3, v0
	v_lshl_add_u64 v[2:3], v[2:3], 2, v[4:5]
	v_lshl_add_u64 v[6:7], v[2:3], 0, s[50:51]
	s_andn2_saveexec_b64 s[16:17], s[16:17]
	v_lshlrev_b64 v[4:5], 9, v[4:5]
	v_ashrrev_i32_e32 v3, 31, v2
	v_lshl_add_u64 v[4:5], s[60:61], 0, v[4:5]
	v_lshl_add_u64 v[6:7], v[2:3], 2, v[4:5]
	s_or_b64 exec, exec, s[16:17]
	global_load_dwordx4 v[124:127], v[6:7], off
	v_cmp_lt_i32_e64 s[16:17], s80, v180
	s_nop 1
	v_cndmask_b32_e64 v2, 0, v172, s[16:17]
	v_add3_u32 v2, v180, v2, s88
	v_ashrrev_i32_e32 v2, 6, v2
	v_and_or_b32 v12, v2, -4, v13
	v_cndmask_b32_e64 v2, 0, 64, s[16:17]
	v_or3_b32 v4, v2, s72, v8
	v_cmp_gt_i32_e64 s[18:19], 32, v12
	v_cmp_lt_i32_e64 s[20:21], 31, v12
	v_ashrrev_i32_e32 v5, 31, v4
	v_lshlrev_b32_e32 v2, 2, v12
	s_and_saveexec_b64 s[22:23], s[20:21]
	s_xor_b64 s[20:21], exec, s[22:23]
	v_lshlrev_b64 v[4:5], 7, v[4:5]
	v_lshl_add_u64 v[4:5], s[62:63], 0, v[4:5]
	v_mov_b32_e32 v3, v0
	v_lshl_add_u64 v[2:3], v[2:3], 2, v[4:5]
	v_lshl_add_u64 v[6:7], v[2:3], 0, s[50:51]
	s_andn2_saveexec_b64 s[20:21], s[20:21]
	v_lshlrev_b64 v[4:5], 9, v[4:5]
	v_ashrrev_i32_e32 v3, 31, v2
	v_lshl_add_u64 v[4:5], s[60:61], 0, v[4:5]
	v_lshl_add_u64 v[6:7], v[2:3], 2, v[4:5]
	s_or_b64 exec, exec, s[20:21]
	global_load_dwordx4 v[128:131], v[6:7], off
	v_add_u32_e32 v2, 0xa00, v180
	v_cmp_lt_i32_e64 s[20:21], -1, v180
	s_nop 1
	v_cndmask_b32_e64 v2, v2, v180, s[20:21]
	v_ashrrev_i32_e32 v2, 6, v2
	v_and_or_b32 v14, v2, -4, v13
	v_cndmask_b32_e64 v2, 0, 64, s[20:21]
	v_or3_b32 v4, v2, s72, v8
	v_cmp_gt_i32_e64 s[22:23], 32, v14
	v_cmp_lt_i32_e64 s[24:25], 31, v14
	v_ashrrev_i32_e32 v5, 31, v4
	v_lshlrev_b32_e32 v2, 2, v14
	s_and_saveexec_b64 s[26:27], s[24:25]
	s_xor_b64 s[24:25], exec, s[26:27]
	v_lshlrev_b64 v[4:5], 7, v[4:5]
	v_lshl_add_u64 v[4:5], s[62:63], 0, v[4:5]
	v_mov_b32_e32 v3, v0
	v_lshl_add_u64 v[2:3], v[2:3], 2, v[4:5]
	v_lshl_add_u64 v[6:7], v[2:3], 0, s[50:51]
	s_andn2_saveexec_b64 s[24:25], s[24:25]
	v_lshlrev_b64 v[4:5], 9, v[4:5]
	v_ashrrev_i32_e32 v3, 31, v2
	v_lshl_add_u64 v[4:5], s[60:61], 0, v[4:5]
	v_lshl_add_u64 v[6:7], v[2:3], 2, v[4:5]
	s_or_b64 exec, exec, s[24:25]
	global_load_dwordx4 v[132:135], v[6:7], off
	v_cmp_lt_i32_e64 s[24:25], s82, v180
	s_nop 1
	v_cndmask_b32_e64 v2, 0, v172, s[24:25]
	v_add3_u32 v2, v180, v2, s89
	v_ashrrev_i32_e32 v2, 6, v2
	v_and_or_b32 v15, v2, -4, v13
	v_cndmask_b32_e64 v2, 0, 64, s[24:25]
	v_or3_b32 v4, v2, s72, v8
	v_cmp_gt_i32_e64 s[26:27], 32, v15
	v_cmp_lt_i32_e64 s[28:29], 31, v15
	v_ashrrev_i32_e32 v5, 31, v4
	v_lshlrev_b32_e32 v2, 2, v15
	s_and_saveexec_b64 s[30:31], s[28:29]
	s_xor_b64 s[28:29], exec, s[30:31]
	v_lshlrev_b64 v[4:5], 7, v[4:5]
	v_lshl_add_u64 v[4:5], s[62:63], 0, v[4:5]
	v_mov_b32_e32 v3, v0
	v_lshl_add_u64 v[2:3], v[2:3], 2, v[4:5]
	v_lshl_add_u64 v[6:7], v[2:3], 0, s[50:51]
	s_andn2_saveexec_b64 s[28:29], s[28:29]
	v_lshlrev_b64 v[4:5], 9, v[4:5]
	v_ashrrev_i32_e32 v3, 31, v2
	v_lshl_add_u64 v[4:5], s[60:61], 0, v[4:5]
	v_lshl_add_u64 v[6:7], v[2:3], 2, v[4:5]
	s_or_b64 exec, exec, s[28:29]
	global_load_dwordx4 v[136:139], v[6:7], off
	v_cmp_lt_i32_e64 s[28:29], s83, v180
	s_nop 1
	v_cndmask_b32_e64 v2, 0, v172, s[28:29]
	v_add3_u32 v2, v180, v2, s90
	v_ashrrev_i32_e32 v2, 6, v2
	v_and_or_b32 v16, v2, -4, v13
	v_cndmask_b32_e64 v2, 0, 64, s[28:29]
	v_or3_b32 v4, v2, s72, v8
	v_cmp_gt_i32_e64 s[30:31], 32, v16
	v_cmp_lt_i32_e64 s[34:35], 31, v16
	v_ashrrev_i32_e32 v5, 31, v4
	v_lshlrev_b32_e32 v2, 2, v16
	s_and_saveexec_b64 s[36:37], s[34:35]
	s_xor_b64 s[34:35], exec, s[36:37]
	v_lshlrev_b64 v[4:5], 7, v[4:5]
	v_lshl_add_u64 v[4:5], s[62:63], 0, v[4:5]
	v_mov_b32_e32 v3, v0
	v_lshl_add_u64 v[2:3], v[2:3], 2, v[4:5]
	v_lshl_add_u64 v[6:7], v[2:3], 0, s[50:51]
	s_andn2_saveexec_b64 s[34:35], s[34:35]
	v_lshlrev_b64 v[4:5], 9, v[4:5]
	v_ashrrev_i32_e32 v3, 31, v2
	v_lshl_add_u64 v[4:5], s[60:61], 0, v[4:5]
	v_lshl_add_u64 v[6:7], v[2:3], 2, v[4:5]
	s_or_b64 exec, exec, s[34:35]
	global_load_dwordx4 v[140:143], v[6:7], off
	v_cmp_lt_i32_e64 s[34:35], s46, v180
	s_nop 1
	v_cndmask_b32_e64 v2, 0, v172, s[34:35]
	v_add3_u32 v2, v180, v2, s81
	v_ashrrev_i32_e32 v2, 6, v2
	v_and_or_b32 v17, v2, -4, v13
	v_cndmask_b32_e64 v2, 0, 64, s[34:35]
	v_or3_b32 v4, v2, s72, v8
	v_cmp_gt_i32_e64 s[36:37], 32, v17
	v_cmp_lt_i32_e64 s[38:39], 31, v17
	v_ashrrev_i32_e32 v5, 31, v4
	v_lshlrev_b32_e32 v2, 2, v17
	s_and_saveexec_b64 s[40:41], s[38:39]
	s_xor_b64 s[38:39], exec, s[40:41]
	v_lshlrev_b64 v[4:5], 7, v[4:5]
	v_lshl_add_u64 v[4:5], s[62:63], 0, v[4:5]
	v_mov_b32_e32 v3, v0
	v_lshl_add_u64 v[2:3], v[2:3], 2, v[4:5]
	v_lshl_add_u64 v[6:7], v[2:3], 0, s[50:51]
	s_andn2_saveexec_b64 s[38:39], s[38:39]
	v_lshlrev_b64 v[4:5], 9, v[4:5]
	v_ashrrev_i32_e32 v3, 31, v2
	v_lshl_add_u64 v[4:5], s[60:61], 0, v[4:5]
	v_lshl_add_u64 v[6:7], v[2:3], 2, v[4:5]
	s_or_b64 exec, exec, s[38:39]
	global_load_dwordx4 v[144:147], v[6:7], off
	v_cmp_lt_i32_e64 s[38:39], s71, v180
	s_nop 1
	v_cndmask_b32_e64 v2, 0, v172, s[38:39]
	v_add3_u32 v2, v180, v2, s95
	v_ashrrev_i32_e32 v2, 6, v2
	v_and_or_b32 v13, v2, -4, v13
	v_cndmask_b32_e64 v2, 0, 64, s[38:39]
	v_or3_b32 v4, v2, s72, v8
	v_cmp_gt_i32_e64 s[40:41], 32, v13
	v_cmp_lt_i32_e64 s[42:43], 31, v13
	v_ashrrev_i32_e32 v5, 31, v4
	v_lshlrev_b32_e32 v2, 2, v13
	s_and_saveexec_b64 s[52:53], s[42:43]
	s_xor_b64 s[42:43], exec, s[52:53]
	v_lshlrev_b64 v[4:5], 7, v[4:5]
	v_lshl_add_u64 v[4:5], s[62:63], 0, v[4:5]
	v_mov_b32_e32 v3, v0
	v_lshl_add_u64 v[2:3], v[2:3], 2, v[4:5]
	v_lshl_add_u64 v[6:7], v[2:3], 0, s[50:51]
	s_andn2_saveexec_b64 s[42:43], s[42:43]
	v_lshlrev_b64 v[4:5], 9, v[4:5]
	v_ashrrev_i32_e32 v3, 31, v2
	v_lshl_add_u64 v[4:5], s[60:61], 0, v[4:5]
	v_lshl_add_u64 v[6:7], v[2:3], 2, v[4:5]
	s_or_b64 exec, exec, s[42:43]
	global_load_dwordx4 v[148:151], v[6:7], off
	v_cndmask_b32_e32 v4, 0, v173, vcc
	v_mul_u32_u24_e32 v5, 0x150, v8
	v_add_u32_e32 v4, 0, v4
	v_lshlrev_b32_e32 v6, 3, v1
	s_waitcnt vmcnt(0) lgkmcnt(0)
	v_cvt_pk_bf16_f32 v2, v112, v113
	v_cvt_pk_bf16_f32 v3, v114, v115
	v_add3_u32 v4, v4, v6, v5
	ds_write_b64 v4, v[2:3] offset:43008
	v_lshlrev_b32_e32 v4, 1, v8
	s_and_saveexec_b64 s[42:43], s[2:3]
	s_cbranch_execz .LBB0_730
	v_cndmask_b32_e32 v6, 0, v174, vcc
	s_add_i32 s2, 0, 0x15000
	v_add_u32_e32 v6, s2, v6
	v_mul_lo_u32 v1, v1, s47
	v_add3_u32 v1, v6, v1, v4
	ds_write_b16 v1, v2
	ds_write_b16_d16_hi v1, v2 offset:136
	ds_write_b16 v1, v3 offset:272
	ds_write_b16_d16_hi v1, v3 offset:408

; #define LAS __attribute__((address_space(3)))
; __device__ __forceinline__ float bflo(unsigned w) { return __uint_as_float(w << 16); }
; __device__ __forceinline__ float bfhi(unsigned w) { return __uint_as_float(w & 0xffff0000u); }
; #define INP(i) ((const float*)tab_get(lds, (i)))
; #define WSB(off) ((bf16*)((unsigned char*)tab_get(lds, 31) + (off)))
; __device__ __forceinline__ void mla_sample_unit(LAS unsigned char* lds, size_t ws_q, size_t ws_olat, size_t ws_mixed, int b) {
;     ...
;     __threadfence(); __syncthreads();
;     { LAS float* OLT = (LAS float*)(lds + KV0);
;       const bf16* OLAT = WSB(ws_olat); const float* w_uv = INP(15); bf16* MIXED = WSB(ws_mixed);
; #pragma unroll
;       for (int i = 0; i < 4; ++i) { const int idx = tid + 512 * i, row = idx >> 4, c8 = idx & 15; const u32x4 v = *(const u32x4*)(OLAT + (size_t)(b * 128 + row) * 128 + 8 * c8);
;           LAS float* d = OLT + ((row >> 4) * 128 + 8 * c8) * 16 + (row & 15);
; #pragma unroll
;           for (int e = 0; e < 4; ++e) { d[(2 * e) * 16] = bflo(v[e]); d[(2 * e + 1) * 16] = bfhi(v[e]); } }
;       __syncthreads();
;       const int d = tid & 63, h = tid >> 6; float acc[16];
; #pragma unroll
;       for (int t = 0; t < 16; ++t) acc[t] = 0.f;
; #pragma unroll 8
;       for (int r = 0; r < 128; ++r) { const float w = w_uv[(size_t)(r * 8 + h) * 64 + d]; const LAS float* ol = OLT + (h * 128 + r) * 16;
; #pragma unroll
;           for (int t4 = 0; t4 < 4; ++t4) { const f32x4 x = *(const LAS f32x4*)(ol + 4 * t4); acc[4 * t4] += x.x * w; acc[4 * t4 + 1] += x.y * w; acc[4 * t4 + 2] += x.z * w; acc[4 * t4 + 3] += x.w * w; } }
.LBB0_930:
	v_mov_b32_e32 v1, s45
	buffer_wbl2 sc1
	s_waitcnt vmcnt(0) lgkmcnt(0)
	buffer_inv sc1
	s_barrier
	ds_read_b64 v[2:3], v1
	v_mov_b32_e32 v5, v0
	v_lshrrev_b32_e32 v11, 1, v176
	v_ashrrev_i32_e32 v12, 4, v178
	v_add_u32_e32 v10, s4, v12
	s_waitcnt lgkmcnt(0)
	v_readfirstlane_b32 s2, v2
	v_mov_b32_e32 v2, s86
	v_readfirstlane_b32 s3, v3
	ds_read_b64 v[16:17], v2
	ds_read_b64 v[2:3], v1
	v_lshlrev_b32_e32 v1, 3, v179
	v_and_b32_e32 v21, 0x78, v1
	v_lshlrev_b32_e32 v4, 1, v21
	v_lshl_add_u64 v[4:5], s[2:3], 0, v[4:5]
	s_mov_b64 s[2:3], 0x12080000
	v_ashrrev_i32_e32 v1, 4, v176
	v_lshl_add_u64 v[8:9], v[4:5], 0, s[2:3]
	v_add_u32_e32 v4, s4, v1
	v_ashrrev_i32_e32 v5, 31, v4
	v_lshlrev_b64 v[4:5], 8, v[4:5]
	v_lshl_add_u64 v[4:5], v[8:9], 0, v[4:5]
	global_load_dwordx4 v[4:7], v[4:5], off
	v_lshlrev_b32_e32 v1, 2, v1
	v_and_or_b32 v13, v11, s56, v21
	v_and_b32_e32 v1, 60, v1
	v_lshlrev_b32_e32 v13, 6, v13
	v_ashrrev_i32_e32 v11, 31, v10
	v_add3_u32 v1, 0, v13, v1
	v_lshlrev_b64 v[10:11], 8, v[10:11]
	v_add_u32_e32 v1, 0xa800, v1
	v_lshl_add_u64 v[10:11], v[8:9], 0, v[10:11]
	v_lshrrev_b32_e32 v28, 1, v155
	s_waitcnt lgkmcnt(0)
	v_readfirstlane_b32 s5, v17
	s_mov_b64 s[2:3], 0
	s_waitcnt vmcnt(0)
	v_lshlrev_b32_e32 v13, 16, v4
	v_and_b32_e32 v4, 0xffff0000, v4
	v_lshlrev_b32_e32 v14, 16, v5
	v_and_b32_e32 v5, 0xffff0000, v5
	v_lshlrev_b32_e32 v15, 16, v6
	v_and_b32_e32 v6, 0xffff0000, v6
	v_lshlrev_b32_e32 v18, 16, v7
	v_and_b32_e32 v7, 0xffff0000, v7
	ds_write2_b32 v1, v13, v4 offset1:16
	ds_write2_b32 v1, v14, v5 offset0:32 offset1:48
	ds_write2_b32 v1, v15, v6 offset0:64 offset1:80
	ds_write2_b32 v1, v18, v7 offset0:96 offset1:112
	global_load_dwordx4 v[4:7], v[10:11], off
	v_lshrrev_b32_e32 v1, 1, v178
	v_ashrrev_i32_e32 v13, 4, v177
	v_lshlrev_b32_e32 v11, 2, v12
	v_and_or_b32 v1, v1, s56, v21
	v_add_u32_e32 v10, s4, v13
	v_and_b32_e32 v12, 60, v11
	v_lshlrev_b32_e32 v1, 6, v1
	v_ashrrev_i32_e32 v11, 31, v10
	v_add3_u32 v1, 0, v1, v12
	v_lshlrev_b64 v[10:11], 8, v[10:11]
	v_add_u32_e32 v1, 0xa800, v1
	v_lshl_add_u64 v[10:11], v[8:9], 0, v[10:11]
	s_waitcnt vmcnt(0) lgkmcnt(0)
	v_lshlrev_b32_e32 v12, 16, v4
	v_and_b32_e32 v4, 0xffff0000, v4
	v_lshlrev_b32_e32 v14, 16, v5
	v_and_b32_e32 v5, 0xffff0000, v5
	v_lshlrev_b32_e32 v15, 16, v6
	v_and_b32_e32 v6, 0xffff0000, v6
	v_lshlrev_b32_e32 v18, 16, v7
	v_and_b32_e32 v7, 0xffff0000, v7
	ds_write2_b32 v1, v12, v4 offset1:16
	ds_write2_b32 v1, v14, v5 offset0:32 offset1:48
	ds_write2_b32 v1, v15, v6 offset0:64 offset1:80
	ds_write2_b32 v1, v18, v7 offset0:96 offset1:112
	global_load_dwordx4 v[4:7], v[10:11], off
	v_lshrrev_b32_e32 v1, 1, v177
	v_ashrrev_i32_e32 v12, 4, v155
	v_lshlrev_b32_e32 v11, 2, v13
	v_add_u32_e32 v10, s4, v12
	v_and_or_b32 v1, v1, s56, v21
	v_and_b32_e32 v13, 60, v11
	v_ashrrev_i32_e32 v11, 31, v10
	v_lshlrev_b32_e32 v1, 6, v1
	v_lshlrev_b64 v[10:11], 8, v[10:11]
	v_add3_u32 v1, 0, v1, v13
	v_add_u32_e32 v1, 0xa800, v1
	v_lshl_add_u64 v[8:9], v[8:9], 0, v[10:11]
	v_ashrrev_i32_e32 v155, 31, v154
	v_lshlrev_b32_e32 v29, 2, v12
	v_and_or_b32 v21, v28, s56, v21
	s_add_i32 s4, 0, 0xa800
	v_lshlrev_b64 v[26:27], 8, v[154:155]
	v_and_b32_e32 v28, 60, v29
	v_lshlrev_b32_e32 v21, 6, v21
	v_lshl_or_b32 v26, v156, 2, v26
	v_add3_u32 v21, 0, v21, v28
	v_add_u32_e32 v21, 0xa800, v21
	s_waitcnt vmcnt(0) lgkmcnt(0)
	v_lshlrev_b32_e32 v10, 16, v4
	v_and_b32_e32 v4, 0xffff0000, v4
	v_lshlrev_b32_e32 v11, 16, v5
	v_and_b32_e32 v5, 0xffff0000, v5
	v_lshlrev_b32_e32 v13, 16, v6
	v_and_b32_e32 v6, 0xffff0000, v6
	v_lshlrev_b32_e32 v14, 16, v7
	v_and_b32_e32 v7, 0xffff0000, v7
	ds_write2_b32 v1, v10, v4 offset1:16
	ds_write2_b32 v1, v11, v5 offset0:32 offset1:48
	ds_write2_b32 v1, v13, v6 offset0:64 offset1:80
	ds_write2_b32 v1, v14, v7 offset0:96 offset1:112
	global_load_dwordx4 v[22:25], v[8:9], off
	v_lshl_add_u32 v1, v154, 13, s4
	v_readfirstlane_b32 s4, v16
	v_mov_b32_e32 v4, 0
	v_mov_b32_e32 v5, v4
	v_lshl_add_u64 v[16:17], s[4:5], 0, v[26:27]
	v_mov_b32_e32 v6, v4
	v_mov_b32_e32 v7, v4
	v_mov_b32_e32 v8, v4
	v_mov_b32_e32 v9, v4
	v_mov_b32_e32 v10, v4
	v_mov_b32_e32 v11, v4
	v_mov_b32_e32 v12, v4
	v_mov_b32_e32 v13, v4
	v_mov_b32_e32 v14, v4
	v_mov_b32_e32 v15, v4
	v_mov_b32_e32 v18, v4
	v_mov_b32_e32 v19, v4
	v_mov_b32_e32 v20, v4
	s_waitcnt vmcnt(0) lgkmcnt(0)
	v_lshlrev_b32_e32 v26, 16, v22
	v_and_b32_e32 v22, 0xffff0000, v22
	v_lshlrev_b32_e32 v27, 16, v23
	v_and_b32_e32 v23, 0xffff0000, v23
	v_lshlrev_b32_e32 v28, 16, v24
	v_and_b32_e32 v24, 0xffff0000, v24
	v_lshlrev_b32_e32 v29, 16, v25
	v_and_b32_e32 v25, 0xffff0000, v25
	ds_write2_b32 v21, v26, v22 offset1:16
	ds_write2_b32 v21, v27, v23 offset0:32 offset1:48
	ds_write2_b32 v21, v28, v24 offset0:64 offset1:80
	ds_write2_b32 v21, v29, v25 offset0:96 offset1:112
	v_mov_b32_e32 v21, v4
	s_waitcnt lgkmcnt(0)
	s_barrier
	s_add_u32 s4, s2, 0x1000
	s_addc_u32 s5, s3, 0
	v_lshl_add_u64 v[186:187], v[16:17], 0, s[4:5]
	s_add_u32 s4, s2, 0x3000
	s_addc_u32 s5, s3, 0
	v_lshl_add_u64 v[188:189], v[16:17], 0, s[4:5]
	global_load_dword v150, v[186:187], off offset:-4096
	global_load_dword v154, v[186:187], off offset:-2048
	global_load_dword v158, v[186:187], off
	global_load_dword v160, v[186:187], off offset:2048
	global_load_dword v178, v[188:189], off offset:-4096
	global_load_dword v180, v[188:189], off offset:-2048
	global_load_dword v182, v[188:189], off
	global_load_dword v184, v[188:189], off offset:2048
; #define LAS __attribute__((address_space(3)))
; __device__ __forceinline__ void mla_sample_unit(LAS unsigned char* lds, size_t ws_q, size_t ws_olat, size_t ws_mixed, int b) {
;     ...
; #pragma unroll 8
;       for (int r = 0; r < 128; ++r) { const float w = w_uv[(size_t)(r * 8 + h) * 64 + d]; const LAS float* ol = OLT + (h * 128 + r) * 16;
; #pragma unroll
;           for (int t4 = 0; t4 < 4; ++t4) { const f32x4 x = *(const LAS f32x4*)(ol + 4 * t4); acc[4 * t4] += x.x * w; acc[4 * t4 + 1] += x.y * w; acc[4 * t4 + 2] += x.z * w; acc[4 * t4 + 3] += x.w * w; } }
.LBB0_931:
	ds_read_b128 v[22:25], v1
	ds_read_b128 v[26:29], v1 offset:16
	ds_read_b128 v[30:33], v1 offset:32
	ds_read_b128 v[34:37], v1 offset:48
	ds_read_b128 v[38:41], v1 offset:64
	ds_read_b128 v[42:45], v1 offset:80
	ds_read_b128 v[46:49], v1 offset:96
	ds_read_b128 v[50:53], v1 offset:112
	ds_read_b128 v[54:57], v1 offset:128
	ds_read_b128 v[58:61], v1 offset:144
	ds_read_b128 v[62:65], v1 offset:160
	ds_read_b128 v[66:69], v1 offset:176
	ds_read_b128 v[70:73], v1 offset:192
	ds_read_b128 v[74:77], v1 offset:208
	ds_read_b128 v[78:81], v1 offset:224
	ds_read_b128 v[82:85], v1 offset:240
	ds_read_b128 v[86:89], v1 offset:256
	ds_read_b128 v[90:93], v1 offset:272
	ds_read_b128 v[94:97], v1 offset:288
	ds_read_b128 v[98:101], v1 offset:304
	ds_read_b128 v[102:105], v1 offset:320
	ds_read_b128 v[106:109], v1 offset:336
	ds_read_b128 v[110:113], v1 offset:352
	ds_read_b128 v[114:117], v1 offset:368
	ds_read_b128 v[118:121], v1 offset:384
	ds_read_b128 v[122:125], v1 offset:400
	ds_read_b128 v[126:129], v1 offset:416
	ds_read_b128 v[130:133], v1 offset:432
	ds_read_b128 v[134:137], v1 offset:448
	ds_read_b128 v[138:141], v1 offset:464
	ds_read_b128 v[142:145], v1 offset:480
	ds_read_b128 v[146:149], v1 offset:496
	v_add_u32_e32 v1, 0x200, v1
	s_add_u32 s2, s2, 0x4000
	s_addc_u32 s3, s3, 0
	s_waitcnt vmcnt(0)
	v_mov_b32_e32 v190, v150
	v_mov_b32_e32 v192, v154
	v_mov_b32_e32 v194, v158
	v_mov_b32_e32 v196, v160
	v_mov_b32_e32 v198, v178
	v_mov_b32_e32 v200, v180
	v_mov_b32_e32 v202, v182
	v_mov_b32_e32 v204, v184
	s_cmp_eq_u32 s2, 0x40000
	s_cbranch_scc1 .Lps_noload
	s_add_u32 s4, s2, 0x1000
	s_addc_u32 s5, s3, 0
	v_lshl_add_u64 v[186:187], v[16:17], 0, s[4:5]
	s_add_u32 s4, s2, 0x3000
	s_addc_u32 s5, s3, 0
	v_lshl_add_u64 v[188:189], v[16:17], 0, s[4:5]
	global_load_dword v150, v[186:187], off offset:-4096
	global_load_dword v154, v[186:187], off offset:-2048
	global_load_dword v158, v[186:187], off
	global_load_dword v160, v[186:187], off offset:2048
	global_load_dword v178, v[188:189], off offset:-4096
	global_load_dword v180, v[188:189], off offset:-2048
	global_load_dword v182, v[188:189], off
	global_load_dword v184, v[188:189], off offset:2048
.Lps_noload:
	s_waitcnt lgkmcnt(0)
	v_pk_fma_f32 v[20:21], v[190:191], v[22:23], v[20:21] op_sel_hi:[0,1,1]
	v_pk_fma_f32 v[18:19], v[190:191], v[24:25], v[18:19] op_sel_hi:[0,1,1]
	v_pk_fma_f32 v[14:15], v[190:191], v[26:27], v[14:15] op_sel_hi:[0,1,1]
	v_pk_fma_f32 v[12:13], v[190:191], v[28:29], v[12:13] op_sel_hi:[0,1,1]
	v_pk_fma_f32 v[10:11], v[190:191], v[30:31], v[10:11] op_sel_hi:[0,1,1]
	v_pk_fma_f32 v[8:9], v[190:191], v[32:33], v[8:9] op_sel_hi:[0,1,1]
	v_pk_fma_f32 v[6:7], v[190:191], v[34:35], v[6:7] op_sel_hi:[0,1,1]
	v_pk_fma_f32 v[4:5], v[190:191], v[36:37], v[4:5] op_sel_hi:[0,1,1]
	v_pk_fma_f32 v[20:21], v[192:193], v[38:39], v[20:21] op_sel_hi:[0,1,1]
	v_pk_fma_f32 v[18:19], v[192:193], v[40:41], v[18:19] op_sel_hi:[0,1,1]
	v_pk_fma_f32 v[14:15], v[192:193], v[42:43], v[14:15] op_sel_hi:[0,1,1]
	v_pk_fma_f32 v[12:13], v[192:193], v[44:45], v[12:13] op_sel_hi:[0,1,1]
	v_pk_fma_f32 v[10:11], v[192:193], v[46:47], v[10:11] op_sel_hi:[0,1,1]
	v_pk_fma_f32 v[8:9], v[192:193], v[48:49], v[8:9] op_sel_hi:[0,1,1]
	v_pk_fma_f32 v[6:7], v[192:193], v[50:51], v[6:7] op_sel_hi:[0,1,1]
	v_pk_fma_f32 v[4:5], v[192:193], v[52:53], v[4:5] op_sel_hi:[0,1,1]
	v_pk_fma_f32 v[20:21], v[194:195], v[54:55], v[20:21] op_sel_hi:[0,1,1]
	v_pk_fma_f32 v[18:19], v[194:195], v[56:57], v[18:19] op_sel_hi:[0,1,1]
	v_pk_fma_f32 v[14:15], v[194:195], v[58:59], v[14:15] op_sel_hi:[0,1,1]
	v_pk_fma_f32 v[12:13], v[194:195], v[60:61], v[12:13] op_sel_hi:[0,1,1]
	v_pk_fma_f32 v[10:11], v[194:195], v[62:63], v[10:11] op_sel_hi:[0,1,1]
	v_pk_fma_f32 v[8:9], v[194:195], v[64:65], v[8:9] op_sel_hi:[0,1,1]
	v_pk_fma_f32 v[6:7], v[194:195], v[66:67], v[6:7] op_sel_hi:[0,1,1]
	v_pk_fma_f32 v[4:5], v[194:195], v[68:69], v[4:5] op_sel_hi:[0,1,1]
	v_pk_fma_f32 v[20:21], v[196:197], v[70:71], v[20:21] op_sel_hi:[0,1,1]
	v_pk_fma_f32 v[18:19], v[196:197], v[72:73], v[18:19] op_sel_hi:[0,1,1]
	v_pk_fma_f32 v[14:15], v[196:197], v[74:75], v[14:15] op_sel_hi:[0,1,1]
	v_pk_fma_f32 v[12:13], v[196:197], v[76:77], v[12:13] op_sel_hi:[0,1,1]
	v_pk_fma_f32 v[10:11], v[196:197], v[78:79], v[10:11] op_sel_hi:[0,1,1]
	v_pk_fma_f32 v[8:9], v[196:197], v[80:81], v[8:9] op_sel_hi:[0,1,1]
	v_pk_fma_f32 v[6:7], v[196:197], v[82:83], v[6:7] op_sel_hi:[0,1,1]
	v_pk_fma_f32 v[4:5], v[196:197], v[84:85], v[4:5] op_sel_hi:[0,1,1]
	v_pk_fma_f32 v[20:21], v[198:199], v[86:87], v[20:21] op_sel_hi:[0,1,1]
	v_pk_fma_f32 v[18:19], v[198:199], v[88:89], v[18:19] op_sel_hi:[0,1,1]
	v_pk_fma_f32 v[14:15], v[198:199], v[90:91], v[14:15] op_sel_hi:[0,1,1]
	v_pk_fma_f32 v[12:13], v[198:199], v[92:93], v[12:13] op_sel_hi:[0,1,1]
	v_pk_fma_f32 v[10:11], v[198:199], v[94:95], v[10:11] op_sel_hi:[0,1,1]
	v_pk_fma_f32 v[8:9], v[198:199], v[96:97], v[8:9] op_sel_hi:[0,1,1]
	v_pk_fma_f32 v[6:7], v[198:199], v[98:99], v[6:7] op_sel_hi:[0,1,1]
	v_pk_fma_f32 v[4:5], v[198:199], v[100:101], v[4:5] op_sel_hi:[0,1,1]
	v_pk_fma_f32 v[20:21], v[200:201], v[102:103], v[20:21] op_sel_hi:[0,1,1]
	v_pk_fma_f32 v[18:19], v[200:201], v[104:105], v[18:19] op_sel_hi:[0,1,1]
	v_pk_fma_f32 v[14:15], v[200:201], v[106:107], v[14:15] op_sel_hi:[0,1,1]
	v_pk_fma_f32 v[12:13], v[200:201], v[108:109], v[12:13] op_sel_hi:[0,1,1]
	v_pk_fma_f32 v[10:11], v[200:201], v[110:111], v[10:11] op_sel_hi:[0,1,1]
	v_pk_fma_f32 v[8:9], v[200:201], v[112:113], v[8:9] op_sel_hi:[0,1,1]
	v_pk_fma_f32 v[6:7], v[200:201], v[114:115], v[6:7] op_sel_hi:[0,1,1]
	v_pk_fma_f32 v[4:5], v[200:201], v[116:117], v[4:5] op_sel_hi:[0,1,1]
	v_pk_fma_f32 v[20:21], v[202:203], v[118:119], v[20:21] op_sel_hi:[0,1,1]
	v_pk_fma_f32 v[18:19], v[202:203], v[120:121], v[18:19] op_sel_hi:[0,1,1]
	v_pk_fma_f32 v[14:15], v[202:203], v[122:123], v[14:15] op_sel_hi:[0,1,1]
	v_pk_fma_f32 v[12:13], v[202:203], v[124:125], v[12:13] op_sel_hi:[0,1,1]
	v_pk_fma_f32 v[10:11], v[202:203], v[126:127], v[10:11] op_sel_hi:[0,1,1]
	v_pk_fma_f32 v[8:9], v[202:203], v[128:129], v[8:9] op_sel_hi:[0,1,1]
	v_pk_fma_f32 v[6:7], v[202:203], v[130:131], v[6:7] op_sel_hi:[0,1,1]
	v_pk_fma_f32 v[4:5], v[202:203], v[132:133], v[4:5] op_sel_hi:[0,1,1]
	v_pk_fma_f32 v[20:21], v[204:205], v[134:135], v[20:21] op_sel_hi:[0,1,1]
	v_pk_fma_f32 v[18:19], v[204:205], v[136:137], v[18:19] op_sel_hi:[0,1,1]
	v_pk_fma_f32 v[14:15], v[204:205], v[138:139], v[14:15] op_sel_hi:[0,1,1]
	v_pk_fma_f32 v[12:13], v[204:205], v[140:141], v[12:13] op_sel_hi:[0,1,1]
	v_pk_fma_f32 v[10:11], v[204:205], v[142:143], v[10:11] op_sel_hi:[0,1,1]
	v_pk_fma_f32 v[8:9], v[204:205], v[144:145], v[8:9] op_sel_hi:[0,1,1]
	v_pk_fma_f32 v[6:7], v[204:205], v[146:147], v[6:7] op_sel_hi:[0,1,1]
	v_pk_fma_f32 v[4:5], v[204:205], v[148:149], v[4:5] op_sel_hi:[0,1,1]
	s_cmp_lg_u32 s2, 0x40000
	s_cbranch_scc1 .LBB0_931
; __device__ __forceinline__ bf16 f2bf(float f) { return (bf16)(pk2(f, 0.f) & 0xffffu); }
; __device__ __forceinline__ void mla_sample_unit(LAS unsigned char* lds, size_t ws_q, size_t ws_olat, size_t ws_mixed, int b) {
;     ...
; #pragma unroll
;       for (int t = 0; t < 16; ++t) MIXED[(size_t)(rowbase + t) * 1024 + h * 64 + d] = f2bf(acc[t]); }
;     __syncthreads();
	v_readfirstlane_b32 s2, v3
	v_readfirstlane_b32 s3, v2
	v_and_b32_e32 v16, 0xffffffc0, v176
	v_mov_b32_e32 v3, s2
	v_mov_b32_e32 v2, s3
	v_ashrrev_i32_e32 v17, 31, v16
	v_lshl_add_u64 v[2:3], v[16:17], 1, v[2:3]
	v_lshlrev_b32_e32 v16, 1, v156
	v_mov_b32_e32 v17, v0
	v_lshl_add_u64 v[2:3], v[2:3], 0, v[16:17]
	s_mov_b64 s[2:3], 0x2600000
	s_ashr_i32 s59, s58, 31
	v_lshl_add_u64 v[2:3], v[2:3], 0, s[2:3]
	s_lshl_b64 s[2:3], s[58:59], 11
	v_lshl_add_u64 v[16:17], v[2:3], 0, s[2:3]
	s_or_b32 s2, s58, 1
	s_ashr_i32 s3, s2, 31
	v_cvt_pk_bf16_f32 v1, v20, s0
	s_lshl_b64 s[2:3], s[2:3], 11
	global_store_short v[16:17], v1, off
	v_lshl_add_u64 v[16:17], v[2:3], 0, s[2:3]
	s_or_b32 s2, s58, 2
	s_ashr_i32 s3, s2, 31
	v_cvt_pk_bf16_f32 v1, v21, s0
	s_lshl_b64 s[2:3], s[2:3], 11
	global_store_short v[16:17], v1, off
	v_lshl_add_u64 v[16:17], v[2:3], 0, s[2:3]
	s_or_b32 s2, s58, 3
	s_ashr_i32 s3, s2, 31
	v_cvt_pk_bf16_f32 v1, v18, s0
	s_lshl_b64 s[2:3], s[2:3], 11
	global_store_short v[16:17], v1, off
	v_lshl_add_u64 v[16:17], v[2:3], 0, s[2:3]
	s_or_b32 s2, s58, 4
	s_ashr_i32 s3, s2, 31
	v_cvt_pk_bf16_f32 v1, v19, s0
	s_lshl_b64 s[2:3], s[2:3], 11
	global_store_short v[16:17], v1, off
	v_lshl_add_u64 v[16:17], v[2:3], 0, s[2:3]
	s_or_b32 s2, s58, 5
	s_ashr_i32 s3, s2, 31
	v_cvt_pk_bf16_f32 v1, v14, s0
	s_lshl_b64 s[2:3], s[2:3], 11
	global_store_short v[16:17], v1, off
	v_cvt_pk_bf16_f32 v1, v15, s0
	v_lshl_add_u64 v[14:15], v[2:3], 0, s[2:3]
	s_or_b32 s2, s58, 6
	s_ashr_i32 s3, s2, 31
	s_lshl_b64 s[2:3], s[2:3], 11
	global_store_short v[14:15], v1, off
	v_lshl_add_u64 v[14:15], v[2:3], 0, s[2:3]
	s_or_b32 s2, s58, 7
	s_ashr_i32 s3, s2, 31
	v_cvt_pk_bf16_f32 v1, v12, s0
	s_lshl_b64 s[2:3], s[2:3], 11
	global_store_short v[14:15], v1, off
	v_cvt_pk_bf16_f32 v1, v13, s0
	v_lshl_add_u64 v[12:13], v[2:3], 0, s[2:3]
	s_or_b32 s2, s58, 8
	s_ashr_i32 s3, s2, 31
	s_lshl_b64 s[2:3], s[2:3], 11
	global_store_short v[12:13], v1, off
	v_lshl_add_u64 v[12:13], v[2:3], 0, s[2:3]
	s_or_b32 s2, s58, 9
	s_ashr_i32 s3, s2, 31
	v_cvt_pk_bf16_f32 v1, v10, s0
	s_lshl_b64 s[2:3], s[2:3], 11
	global_store_short v[12:13], v1, off
	v_cvt_pk_bf16_f32 v1, v11, s0
	v_lshl_add_u64 v[10:11], v[2:3], 0, s[2:3]
	s_or_b32 s2, s58, 10
	s_ashr_i32 s3, s2, 31
	s_lshl_b64 s[2:3], s[2:3], 11
	global_store_short v[10:11], v1, off
	v_lshl_add_u64 v[10:11], v[2:3], 0, s[2:3]
	s_or_b32 s2, s58, 11
	s_ashr_i32 s3, s2, 31
	v_cvt_pk_bf16_f32 v1, v8, s0
	s_lshl_b64 s[2:3], s[2:3], 11
	global_store_short v[10:11], v1, off
	v_cvt_pk_bf16_f32 v1, v9, s0
	v_lshl_add_u64 v[8:9], v[2:3], 0, s[2:3]
	s_or_b32 s2, s58, 12
	s_ashr_i32 s3, s2, 31
	s_lshl_b64 s[2:3], s[2:3], 11
	global_store_short v[8:9], v1, off
	v_lshl_add_u64 v[8:9], v[2:3], 0, s[2:3]
	s_or_b32 s2, s58, 13
	s_ashr_i32 s3, s2, 31
	v_cvt_pk_bf16_f32 v1, v6, s0
	s_lshl_b64 s[2:3], s[2:3], 11
	global_store_short v[8:9], v1, off
	v_cvt_pk_bf16_f32 v1, v7, s0
	v_lshl_add_u64 v[6:7], v[2:3], 0, s[2:3]
	s_or_b32 s2, s58, 14
	s_ashr_i32 s3, s2, 31
	s_lshl_b64 s[2:3], s[2:3], 11
	global_store_short v[6:7], v1, off
	v_lshl_add_u64 v[6:7], v[2:3], 0, s[2:3]
	s_or_b32 s2, s58, 15
	s_ashr_i32 s3, s2, 31
	v_cvt_pk_bf16_f32 v1, v4, s0
	s_lshl_b64 s[2:3], s[2:3], 11
	global_store_short v[6:7], v1, off
	v_cvt_pk_bf16_f32 v1, v5, s0
	v_lshl_add_u64 v[2:3], v[2:3], 0, s[2:3]
	global_store_short v[2:3], v1, off
	s_waitcnt lgkmcnt(0)
	s_barrier
	s_branch .LBB0_622

;     __device__ __forceinline__ void operator()(EPI_ARGS) const {
;         const int row0 = u.pm * BM + wr * 64 + fr, col0 = u.pn * BM + wc * 32 + 8 * fq;
; #pragma unroll
;         for (int ai = 0; ai < 2; ++ai)
; #pragma unroll
;             for (int m = 0; m < 4; ++m) { const int row = row0 + ai * HALF + m * 16;
;                 const float* b = base + (size_t)row * DM + col0; float* o = X + (size_t)row * DM + col0;
; #pragma unroll
;                 for (int bj = 0; bj < 2; ++bj) { const f32x4 b0 = *(const f32x4*)(b + bj * HALF), b1 = *(const f32x4*)(b + bj * HALF + 4);
;                     *(f32x4*)(o + bj * HALF) = b0 + acc[ai][bj][m][0]; *(f32x4*)(o + bj * HALF + 4) = b1 + acc[ai][bj][m][1]; } }
;     }
.LBB0_997:
	v_lshl_add_u32 v162, s30, 8, v148
	v_lshl_or_b32 v144, s60, 8, v150
	v_ashrrev_i32_e32 v163, 31, v162
	v_ashrrev_i32_e32 v145, 31, v144
	v_lshlrev_b64 v[146:147], 12, v[162:163]
	v_lshl_add_u64 v[154:155], s[4:5], 0, v[146:147]
	v_lshlrev_b64 v[144:145], 2, v[144:145]
	v_lshl_add_u64 v[164:165], v[154:155], 0, v[144:145]
	v_lshl_add_u64 v[166:167], s[6:7], 0, v[146:147]
	v_lshl_add_u64 v[166:167], v[166:167], 0, v[144:145]
	s_mov_b64 s[98:99], 0x10000
	s_mov_b64 s[100:101], 0x50000
	global_load_dwordx4 v[144:147], v[164:165], off
	global_load_dwordx4 v[154:157], v[164:165], off offset:16
	global_load_dwordx4 v[158:161], v[164:165], off offset:512
	global_load_dwordx4 v[170:173], v[164:165], off offset:528
	v_lshl_add_u64 v[164:165], v[164:165], 0, s[98:99]
	global_load_dwordx4 v[174:177], v[164:165], off
	global_load_dwordx4 v[178:181], v[164:165], off offset:16
	global_load_dwordx4 v[182:185], v[164:165], off offset:512
	global_load_dwordx4 v[186:189], v[164:165], off offset:528
	v_lshl_add_u64 v[164:165], v[164:165], 0, s[98:99]
	global_load_dwordx4 v[190:193], v[164:165], off
	global_load_dwordx4 v[194:197], v[164:165], off offset:16
	global_load_dwordx4 v[198:201], v[164:165], off offset:512
	global_load_dwordx4 v[202:205], v[164:165], off offset:528
	s_waitcnt vmcnt(10)
	v_pk_add_f32 v[124:125], v[124:125], v[144:145]
	v_pk_add_f32 v[126:127], v[126:127], v[146:147]
	v_pk_add_f32 v[120:121], v[120:121], v[154:155]
	v_pk_add_f32 v[122:123], v[122:123], v[156:157]
	global_store_dwordx4 v[166:167], v[124:127], off
	global_store_dwordx4 v[166:167], v[120:123], off offset:16
	v_lshl_add_u64 v[164:165], v[164:165], 0, s[98:99]
	global_load_dwordx4 v[144:147], v[164:165], off
	global_load_dwordx4 v[154:157], v[164:165], off offset:16
	s_waitcnt vmcnt(12)
	v_pk_add_f32 v[112:113], v[112:113], v[158:159]
	v_pk_add_f32 v[114:115], v[114:115], v[160:161]
	v_pk_add_f32 v[108:109], v[108:109], v[170:171]
	v_pk_add_f32 v[110:111], v[110:111], v[172:173]
	global_store_dwordx4 v[166:167], v[112:115], off offset:512
	global_store_dwordx4 v[166:167], v[108:111], off offset:528
	global_load_dwordx4 v[158:161], v[164:165], off offset:512
	global_load_dwordx4 v[170:173], v[164:165], off offset:528
	s_waitcnt vmcnt(14)
	v_pk_add_f32 v[116:117], v[116:117], v[174:175]
	v_pk_add_f32 v[118:119], v[118:119], v[176:177]
	v_pk_add_f32 v[104:105], v[104:105], v[178:179]
	v_pk_add_f32 v[106:107], v[106:107], v[180:181]
	v_lshl_add_u64 v[166:167], v[166:167], 0, s[98:99]
	global_store_dwordx4 v[166:167], v[116:119], off
	global_store_dwordx4 v[166:167], v[104:107], off offset:16
	v_lshl_add_u64 v[164:165], v[164:165], 0, s[100:101]
	global_load_dwordx4 v[174:177], v[164:165], off
	global_load_dwordx4 v[178:181], v[164:165], off offset:16
	s_waitcnt vmcnt(16)
	v_pk_add_f32 v[96:97], v[96:97], v[182:183]
	v_pk_add_f32 v[98:99], v[98:99], v[184:185]
	v_pk_add_f32 v[92:93], v[92:93], v[186:187]
	v_pk_add_f32 v[94:95], v[94:95], v[188:189]
	global_store_dwordx4 v[166:167], v[96:99], off offset:512
	global_store_dwordx4 v[166:167], v[92:95], off offset:528
	global_load_dwordx4 v[182:185], v[164:165], off offset:512
	global_load_dwordx4 v[186:189], v[164:165], off offset:528
	s_waitcnt vmcnt(18)
	v_pk_add_f32 v[100:101], v[100:101], v[190:191]
	v_pk_add_f32 v[102:103], v[102:103], v[192:193]
	v_pk_add_f32 v[88:89], v[88:89], v[194:195]
	v_pk_add_f32 v[90:91], v[90:91], v[196:197]
	v_lshl_add_u64 v[166:167], v[166:167], 0, s[98:99]
	global_store_dwordx4 v[166:167], v[100:103], off
	global_store_dwordx4 v[166:167], v[88:91], off offset:16
	v_lshl_add_u64 v[164:165], v[164:165], 0, s[98:99]
	global_load_dwordx4 v[190:193], v[164:165], off
	global_load_dwordx4 v[194:197], v[164:165], off offset:16
	s_waitcnt vmcnt(20)
	v_pk_add_f32 v[80:81], v[80:81], v[198:199]
	v_pk_add_f32 v[82:83], v[82:83], v[200:201]
	v_pk_add_f32 v[76:77], v[76:77], v[202:203]
	v_pk_add_f32 v[78:79], v[78:79], v[204:205]
	global_store_dwordx4 v[166:167], v[80:83], off offset:512
	global_store_dwordx4 v[166:167], v[76:79], off offset:528
	global_load_dwordx4 v[198:201], v[164:165], off offset:512
	global_load_dwordx4 v[202:205], v[164:165], off offset:528
	s_waitcnt vmcnt(20)
;     __device__ __forceinline__ void operator()(EPI_ARGS) const {
;         const int row0 = u.pm * BM + wr * 64 + fr, col0 = u.pn * BM + wc * 32 + 8 * fq;
; #pragma unroll
;         for (int ai = 0; ai < 2; ++ai)
; #pragma unroll
;             for (int m = 0; m < 4; ++m) { const int row = row0 + ai * HALF + m * 16;
;                 const float* b = base + (size_t)row * DM + col0; float* o = X + (size_t)row * DM + col0;
; #pragma unroll
;                 for (int bj = 0; bj < 2; ++bj) { const f32x4 b0 = *(const f32x4*)(b + bj * HALF), b1 = *(const f32x4*)(b + bj * HALF + 4);
;                     *(f32x4*)(o + bj * HALF) = b0 + acc[ai][bj][m][0]; *(f32x4*)(o + bj * HALF + 4) = b1 + acc[ai][bj][m][1]; } }
;     }
	v_pk_add_f32 v[84:85], v[84:85], v[144:145]
	v_pk_add_f32 v[86:87], v[86:87], v[146:147]
	v_pk_add_f32 v[72:73], v[72:73], v[154:155]
	v_pk_add_f32 v[74:75], v[74:75], v[156:157]
	v_lshl_add_u64 v[166:167], v[166:167], 0, s[98:99]
	global_store_dwordx4 v[166:167], v[84:87], off
	global_store_dwordx4 v[166:167], v[72:75], off offset:16
	v_lshl_add_u64 v[164:165], v[164:165], 0, s[98:99]
	global_load_dwordx4 v[144:147], v[164:165], off
	global_load_dwordx4 v[154:157], v[164:165], off offset:16
	s_waitcnt vmcnt(20)
	v_pk_add_f32 v[68:69], v[68:69], v[158:159]
	v_pk_add_f32 v[70:71], v[70:71], v[160:161]
	v_pk_add_f32 v[64:65], v[64:65], v[170:171]
	v_pk_add_f32 v[66:67], v[66:67], v[172:173]
	global_store_dwordx4 v[166:167], v[68:71], off offset:512
	global_store_dwordx4 v[166:167], v[64:67], off offset:528
	global_load_dwordx4 v[158:161], v[164:165], off offset:512
	global_load_dwordx4 v[170:173], v[164:165], off offset:528
	s_waitcnt vmcnt(20)
	v_pk_add_f32 v[60:61], v[60:61], v[174:175]
	v_pk_add_f32 v[62:63], v[62:63], v[176:177]
	v_pk_add_f32 v[56:57], v[56:57], v[178:179]
	v_pk_add_f32 v[58:59], v[58:59], v[180:181]
	v_lshl_add_u64 v[166:167], v[166:167], 0, s[100:101]
	global_store_dwordx4 v[166:167], v[60:63], off
	global_store_dwordx4 v[166:167], v[56:59], off offset:16
	v_lshl_add_u64 v[164:165], v[164:165], 0, s[98:99]
	global_load_dwordx4 v[174:177], v[164:165], off
	global_load_dwordx4 v[178:181], v[164:165], off offset:16
	s_waitcnt vmcnt(20)
	v_pk_add_f32 v[48:49], v[48:49], v[182:183]
	v_pk_add_f32 v[50:51], v[50:51], v[184:185]
	v_pk_add_f32 v[44:45], v[44:45], v[186:187]
	v_pk_add_f32 v[46:47], v[46:47], v[188:189]
	global_store_dwordx4 v[166:167], v[48:51], off offset:512
	global_store_dwordx4 v[166:167], v[44:47], off offset:528
	global_load_dwordx4 v[182:185], v[164:165], off offset:512
	global_load_dwordx4 v[186:189], v[164:165], off offset:528
	s_waitcnt vmcnt(20)
	v_pk_add_f32 v[52:53], v[52:53], v[190:191]
	v_pk_add_f32 v[54:55], v[54:55], v[192:193]
	v_pk_add_f32 v[40:41], v[40:41], v[194:195]
	v_pk_add_f32 v[42:43], v[42:43], v[196:197]
	v_lshl_add_u64 v[166:167], v[166:167], 0, s[98:99]
	global_store_dwordx4 v[166:167], v[52:55], off
	global_store_dwordx4 v[166:167], v[40:43], off offset:16
	s_waitcnt vmcnt(18)
	v_pk_add_f32 v[32:33], v[32:33], v[198:199]
	v_pk_add_f32 v[34:35], v[34:35], v[200:201]
	v_pk_add_f32 v[28:29], v[28:29], v[202:203]
	v_pk_add_f32 v[30:31], v[30:31], v[204:205]
	global_store_dwordx4 v[166:167], v[32:35], off offset:512
	global_store_dwordx4 v[166:167], v[28:31], off offset:528
	s_waitcnt vmcnt(16)
	v_pk_add_f32 v[36:37], v[36:37], v[144:145]
	v_pk_add_f32 v[38:39], v[38:39], v[146:147]
	v_pk_add_f32 v[24:25], v[24:25], v[154:155]
	v_pk_add_f32 v[26:27], v[26:27], v[156:157]
	v_lshl_add_u64 v[166:167], v[166:167], 0, s[98:99]
	global_store_dwordx4 v[166:167], v[36:39], off
	global_store_dwordx4 v[166:167], v[24:27], off offset:16
	s_waitcnt vmcnt(14)
	v_pk_add_f32 v[16:17], v[16:17], v[158:159]
	v_pk_add_f32 v[18:19], v[18:19], v[160:161]
	v_pk_add_f32 v[12:13], v[12:13], v[170:171]
	v_pk_add_f32 v[14:15], v[14:15], v[172:173]
	global_store_dwordx4 v[166:167], v[16:19], off offset:512
	global_store_dwordx4 v[166:167], v[12:15], off offset:528
	s_waitcnt vmcnt(12)
	v_pk_add_f32 v[20:21], v[20:21], v[174:175]
	v_pk_add_f32 v[22:23], v[22:23], v[176:177]
	v_pk_add_f32 v[8:9], v[8:9], v[178:179]
	v_pk_add_f32 v[10:11], v[10:11], v[180:181]
	v_lshl_add_u64 v[166:167], v[166:167], 0, s[98:99]
	global_store_dwordx4 v[166:167], v[20:23], off
	global_store_dwordx4 v[166:167], v[8:11], off offset:16
	s_waitcnt vmcnt(10)
	v_pk_add_f32 v[4:5], v[4:5], v[182:183]
	v_pk_add_f32 v[6:7], v[6:7], v[184:185]
	v_pk_add_f32 v[0:1], v[0:1], v[186:187]
	v_pk_add_f32 v[2:3], v[2:3], v[188:189]
	global_store_dwordx4 v[166:167], v[4:7], off offset:512
	global_store_dwordx4 v[166:167], v[0:3], off offset:528
	s_andn2_b64 vcc, exec, s[2:3]
	s_mov_b64 s[2:3], -1
	s_cbranch_vccnz .LBB0_986
	s_andn2_b64 vcc, exec, s[8:9]
	s_cbranch_vccnz .LBB0_985
	s_barrier
	s_branch .LBB0_985

; __device__ __forceinline__ unsigned xb_ld(unsigned* p)              { return __hip_atomic_load(p, __ATOMIC_RELAXED, __HIP_MEMORY_SCOPE_AGENT); }
; __device__ __forceinline__ unsigned xb_add(unsigned* p, unsigned v) { return __hip_atomic_fetch_add(p, v, __ATOMIC_RELAXED, __HIP_MEMORY_SCOPE_AGENT); }
; #define XB_SPIN(cond, bar) do { unsigned _sp = 0; while (cond) { __builtin_amdgcn_s_sleep(1); \
;     if ((++_sp & 255u) == 0u) { if (xb_ld(&(bar)[XB_TMO])) break; if (_sp > XB_SPIN_CAP) { atomicAdd(&(bar)[XB_TMO], 1u); break; } } } } while (0)
; __device__ __forceinline__ void xcd_barrier(const XcdBarrier& b, bool leader) {
;     ...
;     if (leader) {
;         unsigned* bar = b.bar;
;         __builtin_amdgcn_s_waitcnt(0);
;         unsigned nloc = b.st[0], nx = b.st[1];
;         if (nloc == 0u) { xcd_barrier_complete(bar, b.x, nloc, nx); b.st[0] = nloc; b.st[1] = nx; }
;         const unsigned old = xb_add(&bar[XB_XSUB(b.x)], 1u);
;         const unsigned gen = old / nloc;
;         if (old + 1u == (gen + 1u) * nloc) {
;             __builtin_amdgcn_fence(__ATOMIC_RELEASE, "agent");
;             asm volatile("s_waitcnt vmcnt(0)" ::: "memory");
;             const unsigned og = xb_add(&bar[XB_TOP], 1u);
;             const unsigned tg = og / nx;
;             if (og + 1u == (tg + 1u) * nx) xb_add(&bar[XB_TOPGEN], 1u);
;             else XB_SPIN(xb_ld(&bar[XB_TOPGEN]) == tg, bar);
;             __builtin_amdgcn_fence(__ATOMIC_ACQUIRE, "agent");
;             xb_add(&bar[XB_XGEN(b.x)], 1u);
;             asm volatile("s_waitcnt vmcnt(0)" ::: "memory");
;         } else {
;             XB_SPIN(xb_ld(&bar[XB_XGEN(b.x)]) == gen, bar);
;             __builtin_amdgcn_fence(__ATOMIC_ACQUIRE, "agent");
;             asm volatile("s_waitcnt vmcnt(0)" ::: "memory");
;         }
.LBB0_1016:
	s_lshl_b32 s2, s38, 8
	s_add_u32 s2, s1, s2
	s_addc_u32 s3, s0, 0
	v_mov_b32_e32 v1, s2
	v_add_co_u32_e32 v4, vcc, 0x2000, v1
	v_mov_b32_e32 v1, s3
	s_nop 0
	v_addc_co_u32_e32 v5, vcc, 0, v1, vcc
	v_mov_b32_e32 v1, 1
	global_atomic_add v1, v[4:5], v1, off offset:1024 sc0
	v_cvt_f32_u32_e32 v3, v2
	v_sub_u32_e32 v4, 0, v2
	s_add_u32 s25, s2, 0x1000
	s_addc_u32 s24, s3, 0
	v_rcp_iflag_f32_e32 v3, v3
	s_nop 0
	v_mul_f32_e32 v3, 0x4f7ffffe, v3
	v_cvt_u32_f32_e32 v3, v3
	v_mul_lo_u32 v4, v4, v3
	v_mul_hi_u32 v4, v3, v4
	v_add_u32_e32 v3, v3, v4
	s_waitcnt vmcnt(0) lgkmcnt(0)
	v_mul_hi_u32 v3, v1, v3
	v_mul_lo_u32 v5, v3, v2
	v_add_u32_e32 v4, 1, v1
	v_sub_u32_e32 v1, v1, v5
	v_add_u32_e32 v6, 1, v3
	v_cmp_ge_u32_e32 vcc, v1, v2
	v_sub_u32_e32 v5, v1, v2
	s_nop 0
	v_cndmask_b32_e32 v3, v3, v6, vcc
	v_cndmask_b32_e32 v1, v1, v5, vcc
	v_add_u32_e32 v5, 1, v3
	v_cmp_ge_u32_e32 vcc, v1, v2
	s_nop 1
	v_cndmask_b32_e32 v1, v3, v5, vcc
	v_mad_u64_u32 v[2:3], s[2:3], v2, v1, v[2:3]
	v_cmp_ne_u32_e32 vcc, v4, v2
	s_and_saveexec_b64 s[2:3], vcc
	s_xor_b64 s[2:3], exec, s[2:3]
	s_cbranch_execz .LBB0_1029
	v_mov_b32_e32 v0, s1
	v_add_co_u32_e32 v2, vcc, 0x4100, v0
	v_mov_b32_e32 v0, s0
	s_nop 0
	v_addc_co_u32_e32 v3, vcc, 0, v0, vcc
	global_load_dword v0, v[2:3], off offset:1024 sc1
	s_add_u32 s8, s1, 0x4500
	s_addc_u32 s9, s0, 0
	s_waitcnt vmcnt(0) lgkmcnt(0)
	v_cmp_eq_u32_e32 vcc, v0, v1
	s_and_saveexec_b64 s[4:5], vcc
	s_cbranch_execz .LBB0_1028
	s_add_u32 s6, s1, 0x1200
	s_addc_u32 s7, s0, 0
	s_mov_b32 s26, 1
	s_mov_b64 s[10:11], 0
	s_branch .LBB0_1020

;     __device__ __forceinline__ void operator()(EPI_ARGS) const {
;         const int row0 = u.pm * BM + wr * 64 + fr, col0 = u.pn * BM + wc * 32 + 8 * fq;
; #pragma unroll
;         for (int ai = 0; ai < 2; ++ai)
; #pragma unroll
;             for (int m = 0; m < 4; ++m) { const int row = row0 + ai * HALF + m * 16;
;                 const float* b = base + (size_t)row * DM + col0; float* o = X + (size_t)row * DM + col0;
; #pragma unroll
;                 for (int bj = 0; bj < 2; ++bj) { const f32x4 b0 = *(const f32x4*)(b + bj * HALF), b1 = *(const f32x4*)(b + bj * HALF + 4);
;                     *(f32x4*)(o + bj * HALF) = b0 + acc[ai][bj][m][0]; *(f32x4*)(o + bj * HALF + 4) = b1 + acc[ai][bj][m][1]; } }
;     }
.LBB0_1057:
	v_lshl_add_u32 v158, s30, 8, v144
	v_lshl_or_b32 v140, s63, 8, v146
	v_ashrrev_i32_e32 v159, 31, v158
	v_ashrrev_i32_e32 v141, 31, v140
	v_lshlrev_b64 v[142:143], 12, v[158:159]
	v_lshl_add_u64 v[150:151], s[2:3], 0, v[142:143]
	v_lshlrev_b64 v[140:141], 2, v[140:141]
	v_lshl_add_u64 v[160:161], v[150:151], 0, v[140:141]
	v_lshl_add_u64 v[162:163], s[6:7], 0, v[142:143]
	v_lshl_add_u64 v[162:163], v[162:163], 0, v[140:141]
	s_mov_b64 s[98:99], 0x10000
	s_mov_b64 s[100:101], 0x50000
	global_load_dwordx4 v[140:143], v[160:161], off
	global_load_dwordx4 v[150:153], v[160:161], off offset:16
	global_load_dwordx4 v[154:157], v[160:161], off offset:512
	global_load_dwordx4 v[166:169], v[160:161], off offset:528
	v_lshl_add_u64 v[160:161], v[160:161], 0, s[98:99]
	global_load_dwordx4 v[170:173], v[160:161], off
	global_load_dwordx4 v[174:177], v[160:161], off offset:16
	global_load_dwordx4 v[178:181], v[160:161], off offset:512
	global_load_dwordx4 v[182:185], v[160:161], off offset:528
	v_lshl_add_u64 v[160:161], v[160:161], 0, s[98:99]
	global_load_dwordx4 v[186:189], v[160:161], off
	global_load_dwordx4 v[190:193], v[160:161], off offset:16
	global_load_dwordx4 v[194:197], v[160:161], off offset:512
	global_load_dwordx4 v[198:201], v[160:161], off offset:528
	s_waitcnt vmcnt(10)
	v_pk_add_f32 v[124:125], v[124:125], v[140:141]
	v_pk_add_f32 v[126:127], v[126:127], v[142:143]
	v_pk_add_f32 v[120:121], v[120:121], v[150:151]
	v_pk_add_f32 v[122:123], v[122:123], v[152:153]
	global_store_dwordx4 v[162:163], v[124:127], off
	global_store_dwordx4 v[162:163], v[120:123], off offset:16
	v_lshl_add_u64 v[160:161], v[160:161], 0, s[98:99]
	global_load_dwordx4 v[140:143], v[160:161], off
	global_load_dwordx4 v[150:153], v[160:161], off offset:16
	s_waitcnt vmcnt(12)
	v_pk_add_f32 v[112:113], v[112:113], v[154:155]
	v_pk_add_f32 v[114:115], v[114:115], v[156:157]
	v_pk_add_f32 v[108:109], v[108:109], v[166:167]
	v_pk_add_f32 v[110:111], v[110:111], v[168:169]
	global_store_dwordx4 v[162:163], v[112:115], off offset:512
	global_store_dwordx4 v[162:163], v[108:111], off offset:528
	global_load_dwordx4 v[154:157], v[160:161], off offset:512
	global_load_dwordx4 v[166:169], v[160:161], off offset:528
	s_waitcnt vmcnt(14)
	v_pk_add_f32 v[116:117], v[116:117], v[170:171]
	v_pk_add_f32 v[118:119], v[118:119], v[172:173]
	v_pk_add_f32 v[104:105], v[104:105], v[174:175]
	v_pk_add_f32 v[106:107], v[106:107], v[176:177]
	v_lshl_add_u64 v[162:163], v[162:163], 0, s[98:99]
	global_store_dwordx4 v[162:163], v[116:119], off
	global_store_dwordx4 v[162:163], v[104:107], off offset:16
	v_lshl_add_u64 v[160:161], v[160:161], 0, s[100:101]
	global_load_dwordx4 v[170:173], v[160:161], off
	global_load_dwordx4 v[174:177], v[160:161], off offset:16
	s_waitcnt vmcnt(16)
	v_pk_add_f32 v[96:97], v[96:97], v[178:179]
	v_pk_add_f32 v[98:99], v[98:99], v[180:181]
	v_pk_add_f32 v[92:93], v[92:93], v[182:183]
	v_pk_add_f32 v[94:95], v[94:95], v[184:185]
	global_store_dwordx4 v[162:163], v[96:99], off offset:512
	global_store_dwordx4 v[162:163], v[92:95], off offset:528
	global_load_dwordx4 v[178:181], v[160:161], off offset:512
	global_load_dwordx4 v[182:185], v[160:161], off offset:528
	s_waitcnt vmcnt(18)
	v_pk_add_f32 v[100:101], v[100:101], v[186:187]
	v_pk_add_f32 v[102:103], v[102:103], v[188:189]
	v_pk_add_f32 v[88:89], v[88:89], v[190:191]
	v_pk_add_f32 v[90:91], v[90:91], v[192:193]
	v_lshl_add_u64 v[162:163], v[162:163], 0, s[98:99]
	global_store_dwordx4 v[162:163], v[100:103], off
	global_store_dwordx4 v[162:163], v[88:91], off offset:16
	v_lshl_add_u64 v[160:161], v[160:161], 0, s[98:99]
	global_load_dwordx4 v[186:189], v[160:161], off
	global_load_dwordx4 v[190:193], v[160:161], off offset:16
	s_waitcnt vmcnt(20)
	v_pk_add_f32 v[80:81], v[80:81], v[194:195]
	v_pk_add_f32 v[82:83], v[82:83], v[196:197]
	v_pk_add_f32 v[76:77], v[76:77], v[198:199]
	v_pk_add_f32 v[78:79], v[78:79], v[200:201]
	global_store_dwordx4 v[162:163], v[80:83], off offset:512
	global_store_dwordx4 v[162:163], v[76:79], off offset:528
	global_load_dwordx4 v[194:197], v[160:161], off offset:512
	global_load_dwordx4 v[198:201], v[160:161], off offset:528
	s_waitcnt vmcnt(20)
;     __device__ __forceinline__ void operator()(EPI_ARGS) const {
;         const int row0 = u.pm * BM + wr * 64 + fr, col0 = u.pn * BM + wc * 32 + 8 * fq;
; #pragma unroll
;         for (int ai = 0; ai < 2; ++ai)
; #pragma unroll
;             for (int m = 0; m < 4; ++m) { const int row = row0 + ai * HALF + m * 16;
;                 const float* b = base + (size_t)row * DM + col0; float* o = X + (size_t)row * DM + col0;
; #pragma unroll
;                 for (int bj = 0; bj < 2; ++bj) { const f32x4 b0 = *(const f32x4*)(b + bj * HALF), b1 = *(const f32x4*)(b + bj * HALF + 4);
;                     *(f32x4*)(o + bj * HALF) = b0 + acc[ai][bj][m][0]; *(f32x4*)(o + bj * HALF + 4) = b1 + acc[ai][bj][m][1]; } }
;     }
	v_pk_add_f32 v[84:85], v[84:85], v[140:141]
	v_pk_add_f32 v[86:87], v[86:87], v[142:143]
	v_pk_add_f32 v[72:73], v[72:73], v[150:151]
	v_pk_add_f32 v[74:75], v[74:75], v[152:153]
	v_lshl_add_u64 v[162:163], v[162:163], 0, s[98:99]
	global_store_dwordx4 v[162:163], v[84:87], off
	global_store_dwordx4 v[162:163], v[72:75], off offset:16
	v_lshl_add_u64 v[160:161], v[160:161], 0, s[98:99]
	global_load_dwordx4 v[140:143], v[160:161], off
	global_load_dwordx4 v[150:153], v[160:161], off offset:16
	s_waitcnt vmcnt(20)
	v_pk_add_f32 v[68:69], v[68:69], v[154:155]
	v_pk_add_f32 v[70:71], v[70:71], v[156:157]
	v_pk_add_f32 v[64:65], v[64:65], v[166:167]
	v_pk_add_f32 v[66:67], v[66:67], v[168:169]
	global_store_dwordx4 v[162:163], v[68:71], off offset:512
	global_store_dwordx4 v[162:163], v[64:67], off offset:528
	global_load_dwordx4 v[154:157], v[160:161], off offset:512
	global_load_dwordx4 v[166:169], v[160:161], off offset:528
	s_waitcnt vmcnt(20)
	v_pk_add_f32 v[60:61], v[60:61], v[170:171]
	v_pk_add_f32 v[62:63], v[62:63], v[172:173]
	v_pk_add_f32 v[56:57], v[56:57], v[174:175]
	v_pk_add_f32 v[58:59], v[58:59], v[176:177]
	v_lshl_add_u64 v[162:163], v[162:163], 0, s[100:101]
	global_store_dwordx4 v[162:163], v[60:63], off
	global_store_dwordx4 v[162:163], v[56:59], off offset:16
	v_lshl_add_u64 v[160:161], v[160:161], 0, s[98:99]
	global_load_dwordx4 v[170:173], v[160:161], off
	global_load_dwordx4 v[174:177], v[160:161], off offset:16
	s_waitcnt vmcnt(20)
	v_pk_add_f32 v[48:49], v[48:49], v[178:179]
	v_pk_add_f32 v[50:51], v[50:51], v[180:181]
	v_pk_add_f32 v[44:45], v[44:45], v[182:183]
	v_pk_add_f32 v[46:47], v[46:47], v[184:185]
	global_store_dwordx4 v[162:163], v[48:51], off offset:512
	global_store_dwordx4 v[162:163], v[44:47], off offset:528
	global_load_dwordx4 v[178:181], v[160:161], off offset:512
	global_load_dwordx4 v[182:185], v[160:161], off offset:528
	s_waitcnt vmcnt(20)
	v_pk_add_f32 v[52:53], v[52:53], v[186:187]
	v_pk_add_f32 v[54:55], v[54:55], v[188:189]
	v_pk_add_f32 v[40:41], v[40:41], v[190:191]
	v_pk_add_f32 v[42:43], v[42:43], v[192:193]
	v_lshl_add_u64 v[162:163], v[162:163], 0, s[98:99]
	global_store_dwordx4 v[162:163], v[52:55], off
	global_store_dwordx4 v[162:163], v[40:43], off offset:16
	s_waitcnt vmcnt(18)
	v_pk_add_f32 v[32:33], v[32:33], v[194:195]
	v_pk_add_f32 v[34:35], v[34:35], v[196:197]
	v_pk_add_f32 v[28:29], v[28:29], v[198:199]
	v_pk_add_f32 v[30:31], v[30:31], v[200:201]
	global_store_dwordx4 v[162:163], v[32:35], off offset:512
	global_store_dwordx4 v[162:163], v[28:31], off offset:528
	s_waitcnt vmcnt(16)
	v_pk_add_f32 v[36:37], v[36:37], v[140:141]
	v_pk_add_f32 v[38:39], v[38:39], v[142:143]
	v_pk_add_f32 v[24:25], v[24:25], v[150:151]
	v_pk_add_f32 v[26:27], v[26:27], v[152:153]
	v_lshl_add_u64 v[162:163], v[162:163], 0, s[98:99]
	global_store_dwordx4 v[162:163], v[36:39], off
	global_store_dwordx4 v[162:163], v[24:27], off offset:16
	s_waitcnt vmcnt(14)
	v_pk_add_f32 v[16:17], v[16:17], v[154:155]
	v_pk_add_f32 v[18:19], v[18:19], v[156:157]
	v_pk_add_f32 v[12:13], v[12:13], v[166:167]
	v_pk_add_f32 v[14:15], v[14:15], v[168:169]
	global_store_dwordx4 v[162:163], v[16:19], off offset:512
	global_store_dwordx4 v[162:163], v[12:15], off offset:528
	s_waitcnt vmcnt(12)
	v_pk_add_f32 v[20:21], v[20:21], v[170:171]
	v_pk_add_f32 v[22:23], v[22:23], v[172:173]
	v_pk_add_f32 v[8:9], v[8:9], v[174:175]
	v_pk_add_f32 v[10:11], v[10:11], v[176:177]
	v_lshl_add_u64 v[162:163], v[162:163], 0, s[98:99]
	global_store_dwordx4 v[162:163], v[20:23], off
	global_store_dwordx4 v[162:163], v[8:11], off offset:16
	s_waitcnt vmcnt(10)
	v_pk_add_f32 v[4:5], v[4:5], v[178:179]
	v_pk_add_f32 v[6:7], v[6:7], v[180:181]
	v_pk_add_f32 v[0:1], v[0:1], v[182:183]
	v_pk_add_f32 v[2:3], v[2:3], v[184:185]
	global_store_dwordx4 v[162:163], v[4:7], off offset:512
	global_store_dwordx4 v[162:163], v[0:3], off offset:528
	s_andn2_b64 vcc, exec, s[24:25]
	s_mov_b64 s[24:25], -1
	s_cbranch_vccnz .LBB0_1050
	s_andn2_b64 vcc, exec, s[4:5]
	s_cbranch_vccnz .LBB0_1049
	s_barrier
	s_branch .LBB0_1049

; __device__ __forceinline__ unsigned xb_ld(unsigned* p)              { return __hip_atomic_load(p, __ATOMIC_RELAXED, __HIP_MEMORY_SCOPE_AGENT); }
; __device__ __forceinline__ unsigned xb_add(unsigned* p, unsigned v) { return __hip_atomic_fetch_add(p, v, __ATOMIC_RELAXED, __HIP_MEMORY_SCOPE_AGENT); }
; #define XB_SPIN(cond, bar) do { unsigned _sp = 0; while (cond) { __builtin_amdgcn_s_sleep(1); \
;     if ((++_sp & 255u) == 0u) { if (xb_ld(&(bar)[XB_TMO])) break; if (_sp > XB_SPIN_CAP) { atomicAdd(&(bar)[XB_TMO], 1u); break; } } } } while (0)
; __device__ __forceinline__ void xcd_barrier(const XcdBarrier& b, bool leader) {
;     ...
;     if (leader) {
;         unsigned* bar = b.bar;
;         __builtin_amdgcn_s_waitcnt(0);
;         unsigned nloc = b.st[0], nx = b.st[1];
;         if (nloc == 0u) { xcd_barrier_complete(bar, b.x, nloc, nx); b.st[0] = nloc; b.st[1] = nx; }
;         const unsigned old = xb_add(&bar[XB_XSUB(b.x)], 1u);
;         const unsigned gen = old / nloc;
;         if (old + 1u == (gen + 1u) * nloc) {
;             __builtin_amdgcn_fence(__ATOMIC_RELEASE, "agent");
;             asm volatile("s_waitcnt vmcnt(0)" ::: "memory");
;             const unsigned og = xb_add(&bar[XB_TOP], 1u);
;             const unsigned tg = og / nx;
;             if (og + 1u == (tg + 1u) * nx) xb_add(&bar[XB_TOPGEN], 1u);
;             else XB_SPIN(xb_ld(&bar[XB_TOPGEN]) == tg, bar);
;             __builtin_amdgcn_fence(__ATOMIC_ACQUIRE, "agent");
;             xb_add(&bar[XB_XGEN(b.x)], 1u);
;             asm volatile("s_waitcnt vmcnt(0)" ::: "memory");
;         } else {
;             XB_SPIN(xb_ld(&bar[XB_XGEN(b.x)]) == gen, bar);
;             __builtin_amdgcn_fence(__ATOMIC_ACQUIRE, "agent");
;             asm volatile("s_waitcnt vmcnt(0)" ::: "memory");
;         }
.LBB0_1084:
	s_lshl_b32 s2, s40, 8
	s_add_u32 s2, s1, s2
	s_addc_u32 s3, s0, 0
	v_mov_b32_e32 v1, s2
	v_add_co_u32_e32 v4, vcc, 0x2000, v1
	v_mov_b32_e32 v1, s3
	s_nop 0
	v_addc_co_u32_e32 v5, vcc, 0, v1, vcc
	v_mov_b32_e32 v1, 1
	global_atomic_add v1, v[4:5], v1, off offset:1024 sc0
	v_cvt_f32_u32_e32 v3, v2
	v_sub_u32_e32 v4, 0, v2
	s_add_u32 s25, s2, 0x1000
	s_addc_u32 s24, s3, 0
	v_rcp_iflag_f32_e32 v3, v3
	s_nop 0
	v_mul_f32_e32 v3, 0x4f7ffffe, v3
	v_cvt_u32_f32_e32 v3, v3
	v_mul_lo_u32 v4, v4, v3
	v_mul_hi_u32 v4, v3, v4
	v_add_u32_e32 v3, v3, v4
	s_waitcnt vmcnt(0) lgkmcnt(0)
	v_mul_hi_u32 v3, v1, v3
	v_mul_lo_u32 v5, v3, v2
	v_add_u32_e32 v4, 1, v1
	v_sub_u32_e32 v1, v1, v5
	v_add_u32_e32 v6, 1, v3
	v_cmp_ge_u32_e32 vcc, v1, v2
	v_sub_u32_e32 v5, v1, v2
	s_nop 0
	v_cndmask_b32_e32 v3, v3, v6, vcc
	v_cndmask_b32_e32 v1, v1, v5, vcc
	v_add_u32_e32 v5, 1, v3
	v_cmp_ge_u32_e32 vcc, v1, v2
	s_nop 1
	v_cndmask_b32_e32 v1, v3, v5, vcc
	v_mad_u64_u32 v[2:3], s[2:3], v2, v1, v[2:3]
	v_cmp_ne_u32_e32 vcc, v4, v2
	s_and_saveexec_b64 s[2:3], vcc
	s_xor_b64 s[2:3], exec, s[2:3]
	s_cbranch_execz .LBB0_1097
	v_mov_b32_e32 v0, s1
	v_add_co_u32_e32 v2, vcc, 0x4100, v0
	v_mov_b32_e32 v0, s0
	s_nop 0
	v_addc_co_u32_e32 v3, vcc, 0, v0, vcc
	global_load_dword v0, v[2:3], off offset:1024 sc1
	s_add_u32 s8, s1, 0x4500
	s_addc_u32 s9, s0, 0
	s_waitcnt vmcnt(0) lgkmcnt(0)
	v_cmp_eq_u32_e32 vcc, v0, v1
	s_and_saveexec_b64 s[4:5], vcc
	s_cbranch_execz .LBB0_1096
	s_add_u32 s6, s1, 0x1200
	s_addc_u32 s7, s0, 0
	s_mov_b32 s26, 1
	s_mov_b64 s[10:11], 0
	s_branch .LBB0_1088

; __device__ __forceinline__ unsigned xb_ld(unsigned* p)              { return __hip_atomic_load(p, __ATOMIC_RELAXED, __HIP_MEMORY_SCOPE_AGENT); }
; __device__ __forceinline__ unsigned xb_add(unsigned* p, unsigned v) { return __hip_atomic_fetch_add(p, v, __ATOMIC_RELAXED, __HIP_MEMORY_SCOPE_AGENT); }
; #define XB_SPIN(cond, bar) do { unsigned _sp = 0; while (cond) { __builtin_amdgcn_s_sleep(1); \
;     if ((++_sp & 255u) == 0u) { if (xb_ld(&(bar)[XB_TMO])) break; if (_sp > XB_SPIN_CAP) { atomicAdd(&(bar)[XB_TMO], 1u); break; } } } } while (0)
; __device__ __forceinline__ void xcd_barrier(const XcdBarrier& b, bool leader) {
;     ...
;     if (leader) {
;         unsigned* bar = b.bar;
;         __builtin_amdgcn_s_waitcnt(0);
;         unsigned nloc = b.st[0], nx = b.st[1];
;         if (nloc == 0u) { xcd_barrier_complete(bar, b.x, nloc, nx); b.st[0] = nloc; b.st[1] = nx; }
;         const unsigned old = xb_add(&bar[XB_XSUB(b.x)], 1u);
;         const unsigned gen = old / nloc;
;         if (old + 1u == (gen + 1u) * nloc) {
;             __builtin_amdgcn_fence(__ATOMIC_RELEASE, "agent");
;             asm volatile("s_waitcnt vmcnt(0)" ::: "memory");
;             const unsigned og = xb_add(&bar[XB_TOP], 1u);
;             const unsigned tg = og / nx;
;             if (og + 1u == (tg + 1u) * nx) xb_add(&bar[XB_TOPGEN], 1u);
;             else XB_SPIN(xb_ld(&bar[XB_TOPGEN]) == tg, bar);
;             __builtin_amdgcn_fence(__ATOMIC_ACQUIRE, "agent");
;             xb_add(&bar[XB_XGEN(b.x)], 1u);
;             asm volatile("s_waitcnt vmcnt(0)" ::: "memory");
;         } else {
;             XB_SPIN(xb_ld(&bar[XB_XGEN(b.x)]) == gen, bar);
;             __builtin_amdgcn_fence(__ATOMIC_ACQUIRE, "agent");
;             asm volatile("s_waitcnt vmcnt(0)" ::: "memory");
;         }
.LBB0_1155:
	s_lshl_b32 s4, s37, 8
	s_add_u32 s4, s1, s4
	s_addc_u32 s5, s0, 0
	v_mov_b32_e32 v1, s4
	v_add_co_u32_e32 v4, vcc, 0x2000, v1
	v_mov_b32_e32 v1, s5
	s_nop 0
	v_addc_co_u32_e32 v5, vcc, 0, v1, vcc
	v_mov_b32_e32 v1, 1
	global_atomic_add v1, v[4:5], v1, off offset:1024 sc0
	v_cvt_f32_u32_e32 v3, v2
	v_sub_u32_e32 v4, 0, v2
	s_add_u32 s27, s4, 0x1000
	s_addc_u32 s26, s5, 0
	v_rcp_iflag_f32_e32 v3, v3
	s_nop 0
	v_mul_f32_e32 v3, 0x4f7ffffe, v3
	v_cvt_u32_f32_e32 v3, v3
	v_mul_lo_u32 v4, v4, v3
	v_mul_hi_u32 v4, v3, v4
	v_add_u32_e32 v3, v3, v4
	s_waitcnt vmcnt(0) lgkmcnt(0)
	v_mul_hi_u32 v3, v1, v3
	v_mul_lo_u32 v5, v3, v2
	v_add_u32_e32 v4, 1, v1
	v_sub_u32_e32 v1, v1, v5
	v_add_u32_e32 v6, 1, v3
	v_cmp_ge_u32_e32 vcc, v1, v2
	v_sub_u32_e32 v5, v1, v2
	s_nop 0
	v_cndmask_b32_e32 v3, v3, v6, vcc
	v_cndmask_b32_e32 v1, v1, v5, vcc
	v_add_u32_e32 v5, 1, v3
	v_cmp_ge_u32_e32 vcc, v1, v2
	s_nop 1
	v_cndmask_b32_e32 v1, v3, v5, vcc
	v_mad_u64_u32 v[2:3], s[4:5], v2, v1, v[2:3]
	v_cmp_ne_u32_e32 vcc, v4, v2
	s_and_saveexec_b64 s[4:5], vcc
	s_xor_b64 s[4:5], exec, s[4:5]
	s_cbranch_execz .LBB0_1168
	v_mov_b32_e32 v0, s1
	v_add_co_u32_e32 v2, vcc, 0x4100, v0
	v_mov_b32_e32 v0, s0
	s_nop 0
	v_addc_co_u32_e32 v3, vcc, 0, v0, vcc
	global_load_dword v0, v[2:3], off offset:1024 sc1
	s_add_u32 s10, s1, 0x4500
	s_addc_u32 s11, s0, 0
	s_waitcnt vmcnt(0) lgkmcnt(0)
	v_cmp_eq_u32_e32 vcc, v0, v1
	s_and_saveexec_b64 s[6:7], vcc
	s_cbranch_execz .LBB0_1167
	s_add_u32 s8, s1, 0x1200
	s_addc_u32 s9, s0, 0
	s_mov_b32 s28, 1
	s_mov_b64 s[12:13], 0
	s_branch .LBB0_1159

;     __device__ __forceinline__ void operator()(EPI_ARGS) const {
;         const int row0 = u.pm * BM + wr * 64 + fr, col0 = u.pn * BM + wc * 32 + 8 * fq;
; #pragma unroll
;         for (int ai = 0; ai < 2; ++ai)
; #pragma unroll
;             for (int m = 0; m < 4; ++m) { const int row = row0 + ai * HALF + m * 16;
;                 const float* b = base + (size_t)row * DM + col0; float* o = X + (size_t)row * DM + col0;
; #pragma unroll
;                 for (int bj = 0; bj < 2; ++bj) { const f32x4 b0 = *(const f32x4*)(b + bj * HALF), b1 = *(const f32x4*)(b + bj * HALF + 4);
;                     *(f32x4*)(o + bj * HALF) = b0 + acc[ai][bj][m][0]; *(f32x4*)(o + bj * HALF + 4) = b1 + acc[ai][bj][m][1]; } }
;     }
.LBB0_1314:
	v_lshl_add_u32 v148, s30, 8, v150
	v_lshl_or_b32 v144, s31, 8, v152
	v_ashrrev_i32_e32 v149, 31, v148
	v_ashrrev_i32_e32 v145, 31, v144
	v_lshlrev_b64 v[146:147], 12, v[148:149]
	v_lshl_add_u64 v[156:157], s[6:7], 0, v[146:147]
	v_lshlrev_b64 v[146:147], 2, v[144:145]
	v_lshl_add_u64 v[144:145], v[156:157], 0, v[146:147]
	s_mov_b64 s[98:99], 0x10000
	s_mov_b64 s[100:101], 0x50000
	v_mov_b64_e32 v[212:213], v[144:145]
	global_load_dwordx4 v[156:159], v[144:145], off
	global_load_dwordx4 v[160:163], v[144:145], off offset:16
	global_load_dwordx4 v[164:167], v[144:145], off offset:512
	global_load_dwordx4 v[168:171], v[144:145], off offset:528
	v_lshl_add_u64 v[144:145], v[144:145], 0, s[98:99]
	global_load_dwordx4 v[172:175], v[144:145], off
	global_load_dwordx4 v[176:179], v[144:145], off offset:16
	global_load_dwordx4 v[180:183], v[144:145], off offset:512
	global_load_dwordx4 v[184:187], v[144:145], off offset:528
	v_lshl_add_u64 v[144:145], v[144:145], 0, s[98:99]
	global_load_dwordx4 v[188:191], v[144:145], off
	global_load_dwordx4 v[192:195], v[144:145], off offset:16
	global_load_dwordx4 v[196:199], v[144:145], off offset:512
	global_load_dwordx4 v[200:203], v[144:145], off offset:528
	s_waitcnt vmcnt(10)
	v_pk_add_f32 v[124:125], v[124:125], v[156:157]
	v_pk_add_f32 v[126:127], v[126:127], v[158:159]
	v_pk_add_f32 v[120:121], v[120:121], v[160:161]
	v_pk_add_f32 v[122:123], v[122:123], v[162:163]
	global_store_dwordx4 v[212:213], v[124:127], off
	global_store_dwordx4 v[212:213], v[120:123], off offset:16
	v_lshl_add_u64 v[144:145], v[144:145], 0, s[98:99]
	global_load_dwordx4 v[156:159], v[144:145], off
	global_load_dwordx4 v[160:163], v[144:145], off offset:16
	s_waitcnt vmcnt(12)
	v_pk_add_f32 v[116:117], v[116:117], v[164:165]
	v_pk_add_f32 v[118:119], v[118:119], v[166:167]
	v_pk_add_f32 v[112:113], v[112:113], v[168:169]
	v_pk_add_f32 v[114:115], v[114:115], v[170:171]
	global_store_dwordx4 v[212:213], v[116:119], off offset:512
	global_store_dwordx4 v[212:213], v[112:115], off offset:528
	global_load_dwordx4 v[164:167], v[144:145], off offset:512
	global_load_dwordx4 v[168:171], v[144:145], off offset:528
	s_waitcnt vmcnt(14)
	v_pk_add_f32 v[108:109], v[108:109], v[172:173]
	v_pk_add_f32 v[110:111], v[110:111], v[174:175]
	v_pk_add_f32 v[104:105], v[104:105], v[176:177]
	v_pk_add_f32 v[106:107], v[106:107], v[178:179]
	v_lshl_add_u64 v[212:213], v[212:213], 0, s[98:99]
	global_store_dwordx4 v[212:213], v[108:111], off
	global_store_dwordx4 v[212:213], v[104:107], off offset:16
	v_lshl_add_u64 v[144:145], v[144:145], 0, s[100:101]
	global_load_dwordx4 v[172:175], v[144:145], off
	global_load_dwordx4 v[176:179], v[144:145], off offset:16
	s_waitcnt vmcnt(16)
	v_pk_add_f32 v[100:101], v[100:101], v[180:181]
	v_pk_add_f32 v[102:103], v[102:103], v[182:183]
	v_pk_add_f32 v[96:97], v[96:97], v[184:185]
	v_pk_add_f32 v[98:99], v[98:99], v[186:187]
	global_store_dwordx4 v[212:213], v[100:103], off offset:512
	global_store_dwordx4 v[212:213], v[96:99], off offset:528
	global_load_dwordx4 v[180:183], v[144:145], off offset:512
	global_load_dwordx4 v[184:187], v[144:145], off offset:528
	s_waitcnt vmcnt(18)
	v_pk_add_f32 v[92:93], v[92:93], v[188:189]
	v_pk_add_f32 v[94:95], v[94:95], v[190:191]
	v_pk_add_f32 v[88:89], v[88:89], v[192:193]
	v_pk_add_f32 v[90:91], v[90:91], v[194:195]
	v_lshl_add_u64 v[212:213], v[212:213], 0, s[98:99]
	global_store_dwordx4 v[212:213], v[92:95], off
	global_store_dwordx4 v[212:213], v[88:91], off offset:16
	v_lshl_add_u64 v[144:145], v[144:145], 0, s[98:99]
	global_load_dwordx4 v[188:191], v[144:145], off
	global_load_dwordx4 v[192:195], v[144:145], off offset:16
	s_waitcnt vmcnt(20)
	v_pk_add_f32 v[84:85], v[84:85], v[196:197]
	v_pk_add_f32 v[86:87], v[86:87], v[198:199]
	v_pk_add_f32 v[80:81], v[80:81], v[200:201]
	v_pk_add_f32 v[82:83], v[82:83], v[202:203]
	global_store_dwordx4 v[212:213], v[84:87], off offset:512
	global_store_dwordx4 v[212:213], v[80:83], off offset:528
	global_load_dwordx4 v[196:199], v[144:145], off offset:512
	global_load_dwordx4 v[200:203], v[144:145], off offset:528
	s_waitcnt vmcnt(20)
;     __device__ __forceinline__ void operator()(EPI_ARGS) const {
;         const int row0 = u.pm * BM + wr * 64 + fr, col0 = u.pn * BM + wc * 32 + 8 * fq;
; #pragma unroll
;         for (int ai = 0; ai < 2; ++ai)
; #pragma unroll
;             for (int m = 0; m < 4; ++m) { const int row = row0 + ai * HALF + m * 16;
;                 const float* b = base + (size_t)row * DM + col0; float* o = X + (size_t)row * DM + col0;
; #pragma unroll
;                 for (int bj = 0; bj < 2; ++bj) { const f32x4 b0 = *(const f32x4*)(b + bj * HALF), b1 = *(const f32x4*)(b + bj * HALF + 4);
;                     *(f32x4*)(o + bj * HALF) = b0 + acc[ai][bj][m][0]; *(f32x4*)(o + bj * HALF + 4) = b1 + acc[ai][bj][m][1]; } }
;     }
	v_pk_add_f32 v[76:77], v[76:77], v[156:157]
	v_pk_add_f32 v[78:79], v[78:79], v[158:159]
	v_pk_add_f32 v[72:73], v[72:73], v[160:161]
	v_pk_add_f32 v[74:75], v[74:75], v[162:163]
	v_lshl_add_u64 v[212:213], v[212:213], 0, s[98:99]
	global_store_dwordx4 v[212:213], v[76:79], off
	global_store_dwordx4 v[212:213], v[72:75], off offset:16
	v_lshl_add_u64 v[144:145], v[144:145], 0, s[98:99]
	global_load_dwordx4 v[156:159], v[144:145], off
	global_load_dwordx4 v[160:163], v[144:145], off offset:16
	s_waitcnt vmcnt(20)
	v_pk_add_f32 v[68:69], v[68:69], v[164:165]
	v_pk_add_f32 v[70:71], v[70:71], v[166:167]
	v_pk_add_f32 v[64:65], v[64:65], v[168:169]
	v_pk_add_f32 v[66:67], v[66:67], v[170:171]
	global_store_dwordx4 v[212:213], v[68:71], off offset:512
	global_store_dwordx4 v[212:213], v[64:67], off offset:528
	global_load_dwordx4 v[164:167], v[144:145], off offset:512
	global_load_dwordx4 v[168:171], v[144:145], off offset:528
	s_waitcnt vmcnt(20)
	v_pk_add_f32 v[60:61], v[60:61], v[172:173]
	v_pk_add_f32 v[62:63], v[62:63], v[174:175]
	v_pk_add_f32 v[56:57], v[56:57], v[176:177]
	v_pk_add_f32 v[58:59], v[58:59], v[178:179]
	v_lshl_add_u64 v[212:213], v[212:213], 0, s[100:101]
	global_store_dwordx4 v[212:213], v[60:63], off
	global_store_dwordx4 v[212:213], v[56:59], off offset:16
	v_lshl_add_u64 v[144:145], v[144:145], 0, s[98:99]
	global_load_dwordx4 v[172:175], v[144:145], off
	global_load_dwordx4 v[176:179], v[144:145], off offset:16
	s_waitcnt vmcnt(20)
	v_pk_add_f32 v[52:53], v[52:53], v[180:181]
	v_pk_add_f32 v[54:55], v[54:55], v[182:183]
	v_pk_add_f32 v[48:49], v[48:49], v[184:185]
	v_pk_add_f32 v[50:51], v[50:51], v[186:187]
	global_store_dwordx4 v[212:213], v[52:55], off offset:512
	global_store_dwordx4 v[212:213], v[48:51], off offset:528
	global_load_dwordx4 v[180:183], v[144:145], off offset:512
	global_load_dwordx4 v[184:187], v[144:145], off offset:528
	s_waitcnt vmcnt(20)
	v_pk_add_f32 v[44:45], v[44:45], v[188:189]
	v_pk_add_f32 v[46:47], v[46:47], v[190:191]
	v_pk_add_f32 v[40:41], v[40:41], v[192:193]
	v_pk_add_f32 v[42:43], v[42:43], v[194:195]
	v_lshl_add_u64 v[212:213], v[212:213], 0, s[98:99]
	global_store_dwordx4 v[212:213], v[44:47], off
	global_store_dwordx4 v[212:213], v[40:43], off offset:16
	s_waitcnt vmcnt(18)
	v_pk_add_f32 v[36:37], v[36:37], v[196:197]
	v_pk_add_f32 v[38:39], v[38:39], v[198:199]
	v_pk_add_f32 v[32:33], v[32:33], v[200:201]
	v_pk_add_f32 v[34:35], v[34:35], v[202:203]
	global_store_dwordx4 v[212:213], v[36:39], off offset:512
	global_store_dwordx4 v[212:213], v[32:35], off offset:528
	s_waitcnt vmcnt(16)
	v_pk_add_f32 v[28:29], v[28:29], v[156:157]
	v_pk_add_f32 v[30:31], v[30:31], v[158:159]
	v_pk_add_f32 v[24:25], v[24:25], v[160:161]
	v_pk_add_f32 v[26:27], v[26:27], v[162:163]
	v_lshl_add_u64 v[212:213], v[212:213], 0, s[98:99]
	global_store_dwordx4 v[212:213], v[28:31], off
	global_store_dwordx4 v[212:213], v[24:27], off offset:16
	s_waitcnt vmcnt(14)
	v_pk_add_f32 v[20:21], v[20:21], v[164:165]
	v_pk_add_f32 v[22:23], v[22:23], v[166:167]
	v_pk_add_f32 v[16:17], v[16:17], v[168:169]
	v_pk_add_f32 v[18:19], v[18:19], v[170:171]
	global_store_dwordx4 v[212:213], v[20:23], off offset:512
	global_store_dwordx4 v[212:213], v[16:19], off offset:528
	s_waitcnt vmcnt(12)
	v_pk_add_f32 v[12:13], v[12:13], v[172:173]
	v_pk_add_f32 v[14:15], v[14:15], v[174:175]
	v_pk_add_f32 v[8:9], v[8:9], v[176:177]
	v_pk_add_f32 v[10:11], v[10:11], v[178:179]
	v_lshl_add_u64 v[212:213], v[212:213], 0, s[98:99]
	global_store_dwordx4 v[212:213], v[12:15], off
	global_store_dwordx4 v[212:213], v[8:11], off offset:16
	s_waitcnt vmcnt(10)
	v_pk_add_f32 v[4:5], v[4:5], v[180:181]
	v_pk_add_f32 v[6:7], v[6:7], v[182:183]
	v_pk_add_f32 v[0:1], v[0:1], v[184:185]
	v_pk_add_f32 v[2:3], v[2:3], v[186:187]
	global_store_dwordx4 v[212:213], v[4:7], off offset:512
	global_store_dwordx4 v[212:213], v[0:3], off offset:528
	s_mov_b64 s[30:31], -1
	s_andn2_b64 vcc, exec, s[4:5]
	s_cbranch_vccnz .LBB0_1303
	s_andn2_b64 vcc, exec, s[8:9]
	s_cbranch_vccnz .LBB0_1302
	s_barrier
	s_branch .LBB0_1302

; __device__ __forceinline__ unsigned xb_ld(unsigned* p)              { return __hip_atomic_load(p, __ATOMIC_RELAXED, __HIP_MEMORY_SCOPE_AGENT); }
; __device__ __forceinline__ unsigned xb_add(unsigned* p, unsigned v) { return __hip_atomic_fetch_add(p, v, __ATOMIC_RELAXED, __HIP_MEMORY_SCOPE_AGENT); }
; #define XB_SPIN(cond, bar) do { unsigned _sp = 0; while (cond) { __builtin_amdgcn_s_sleep(1); \
;     if ((++_sp & 255u) == 0u) { if (xb_ld(&(bar)[XB_TMO])) break; if (_sp > XB_SPIN_CAP) { atomicAdd(&(bar)[XB_TMO], 1u); break; } } } } while (0)
; __device__ __forceinline__ void xcd_barrier(const XcdBarrier& b, bool leader) {
;     ...
;     if (leader) {
;         unsigned* bar = b.bar;
;         __builtin_amdgcn_s_waitcnt(0);
;         unsigned nloc = b.st[0], nx = b.st[1];
;         if (nloc == 0u) { xcd_barrier_complete(bar, b.x, nloc, nx); b.st[0] = nloc; b.st[1] = nx; }
;         const unsigned old = xb_add(&bar[XB_XSUB(b.x)], 1u);
;         const unsigned gen = old / nloc;
;         if (old + 1u == (gen + 1u) * nloc) {
;             __builtin_amdgcn_fence(__ATOMIC_RELEASE, "agent");
;             asm volatile("s_waitcnt vmcnt(0)" ::: "memory");
;             const unsigned og = xb_add(&bar[XB_TOP], 1u);
;             const unsigned tg = og / nx;
;             if (og + 1u == (tg + 1u) * nx) xb_add(&bar[XB_TOPGEN], 1u);
;             else XB_SPIN(xb_ld(&bar[XB_TOPGEN]) == tg, bar);
;             __builtin_amdgcn_fence(__ATOMIC_ACQUIRE, "agent");
;             xb_add(&bar[XB_XGEN(b.x)], 1u);
;             asm volatile("s_waitcnt vmcnt(0)" ::: "memory");
;         } else {
;             XB_SPIN(xb_ld(&bar[XB_XGEN(b.x)]) == gen, bar);
;             __builtin_amdgcn_fence(__ATOMIC_ACQUIRE, "agent");
;             asm volatile("s_waitcnt vmcnt(0)" ::: "memory");
;         }
.LBB0_1567:
	s_lshl_b32 s4, s41, 8
	s_add_u32 s4, s40, s4
	s_addc_u32 s5, s37, 0
	v_mov_b32_e32 v1, s4
	v_add_co_u32_e32 v4, vcc, 0x2000, v1
	v_mov_b32_e32 v1, s5
	s_nop 0
	v_addc_co_u32_e32 v5, vcc, 0, v1, vcc
	v_mov_b32_e32 v1, 1
	global_atomic_add v1, v[4:5], v1, off offset:1024 sc0
	v_cvt_f32_u32_e32 v3, v2
	v_sub_u32_e32 v4, 0, v2
	s_add_u32 s27, s4, 0x1000
	s_addc_u32 s26, s5, 0
	v_rcp_iflag_f32_e32 v3, v3
	s_nop 0
	v_mul_f32_e32 v3, 0x4f7ffffe, v3
	v_cvt_u32_f32_e32 v3, v3
	v_mul_lo_u32 v4, v4, v3
	v_mul_hi_u32 v4, v3, v4
	v_add_u32_e32 v3, v3, v4
	s_waitcnt vmcnt(0) lgkmcnt(0)
	v_mul_hi_u32 v3, v1, v3
	v_mul_lo_u32 v5, v3, v2
	v_add_u32_e32 v4, 1, v1
	v_sub_u32_e32 v1, v1, v5
	v_add_u32_e32 v6, 1, v3
	v_cmp_ge_u32_e32 vcc, v1, v2
	v_sub_u32_e32 v5, v1, v2
	s_nop 0
	v_cndmask_b32_e32 v3, v3, v6, vcc
	v_cndmask_b32_e32 v1, v1, v5, vcc
	v_add_u32_e32 v5, 1, v3
	v_cmp_ge_u32_e32 vcc, v1, v2
	s_nop 1
	v_cndmask_b32_e32 v1, v3, v5, vcc
	v_mad_u64_u32 v[2:3], s[4:5], v2, v1, v[2:3]
	v_cmp_ne_u32_e32 vcc, v4, v2
	s_and_saveexec_b64 s[4:5], vcc
	s_xor_b64 s[4:5], exec, s[4:5]
	s_cbranch_execz .LBB0_1580
	v_mov_b32_e32 v0, s40
	v_add_co_u32_e32 v2, vcc, 0x4100, v0
	v_mov_b32_e32 v0, s37
	s_nop 0
	v_addc_co_u32_e32 v3, vcc, 0, v0, vcc
	global_load_dword v0, v[2:3], off offset:1024 sc1
	s_add_u32 s10, s40, 0x4500
	s_addc_u32 s11, s37, 0
	s_waitcnt vmcnt(0) lgkmcnt(0)
	v_cmp_eq_u32_e32 vcc, v0, v1
	s_and_saveexec_b64 s[6:7], vcc
	s_cbranch_execz .LBB0_1579
	s_add_u32 s8, s40, 0x1200
	s_addc_u32 s9, s37, 0
	s_mov_b32 s28, 1
	s_mov_b64 s[12:13], 0
	s_branch .LBB0_1571

; #define OUTP() ((float*)tab_get(lds, 30))
; #define WSB(off) ((bf16*)((unsigned char*)tab_get(lds, 31) + (off)))
;     __device__ __forceinline__ void operator()(EPI_ARGS) const {
;         const int row0 = u.pm * BM + wr * 64 + fr, col0 = u.pn * BM + wc * 32 + 8 * fq;
; #pragma unroll
;         for (int ai = 0; ai < 2; ++ai)
; #pragma unroll
;             for (int m = 0; m < 4; ++m) { const int row = row0 + ai * HALF + m * 16;
;                 const float* b = base + (size_t)row * DM + col0; float* o = X + (size_t)row * DM + col0;
; #pragma unroll
;                 for (int bj = 0; bj < 2; ++bj) { const f32x4 b0 = *(const f32x4*)(b + bj * HALF), b1 = *(const f32x4*)(b + bj * HALF + 4);
;                     *(f32x4*)(o + bj * HALF) = b0 + acc[ai][bj][m][0]; *(f32x4*)(o + bj * HALF + 4) = b1 + acc[ai][bj][m][1]; } }
;     }
; __global__ void __launch_bounds__(512, 2) mega_fwd(Params p) {
;     ...
;         { float* X = OUTP(); pg8::Gemm g{WSB(WS_ACT), WSB(WS_WDN), MP, 1024, NFF, NFF, NFF}; pg8::StaticOrder S; S.init(MP, 1024, G, bx); pg8::EpiResid E{X, X}; pg8::gemm_phase(lds, g, S, E); }
.LBB0_1623:
	v_lshl_add_u32 v148, s59, 8, v150
	v_lshl_or_b32 v144, s60, 8, v152
	v_ashrrev_i32_e32 v149, 31, v148
	v_ashrrev_i32_e32 v145, 31, v144
	v_lshlrev_b64 v[146:147], 12, v[148:149]
	v_lshl_add_u64 v[156:157], s[6:7], 0, v[146:147]
	v_lshlrev_b64 v[146:147], 2, v[144:145]
	v_lshl_add_u64 v[144:145], v[156:157], 0, v[146:147]
	s_mov_b64 s[98:99], 0x10000
	s_mov_b64 s[100:101], 0x50000
	v_mov_b64_e32 v[212:213], v[144:145]
	global_load_dwordx4 v[156:159], v[144:145], off
	global_load_dwordx4 v[160:163], v[144:145], off offset:16
	global_load_dwordx4 v[164:167], v[144:145], off offset:512
	global_load_dwordx4 v[168:171], v[144:145], off offset:528
	v_lshl_add_u64 v[144:145], v[144:145], 0, s[98:99]
	global_load_dwordx4 v[172:175], v[144:145], off
	global_load_dwordx4 v[176:179], v[144:145], off offset:16
	global_load_dwordx4 v[180:183], v[144:145], off offset:512
	global_load_dwordx4 v[184:187], v[144:145], off offset:528
	v_lshl_add_u64 v[144:145], v[144:145], 0, s[98:99]
	global_load_dwordx4 v[188:191], v[144:145], off
	global_load_dwordx4 v[192:195], v[144:145], off offset:16
	global_load_dwordx4 v[196:199], v[144:145], off offset:512
	global_load_dwordx4 v[200:203], v[144:145], off offset:528
	s_waitcnt vmcnt(10)
	v_pk_add_f32 v[124:125], v[124:125], v[156:157]
	v_pk_add_f32 v[126:127], v[126:127], v[158:159]
	v_pk_add_f32 v[120:121], v[120:121], v[160:161]
	v_pk_add_f32 v[122:123], v[122:123], v[162:163]
	global_store_dwordx4 v[212:213], v[124:127], off
	global_store_dwordx4 v[212:213], v[120:123], off offset:16
	v_lshl_add_u64 v[144:145], v[144:145], 0, s[98:99]
	global_load_dwordx4 v[156:159], v[144:145], off
	global_load_dwordx4 v[160:163], v[144:145], off offset:16
	s_waitcnt vmcnt(12)
	v_pk_add_f32 v[116:117], v[116:117], v[164:165]
	v_pk_add_f32 v[118:119], v[118:119], v[166:167]
	v_pk_add_f32 v[112:113], v[112:113], v[168:169]
	v_pk_add_f32 v[114:115], v[114:115], v[170:171]
	global_store_dwordx4 v[212:213], v[116:119], off offset:512
	global_store_dwordx4 v[212:213], v[112:115], off offset:528
	global_load_dwordx4 v[164:167], v[144:145], off offset:512
	global_load_dwordx4 v[168:171], v[144:145], off offset:528
	s_waitcnt vmcnt(14)
	v_pk_add_f32 v[108:109], v[108:109], v[172:173]
	v_pk_add_f32 v[110:111], v[110:111], v[174:175]
	v_pk_add_f32 v[104:105], v[104:105], v[176:177]
	v_pk_add_f32 v[106:107], v[106:107], v[178:179]
	v_lshl_add_u64 v[212:213], v[212:213], 0, s[98:99]
	global_store_dwordx4 v[212:213], v[108:111], off
	global_store_dwordx4 v[212:213], v[104:107], off offset:16
	v_lshl_add_u64 v[144:145], v[144:145], 0, s[100:101]
	global_load_dwordx4 v[172:175], v[144:145], off
	global_load_dwordx4 v[176:179], v[144:145], off offset:16
	s_waitcnt vmcnt(16)
	v_pk_add_f32 v[100:101], v[100:101], v[180:181]
	v_pk_add_f32 v[102:103], v[102:103], v[182:183]
	v_pk_add_f32 v[96:97], v[96:97], v[184:185]
	v_pk_add_f32 v[98:99], v[98:99], v[186:187]
	global_store_dwordx4 v[212:213], v[100:103], off offset:512
	global_store_dwordx4 v[212:213], v[96:99], off offset:528
	global_load_dwordx4 v[180:183], v[144:145], off offset:512
	global_load_dwordx4 v[184:187], v[144:145], off offset:528
	s_waitcnt vmcnt(18)
	v_pk_add_f32 v[92:93], v[92:93], v[188:189]
	v_pk_add_f32 v[94:95], v[94:95], v[190:191]
	v_pk_add_f32 v[88:89], v[88:89], v[192:193]
	v_pk_add_f32 v[90:91], v[90:91], v[194:195]
	v_lshl_add_u64 v[212:213], v[212:213], 0, s[98:99]
	global_store_dwordx4 v[212:213], v[92:95], off
	global_store_dwordx4 v[212:213], v[88:91], off offset:16
	v_lshl_add_u64 v[144:145], v[144:145], 0, s[98:99]
	global_load_dwordx4 v[188:191], v[144:145], off
	global_load_dwordx4 v[192:195], v[144:145], off offset:16
	s_waitcnt vmcnt(20)
	v_pk_add_f32 v[84:85], v[84:85], v[196:197]
	v_pk_add_f32 v[86:87], v[86:87], v[198:199]
	v_pk_add_f32 v[80:81], v[80:81], v[200:201]
	v_pk_add_f32 v[82:83], v[82:83], v[202:203]
	global_store_dwordx4 v[212:213], v[84:87], off offset:512
	global_store_dwordx4 v[212:213], v[80:83], off offset:528
	global_load_dwordx4 v[196:199], v[144:145], off offset:512
	global_load_dwordx4 v[200:203], v[144:145], off offset:528
	s_waitcnt vmcnt(20)
;     __device__ __forceinline__ void operator()(EPI_ARGS) const {
;         const int row0 = u.pm * BM + wr * 64 + fr, col0 = u.pn * BM + wc * 32 + 8 * fq;
; #pragma unroll
;         for (int ai = 0; ai < 2; ++ai)
; #pragma unroll
;             for (int m = 0; m < 4; ++m) { const int row = row0 + ai * HALF + m * 16;
;                 const float* b = base + (size_t)row * DM + col0; float* o = X + (size_t)row * DM + col0;
; #pragma unroll
;                 for (int bj = 0; bj < 2; ++bj) { const f32x4 b0 = *(const f32x4*)(b + bj * HALF), b1 = *(const f32x4*)(b + bj * HALF + 4);
;                     *(f32x4*)(o + bj * HALF) = b0 + acc[ai][bj][m][0]; *(f32x4*)(o + bj * HALF + 4) = b1 + acc[ai][bj][m][1]; } }
;     }
	v_pk_add_f32 v[76:77], v[76:77], v[156:157]
	v_pk_add_f32 v[78:79], v[78:79], v[158:159]
	v_pk_add_f32 v[72:73], v[72:73], v[160:161]
	v_pk_add_f32 v[74:75], v[74:75], v[162:163]
	v_lshl_add_u64 v[212:213], v[212:213], 0, s[98:99]
	global_store_dwordx4 v[212:213], v[76:79], off
	global_store_dwordx4 v[212:213], v[72:75], off offset:16
	v_lshl_add_u64 v[144:145], v[144:145], 0, s[98:99]
	global_load_dwordx4 v[156:159], v[144:145], off
	global_load_dwordx4 v[160:163], v[144:145], off offset:16
	s_waitcnt vmcnt(20)
	v_pk_add_f32 v[68:69], v[68:69], v[164:165]
	v_pk_add_f32 v[70:71], v[70:71], v[166:167]
	v_pk_add_f32 v[64:65], v[64:65], v[168:169]
	v_pk_add_f32 v[66:67], v[66:67], v[170:171]
	global_store_dwordx4 v[212:213], v[68:71], off offset:512
	global_store_dwordx4 v[212:213], v[64:67], off offset:528
	global_load_dwordx4 v[164:167], v[144:145], off offset:512
	global_load_dwordx4 v[168:171], v[144:145], off offset:528
	s_waitcnt vmcnt(20)
	v_pk_add_f32 v[60:61], v[60:61], v[172:173]
	v_pk_add_f32 v[62:63], v[62:63], v[174:175]
	v_pk_add_f32 v[56:57], v[56:57], v[176:177]
	v_pk_add_f32 v[58:59], v[58:59], v[178:179]
	v_lshl_add_u64 v[212:213], v[212:213], 0, s[100:101]
	global_store_dwordx4 v[212:213], v[60:63], off
	global_store_dwordx4 v[212:213], v[56:59], off offset:16
	v_lshl_add_u64 v[144:145], v[144:145], 0, s[98:99]
	global_load_dwordx4 v[172:175], v[144:145], off
	global_load_dwordx4 v[176:179], v[144:145], off offset:16
	s_waitcnt vmcnt(20)
	v_pk_add_f32 v[52:53], v[52:53], v[180:181]
	v_pk_add_f32 v[54:55], v[54:55], v[182:183]
	v_pk_add_f32 v[48:49], v[48:49], v[184:185]
	v_pk_add_f32 v[50:51], v[50:51], v[186:187]
	global_store_dwordx4 v[212:213], v[52:55], off offset:512
	global_store_dwordx4 v[212:213], v[48:51], off offset:528
	global_load_dwordx4 v[180:183], v[144:145], off offset:512
	global_load_dwordx4 v[184:187], v[144:145], off offset:528
	s_waitcnt vmcnt(20)
	v_pk_add_f32 v[44:45], v[44:45], v[188:189]
	v_pk_add_f32 v[46:47], v[46:47], v[190:191]
	v_pk_add_f32 v[40:41], v[40:41], v[192:193]
	v_pk_add_f32 v[42:43], v[42:43], v[194:195]
	v_lshl_add_u64 v[212:213], v[212:213], 0, s[98:99]
	global_store_dwordx4 v[212:213], v[44:47], off
	global_store_dwordx4 v[212:213], v[40:43], off offset:16
	s_waitcnt vmcnt(18)
	v_pk_add_f32 v[36:37], v[36:37], v[196:197]
	v_pk_add_f32 v[38:39], v[38:39], v[198:199]
	v_pk_add_f32 v[32:33], v[32:33], v[200:201]
	v_pk_add_f32 v[34:35], v[34:35], v[202:203]
	global_store_dwordx4 v[212:213], v[36:39], off offset:512
	global_store_dwordx4 v[212:213], v[32:35], off offset:528
	s_waitcnt vmcnt(16)
	v_pk_add_f32 v[28:29], v[28:29], v[156:157]
	v_pk_add_f32 v[30:31], v[30:31], v[158:159]
	v_pk_add_f32 v[24:25], v[24:25], v[160:161]
	v_pk_add_f32 v[26:27], v[26:27], v[162:163]
	v_lshl_add_u64 v[212:213], v[212:213], 0, s[98:99]
	global_store_dwordx4 v[212:213], v[28:31], off
	global_store_dwordx4 v[212:213], v[24:27], off offset:16
	s_waitcnt vmcnt(14)
	v_pk_add_f32 v[20:21], v[20:21], v[164:165]
	v_pk_add_f32 v[22:23], v[22:23], v[166:167]
	v_pk_add_f32 v[16:17], v[16:17], v[168:169]
	v_pk_add_f32 v[18:19], v[18:19], v[170:171]
	global_store_dwordx4 v[212:213], v[20:23], off offset:512
	global_store_dwordx4 v[212:213], v[16:19], off offset:528
	s_waitcnt vmcnt(12)
	v_pk_add_f32 v[12:13], v[12:13], v[172:173]
	v_pk_add_f32 v[14:15], v[14:15], v[174:175]
	v_pk_add_f32 v[8:9], v[8:9], v[176:177]
	v_pk_add_f32 v[10:11], v[10:11], v[178:179]
	v_lshl_add_u64 v[212:213], v[212:213], 0, s[98:99]
	global_store_dwordx4 v[212:213], v[12:15], off
	global_store_dwordx4 v[212:213], v[8:11], off offset:16
	s_waitcnt vmcnt(10)
	v_pk_add_f32 v[4:5], v[4:5], v[180:181]
	v_pk_add_f32 v[6:7], v[6:7], v[182:183]
	v_pk_add_f32 v[0:1], v[0:1], v[184:185]
	v_pk_add_f32 v[2:3], v[2:3], v[186:187]
	global_store_dwordx4 v[212:213], v[4:7], off offset:512
	global_store_dwordx4 v[212:213], v[0:3], off offset:528
	s_mov_b64 s[24:25], -1
	s_and_b64 vcc, exec, s[2:3]
	s_cbranch_vccnz .LBB0_1608
	s_andn2_b64 vcc, exec, s[10:11]
	s_cbranch_vccnz .LBB0_1607
	s_barrier
	s_branch .LBB0_1607

; __device__ __forceinline__ unsigned xb_ld(unsigned* p)              { return __hip_atomic_load(p, __ATOMIC_RELAXED, __HIP_MEMORY_SCOPE_AGENT); }
; __device__ __forceinline__ unsigned xb_add(unsigned* p, unsigned v) { return __hip_atomic_fetch_add(p, v, __ATOMIC_RELAXED, __HIP_MEMORY_SCOPE_AGENT); }
; #define XB_SPIN(cond, bar) do { unsigned _sp = 0; while (cond) { __builtin_amdgcn_s_sleep(1); \
;     if ((++_sp & 255u) == 0u) { if (xb_ld(&(bar)[XB_TMO])) break; if (_sp > XB_SPIN_CAP) { atomicAdd(&(bar)[XB_TMO], 1u); break; } } } } while (0)
; __device__ __forceinline__ void xcd_barrier(const XcdBarrier& b, bool leader) {
;     ...
;     if (leader) {
;         unsigned* bar = b.bar;
;         __builtin_amdgcn_s_waitcnt(0);
;         unsigned nloc = b.st[0], nx = b.st[1];
;         if (nloc == 0u) { xcd_barrier_complete(bar, b.x, nloc, nx); b.st[0] = nloc; b.st[1] = nx; }
;         const unsigned old = xb_add(&bar[XB_XSUB(b.x)], 1u);
;         const unsigned gen = old / nloc;
;         if (old + 1u == (gen + 1u) * nloc) {
;             __builtin_amdgcn_fence(__ATOMIC_RELEASE, "agent");
;             asm volatile("s_waitcnt vmcnt(0)" ::: "memory");
;             const unsigned og = xb_add(&bar[XB_TOP], 1u);
;             const unsigned tg = og / nx;
;             if (og + 1u == (tg + 1u) * nx) xb_add(&bar[XB_TOPGEN], 1u);
;             else XB_SPIN(xb_ld(&bar[XB_TOPGEN]) == tg, bar);
;             __builtin_amdgcn_fence(__ATOMIC_ACQUIRE, "agent");
;             xb_add(&bar[XB_XGEN(b.x)], 1u);
;             asm volatile("s_waitcnt vmcnt(0)" ::: "memory");
;         } else {
;             XB_SPIN(xb_ld(&bar[XB_XGEN(b.x)]) == gen, bar);
;             __builtin_amdgcn_fence(__ATOMIC_ACQUIRE, "agent");
;             asm volatile("s_waitcnt vmcnt(0)" ::: "memory");
;         }
.LBB0_1642:
	s_lshl_b32 s2, s39, 8
	s_add_u32 s2, s38, s2
	s_addc_u32 s3, s37, 0
	v_mov_b32_e32 v1, s2
	v_add_co_u32_e32 v4, vcc, 0x2000, v1
	v_mov_b32_e32 v1, s3
	s_nop 0
	v_addc_co_u32_e32 v5, vcc, 0, v1, vcc
	v_mov_b32_e32 v1, 1
	global_atomic_add v1, v[4:5], v1, off offset:1024 sc0
	v_cvt_f32_u32_e32 v3, v2
	v_sub_u32_e32 v4, 0, v2
	s_add_u32 s25, s2, 0x1000
	s_addc_u32 s24, s3, 0
	v_rcp_iflag_f32_e32 v3, v3
	s_nop 0
	v_mul_f32_e32 v3, 0x4f7ffffe, v3
	v_cvt_u32_f32_e32 v3, v3
	v_mul_lo_u32 v4, v4, v3
	v_mul_hi_u32 v4, v3, v4
	v_add_u32_e32 v3, v3, v4
	s_waitcnt vmcnt(0) lgkmcnt(0)
	v_mul_hi_u32 v3, v1, v3
	v_mul_lo_u32 v5, v3, v2
	v_add_u32_e32 v4, 1, v1
	v_sub_u32_e32 v1, v1, v5
	v_add_u32_e32 v6, 1, v3
	v_cmp_ge_u32_e32 vcc, v1, v2
	v_sub_u32_e32 v5, v1, v2
	s_nop 0
	v_cndmask_b32_e32 v3, v3, v6, vcc
	v_cndmask_b32_e32 v1, v1, v5, vcc
	v_add_u32_e32 v5, 1, v3
	v_cmp_ge_u32_e32 vcc, v1, v2
	s_nop 1
	v_cndmask_b32_e32 v1, v3, v5, vcc
	v_mad_u64_u32 v[2:3], s[2:3], v2, v1, v[2:3]
	v_cmp_ne_u32_e32 vcc, v4, v2
	s_and_saveexec_b64 s[2:3], vcc
	s_xor_b64 s[2:3], exec, s[2:3]
	s_cbranch_execz .LBB0_1655
	v_mov_b32_e32 v0, s38
	v_add_co_u32_e32 v2, vcc, 0x4100, v0
	v_mov_b32_e32 v0, s37
	s_nop 0
	v_addc_co_u32_e32 v3, vcc, 0, v0, vcc
	global_load_dword v0, v[2:3], off offset:1024 sc1
	s_add_u32 s8, s38, 0x4500
	s_addc_u32 s9, s37, 0
	s_waitcnt vmcnt(0) lgkmcnt(0)
	v_cmp_eq_u32_e32 vcc, v0, v1
	s_and_saveexec_b64 s[4:5], vcc
	s_cbranch_execz .LBB0_1654
	s_add_u32 s6, s38, 0x1200
	s_addc_u32 s7, s37, 0
	s_mov_b32 s26, 1
	s_mov_b64 s[10:11], 0
	s_branch .LBB0_1646

; __device__ __forceinline__ unsigned xb_ld(unsigned* p)              { return __hip_atomic_load(p, __ATOMIC_RELAXED, __HIP_MEMORY_SCOPE_AGENT); }
; __device__ __forceinline__ unsigned xb_add(unsigned* p, unsigned v) { return __hip_atomic_fetch_add(p, v, __ATOMIC_RELAXED, __HIP_MEMORY_SCOPE_AGENT); }
; #define XB_SPIN(cond, bar) do { unsigned _sp = 0; while (cond) { __builtin_amdgcn_s_sleep(1); \
;     if ((++_sp & 255u) == 0u) { if (xb_ld(&(bar)[XB_TMO])) break; if (_sp > XB_SPIN_CAP) { atomicAdd(&(bar)[XB_TMO], 1u); break; } } } } while (0)
; __device__ __forceinline__ void xcd_barrier(const XcdBarrier& b, bool leader) {
;     ...
;     if (leader) {
;         unsigned* bar = b.bar;
;         __builtin_amdgcn_s_waitcnt(0);
;         unsigned nloc = b.st[0], nx = b.st[1];
;         if (nloc == 0u) { xcd_barrier_complete(bar, b.x, nloc, nx); b.st[0] = nloc; b.st[1] = nx; }
;         const unsigned old = xb_add(&bar[XB_XSUB(b.x)], 1u);
;         const unsigned gen = old / nloc;
;         if (old + 1u == (gen + 1u) * nloc) {
;             __builtin_amdgcn_fence(__ATOMIC_RELEASE, "agent");
;             asm volatile("s_waitcnt vmcnt(0)" ::: "memory");
;             const unsigned og = xb_add(&bar[XB_TOP], 1u);
;             const unsigned tg = og / nx;
;             if (og + 1u == (tg + 1u) * nx) xb_add(&bar[XB_TOPGEN], 1u);
;             else XB_SPIN(xb_ld(&bar[XB_TOPGEN]) == tg, bar);
;             __builtin_amdgcn_fence(__ATOMIC_ACQUIRE, "agent");
;             xb_add(&bar[XB_XGEN(b.x)], 1u);
;             asm volatile("s_waitcnt vmcnt(0)" ::: "memory");
;         } else {
;             XB_SPIN(xb_ld(&bar[XB_XGEN(b.x)]) == gen, bar);
;             __builtin_amdgcn_fence(__ATOMIC_ACQUIRE, "agent");
;             asm volatile("s_waitcnt vmcnt(0)" ::: "memory");
;         }
.LBB0_1736:
	s_lshl_b32 s2, s38, 8
	s_add_u32 s2, s37, s2
	s_addc_u32 s3, s33, 0
	v_mov_b32_e32 v1, s2
	v_add_co_u32_e32 v4, vcc, 0x2000, v1
	v_mov_b32_e32 v1, s3
	s_nop 0
	v_addc_co_u32_e32 v5, vcc, 0, v1, vcc
	v_mov_b32_e32 v1, 1
	global_atomic_add v1, v[4:5], v1, off offset:1024 sc0
	v_cvt_f32_u32_e32 v3, v2
	v_sub_u32_e32 v4, 0, v2
	s_add_u32 s25, s2, 0x1000
	s_addc_u32 s24, s3, 0
	v_rcp_iflag_f32_e32 v3, v3
	s_nop 0
	v_mul_f32_e32 v3, 0x4f7ffffe, v3
	v_cvt_u32_f32_e32 v3, v3
	v_mul_lo_u32 v4, v4, v3
	v_mul_hi_u32 v4, v3, v4
	v_add_u32_e32 v3, v3, v4
	s_waitcnt vmcnt(0) lgkmcnt(0)
	v_mul_hi_u32 v3, v1, v3
	v_mul_lo_u32 v5, v3, v2
	v_add_u32_e32 v4, 1, v1
	v_sub_u32_e32 v1, v1, v5
	v_add_u32_e32 v6, 1, v3
	v_cmp_ge_u32_e32 vcc, v1, v2
	v_sub_u32_e32 v5, v1, v2
	s_nop 0
	v_cndmask_b32_e32 v3, v3, v6, vcc
	v_cndmask_b32_e32 v1, v1, v5, vcc
	v_add_u32_e32 v5, 1, v3
	v_cmp_ge_u32_e32 vcc, v1, v2
	s_nop 1
	v_cndmask_b32_e32 v1, v3, v5, vcc
	v_mad_u64_u32 v[2:3], s[2:3], v2, v1, v[2:3]
	v_cmp_ne_u32_e32 vcc, v4, v2
	s_and_saveexec_b64 s[2:3], vcc
	s_xor_b64 s[2:3], exec, s[2:3]
	s_cbranch_execz .LBB0_1749
	v_mov_b32_e32 v0, s37
	v_add_co_u32_e32 v2, vcc, 0x4100, v0
	v_mov_b32_e32 v0, s33
	s_nop 0
	v_addc_co_u32_e32 v3, vcc, 0, v0, vcc
	global_load_dword v0, v[2:3], off offset:1024 sc1
	s_add_u32 s8, s37, 0x4500
	s_addc_u32 s9, s33, 0
	s_waitcnt vmcnt(0) lgkmcnt(0)
	v_cmp_eq_u32_e32 vcc, v0, v1
	s_and_saveexec_b64 s[4:5], vcc
	s_cbranch_execz .LBB0_1748
	s_add_u32 s6, s37, 0x1200
	s_addc_u32 s7, s33, 0
	s_mov_b32 s26, 1
	s_mov_b64 s[10:11], 0
	s_branch .LBB0_1740

; __device__ __forceinline__ unsigned xb_ld(unsigned* p)              { return __hip_atomic_load(p, __ATOMIC_RELAXED, __HIP_MEMORY_SCOPE_AGENT); }
; __device__ __forceinline__ unsigned xb_add(unsigned* p, unsigned v) { return __hip_atomic_fetch_add(p, v, __ATOMIC_RELAXED, __HIP_MEMORY_SCOPE_AGENT); }
; #define XB_SPIN(cond, bar) do { unsigned _sp = 0; while (cond) { __builtin_amdgcn_s_sleep(1); \
;     if ((++_sp & 255u) == 0u) { if (xb_ld(&(bar)[XB_TMO])) break; if (_sp > XB_SPIN_CAP) { atomicAdd(&(bar)[XB_TMO], 1u); break; } } } } while (0)
; __device__ __forceinline__ void xcd_barrier(const XcdBarrier& b, bool leader) {
;     ...
;     if (leader) {
;         unsigned* bar = b.bar;
;         __builtin_amdgcn_s_waitcnt(0);
;         unsigned nloc = b.st[0], nx = b.st[1];
;         if (nloc == 0u) { xcd_barrier_complete(bar, b.x, nloc, nx); b.st[0] = nloc; b.st[1] = nx; }
;         const unsigned old = xb_add(&bar[XB_XSUB(b.x)], 1u);
;         const unsigned gen = old / nloc;
;         if (old + 1u == (gen + 1u) * nloc) {
;             __builtin_amdgcn_fence(__ATOMIC_RELEASE, "agent");
;             asm volatile("s_waitcnt vmcnt(0)" ::: "memory");
;             const unsigned og = xb_add(&bar[XB_TOP], 1u);
;             const unsigned tg = og / nx;
;             if (og + 1u == (tg + 1u) * nx) xb_add(&bar[XB_TOPGEN], 1u);
;             else XB_SPIN(xb_ld(&bar[XB_TOPGEN]) == tg, bar);
;             __builtin_amdgcn_fence(__ATOMIC_ACQUIRE, "agent");
;             xb_add(&bar[XB_XGEN(b.x)], 1u);
;             asm volatile("s_waitcnt vmcnt(0)" ::: "memory");
;         } else {
;             XB_SPIN(xb_ld(&bar[XB_XGEN(b.x)]) == gen, bar);
;             __builtin_amdgcn_fence(__ATOMIC_ACQUIRE, "agent");
;             asm volatile("s_waitcnt vmcnt(0)" ::: "memory");
;         }
.LBB0_1806:
	s_lshl_b32 s2, s33, 8
	s_add_u32 s2, s1, s2
	s_addc_u32 s3, s0, 0
	v_mov_b32_e32 v1, s2
	v_add_co_u32_e32 v4, vcc, 0x2000, v1
	v_mov_b32_e32 v1, s3
	s_nop 0
	v_addc_co_u32_e32 v5, vcc, 0, v1, vcc
	v_mov_b32_e32 v1, 1
	global_atomic_add v1, v[4:5], v1, off offset:1024 sc0
	v_cvt_f32_u32_e32 v3, v2
	v_sub_u32_e32 v4, 0, v2
	s_add_u32 s25, s2, 0x1000
	s_addc_u32 s24, s3, 0
	v_rcp_iflag_f32_e32 v3, v3
	s_nop 0
	v_mul_f32_e32 v3, 0x4f7ffffe, v3
	v_cvt_u32_f32_e32 v3, v3
	v_mul_lo_u32 v4, v4, v3
	v_mul_hi_u32 v4, v3, v4
	v_add_u32_e32 v3, v3, v4
	s_waitcnt vmcnt(0) lgkmcnt(0)
	v_mul_hi_u32 v3, v1, v3
	v_mul_lo_u32 v5, v3, v2
	v_add_u32_e32 v4, 1, v1
	v_sub_u32_e32 v1, v1, v5
	v_add_u32_e32 v6, 1, v3
	v_cmp_ge_u32_e32 vcc, v1, v2
	v_sub_u32_e32 v5, v1, v2
	s_nop 0
	v_cndmask_b32_e32 v3, v3, v6, vcc
	v_cndmask_b32_e32 v1, v1, v5, vcc
	v_add_u32_e32 v5, 1, v3
	v_cmp_ge_u32_e32 vcc, v1, v2
	s_nop 1
	v_cndmask_b32_e32 v1, v3, v5, vcc
	v_mad_u64_u32 v[2:3], s[2:3], v2, v1, v[2:3]
	v_cmp_ne_u32_e32 vcc, v4, v2
	s_and_saveexec_b64 s[2:3], vcc
	s_xor_b64 s[2:3], exec, s[2:3]
	s_cbranch_execz .LBB0_1819
	v_mov_b32_e32 v0, s1
	v_add_co_u32_e32 v2, vcc, 0x4100, v0
	v_mov_b32_e32 v0, s0
	s_nop 0
	v_addc_co_u32_e32 v3, vcc, 0, v0, vcc
	global_load_dword v0, v[2:3], off offset:1024 sc1
	s_add_u32 s8, s1, 0x4500
	s_addc_u32 s9, s0, 0
	s_waitcnt vmcnt(0) lgkmcnt(0)
	v_cmp_eq_u32_e32 vcc, v0, v1
	s_and_saveexec_b64 s[4:5], vcc
	s_cbranch_execz .LBB0_1818
	s_add_u32 s6, s1, 0x1200
	s_addc_u32 s7, s0, 0
	s_mov_b32 s26, 1
	s_mov_b64 s[10:11], 0
	s_branch .LBB0_1810

; __global__ void __launch_bounds__(512, 2) mega_fwd(Params p) {
	.amdhsa_kernel _Z8mega_fwd6Params
		.amdhsa_group_segment_fixed_size 0
		.amdhsa_private_segment_fixed_size 0
		.amdhsa_kernarg_size 512
		.amdhsa_user_sgpr_count 2
		.amdhsa_user_sgpr_dispatch_ptr 0
		.amdhsa_user_sgpr_queue_ptr 0
		.amdhsa_user_sgpr_kernarg_segment_ptr 1
		.amdhsa_user_sgpr_dispatch_id 0
		.amdhsa_user_sgpr_kernarg_preload_length 0
		.amdhsa_user_sgpr_kernarg_preload_offset 0
		.amdhsa_user_sgpr_private_segment_size 0
		.amdhsa_uses_dynamic_stack 0
		.amdhsa_enable_private_segment 0
		.amdhsa_system_sgpr_workgroup_id_x 1
		.amdhsa_system_sgpr_workgroup_id_y 0
		.amdhsa_system_sgpr_workgroup_id_z 0
		.amdhsa_system_sgpr_workgroup_info 0
		.amdhsa_system_vgpr_workitem_id 2
		.amdhsa_next_free_vgpr 255
		.amdhsa_next_free_sgpr 102
		.amdhsa_accum_offset 256
		.amdhsa_reserve_vcc 1
		.amdhsa_float_round_mode_32 0
		.amdhsa_float_round_mode_16_64 0
		.amdhsa_float_denorm_mode_32 3
		.amdhsa_float_denorm_mode_16_64 3
		.amdhsa_dx10_clamp 1
		.amdhsa_ieee_mode 1
		.amdhsa_fp16_overflow 0
		.amdhsa_tg_split 0
		.amdhsa_exception_fp_ieee_invalid_op 0
		.amdhsa_exception_fp_denorm_src 0
		.amdhsa_exception_fp_ieee_div_zero 0
		.amdhsa_exception_fp_ieee_overflow 0
		.amdhsa_exception_fp_ieee_underflow 0
		.amdhsa_exception_fp_ieee_inexact 0
		.amdhsa_exception_int_div_zero 0
	.end_amdhsa_kernel

; __global__ void __launch_bounds__(512, 2) mega_fwd(Params p) {
amdhsa.kernels:
  - .agpr_count:     0
    .args:
      - .offset:         0
        .size:           256
        .value_kind:     by_value
      - .offset:         256
        .size:           4
        .value_kind:     hidden_block_count_x
      - .offset:         260
        .size:           4
        .value_kind:     hidden_block_count_y
      - .offset:         264
        .size:           4
        .value_kind:     hidden_block_count_z
      - .offset:         268
        .size:           2
        .value_kind:     hidden_group_size_x
      - .offset:         270
        .size:           2
        .value_kind:     hidden_group_size_y
      - .offset:         272
        .size:           2
        .value_kind:     hidden_group_size_z
      - .offset:         274
        .size:           2
        .value_kind:     hidden_remainder_x
      - .offset:         276
        .size:           2
        .value_kind:     hidden_remainder_y
      - .offset:         278
        .size:           2
        .value_kind:     hidden_remainder_z
      - .offset:         296
        .size:           8
        .value_kind:     hidden_global_offset_x
      - .offset:         304
        .size:           8
        .value_kind:     hidden_global_offset_y
      - .offset:         312
        .size:           8
        .value_kind:     hidden_global_offset_z
      - .offset:         320
        .size:           2
        .value_kind:     hidden_grid_dims
      - .offset:         344
        .size:           8
        .value_kind:     hidden_multigrid_sync_arg
      - .offset:         376
        .size:           4
        .value_kind:     hidden_dynamic_lds_size
    .group_segment_fixed_size: 0
    .kernarg_segment_align: 8
    .kernarg_segment_size: 512
    .language:       OpenCL C
    .language_version:
      - 2
      - 0
    .max_flat_workgroup_size: 512
    .name:           _Z8mega_fwd6Params
    .private_segment_fixed_size: 0
    .sgpr_count:     108
    .sgpr_spill_count: 19
    .symbol:         _Z8mega_fwd6Params.kd
    .uniform_work_group_size: 1
    .uses_dynamic_stack: false
    .vgpr_count:     255
    .vgpr_spill_count: 0
    .wavefront_size: 64
